# half of the next-layer latent pre-norm rows in the down-proj tail (idle workgroups), other half stays in the pre-norm phase
# speedup vs baseline: 1.0020x; 1.0020x over previous
; __device__ __forceinline__ int obid() { int b = blockIdx.x; asm volatile("" : "+s"(b)); return b; }
; #define PN_LOAD(dst, rw) do { const float* s_ = (rw) < NLAT ? hlat + (size_t)(rw) * 1024 : hctx + (size_t)((rw) - NLAT) * 1024; \
;         _Pragma("unroll") for (int i = 0; i < 4; ++i) dst[i] = *(const float4*)(s_ + i * 256 + lane * 4); } while (0)
; __device__ __forceinline__ void p_norm(const float* hlat, const float* hctx, const float* g, const float* modl, int sh_off, int sc_off, bf16_t* A, int M,
;                                        const float* part, const float* cgate, float* hcout) {
;     ...
;     int row = obid() * 8 + wave;
;     float4 v[4], nv[4];
;     ...
;     if (row < M) PN_LOAD(v, row);
;     while (row < M) {
;         const int nrow = row + stride;
;         if (nrow < M) PN_LOAD(nv, nrow);
;         const int r = row < NLAT ? (row >> 11) : 16;
;         float ss = 0.f;
; #pragma unroll
;         for (int i = 0; i < 4; ++i) {
;             if (part != nullptr && row >= NLAT) {
;                 const size_t po = (size_t)(row - NLAT) * 1024 + i * 256 + lane * 4;
;                 const float4 p0 = *(const float4*)(part + po), p1 = *(const float4*)(part + (size_t)4096 * 1024 + po), cg = *(const float4*)(cgate + i * 256 + lane * 4);
;                 v[i].x += cg.x * (p0.x + p1.x); v[i].y += cg.y * (p0.y + p1.y); v[i].z += cg.z * (p0.z + p1.z); v[i].w += cg.w * (p0.w + p1.w);
;                 *(float4*)(hcout + po) = v[i];
;             }
;             ss += v[i].x * v[i].x + v[i].y * v[i].y + v[i].z * v[i].z + v[i].w * v[i].w; }
;         ss = wave_sum(ss);
.LBB0_406:
	s_load_dwordx2 s[6:7], s[16:17], 0x0
	s_mul_hi_u32 s5, s8, 0x66000
	s_mov_b32 s9, s55
	v_mov_b32_e32 v14, v253
	s_waitcnt lgkmcnt(0)
	v_writelane_b32 v255, s6, 41
	v_ashrrev_i32_e32 v1, 6, v14
	s_nop 0
	v_writelane_b32 v255, s7, 42
	s_mul_i32 s6, s8, 0x66000
	s_add_u32 s6, s56, s6
	s_addc_u32 s7, s57, s5
	v_writelane_b32 v255, s6, 43
	s_mov_b32 s5, s63
	s_lshl_b32 s5, s5, 3
	v_writelane_b32 v255, s7, 44
	v_writelane_b32 v255, s8, 45
	s_lshl_b32 s6, s8, 10
	s_mov_b32 s7, s55
	v_writelane_b32 v255, s9, 46
	v_writelane_b32 v255, s6, 47
	v_add_u32_e32 v50, s5, v1
	s_waitcnt vmcnt(0) lgkmcnt(0)
	v_readlane_b32 s100, v255, 45
	s_load_dwordx2 s[48:49], s[0:1], 0x30
	s_cmp_eq_u32 s100, 0
	s_cselect_b32 s101, 0, 0xe8
	s_load_dwordx2 s[46:47], s[0:1], s101
	s_load_dwordx2 s[16:17], s[0:1], 0x10
	s_mul_i32 s101, s100, 0x66000
	s_add_u32 s50, s56, s101
	s_addc_u32 s51, s57, 0
	s_sub_u32 s20, s101, 0x66000
	s_cmp_eq_u32 s100, 0
	s_cselect_b32 s20, 0, s20
	s_add_u32 s20, s20, 0x65000
	s_add_u32 s20, s56, s20
	s_addc_u32 s21, s57, 0
	s_add_u32 s98, s50, 0x1000
	s_addc_u32 s99, s51, 0
	s_lshl_b32 s101, s100, 12
	v_and_b32_e32 v240, 63, v253
	v_lshlrev_b32_e32 v241, 4, v240
	v_lshrrev_b32_e32 v148, 7, v50
	v_lshlrev_b32_e32 v146, 4, v50
	v_lshl_add_u32 v144, v146, 12, v241
	v_lshlrev_b32_e32 v146, 11, v146
	v_lshl_add_u32 v146, v240, 3, v146
	v_mul_u32_u24_e32 v148, 0x6000, v148
	v_add_u32_e32 v148, v148, v241
	s_waitcnt lgkmcnt(0)
	s_add_u32 s48, s48, s101
	s_addc_u32 s49, s49, 0
	s_cmp_eq_u32 s100, 0
	s_cselect_b32 s16, s16, s64
	s_cselect_b32 s17, s17, s65
	s_cmp_eq_u32 s100, 0
	s_cbranch_scc1 .Lnorm_P1_alt
	v_lshrrev_b32_e32 v204, 4, v50
	v_bfe_u32 v205, v50, 1, 3
	v_lshl_or_b32 v204, v204, 4, v205
	v_or_b32_e32 v204, 8, v204
	v_lshrrev_b32_e32 v148, 7, v204
	v_and_b32_e32 v205, 1, v50
	v_lshlrev_b32_e32 v205, 3, v205
	v_lshl_or_b32 v146, v204, 4, v205
	v_lshl_add_u32 v144, v146, 12, v241
	v_lshlrev_b32_e32 v146, 11, v146
	v_lshl_add_u32 v146, v240, 3, v146
	v_mul_u32_u24_e32 v148, 0x6000, v148
	v_add_u32_e32 v148, v148, v241
	global_load_dwordx4 v[80:83], v144, s[46:47] nt
	global_load_dwordx4 v[84:87], v144, s[46:47] offset:1024 nt
	global_load_dwordx4 v[88:91], v144, s[46:47] offset:2048 nt
	global_load_dwordx4 v[92:95], v144, s[46:47] offset:3072 nt
	v_add_u32_e32 v144, 0x1000, v144
	global_load_dwordx4 v[34:37], v148, s[98:99]
	global_load_dwordx4 v[38:41], v148, s[98:99] offset:1024
	global_load_dwordx4 v[42:45], v148, s[98:99] offset:2048
	global_load_dwordx4 v[46:49], v148, s[98:99] offset:3072
	global_load_dwordx4 v[224:227], v148, s[50:51]
	global_load_dwordx4 v[228:231], v148, s[50:51] offset:1024
	global_load_dwordx4 v[232:235], v148, s[50:51] offset:2048
	global_load_dwordx4 v[236:239], v148, s[50:51] offset:3072
	global_load_dwordx4 v[188:191], v241, s[48:49]
	global_load_dwordx4 v[192:195], v241, s[48:49] offset:1024
	global_load_dwordx4 v[196:199], v241, s[48:49] offset:2048
	global_load_dwordx4 v[200:203], v241, s[48:49] offset:3072
	global_load_dwordx4 v[96:99], v144, s[46:47] nt
	global_load_dwordx4 v[100:103], v144, s[46:47] offset:1024 nt
	global_load_dwordx4 v[104:107], v144, s[46:47] offset:2048 nt
	global_load_dwordx4 v[108:111], v144, s[46:47] offset:3072 nt
	v_add_u32_e32 v144, 0x1000, v144
	global_load_dwordx4 v[112:115], v144, s[46:47] nt
	global_load_dwordx4 v[116:119], v144, s[46:47] offset:1024 nt
	global_load_dwordx4 v[120:123], v144, s[46:47] offset:2048 nt
	global_load_dwordx4 v[124:127], v144, s[46:47] offset:3072 nt
	v_add_u32_e32 v144, 0x1000, v144
	global_load_dwordx4 v[128:131], v144, s[46:47] nt
	global_load_dwordx4 v[132:135], v144, s[46:47] offset:1024 nt
	global_load_dwordx4 v[136:139], v144, s[46:47] offset:2048 nt
	global_load_dwordx4 v[140:143], v144, s[46:47] offset:3072 nt
	v_add_u32_e32 v144, 0x1000, v144
	global_load_dwordx4 v[156:159], v144, s[46:47] nt
	global_load_dwordx4 v[160:163], v144, s[46:47] offset:1024 nt
	global_load_dwordx4 v[164:167], v144, s[46:47] offset:2048 nt
	global_load_dwordx4 v[168:171], v144, s[46:47] offset:3072 nt
	v_add_u32_e32 v144, 0x1000, v144
	global_load_dwordx4 v[172:175], v144, s[46:47] nt
	global_load_dwordx4 v[176:179], v144, s[46:47] offset:1024 nt
	global_load_dwordx4 v[180:183], v144, s[46:47] offset:2048 nt
	global_load_dwordx4 v[184:187], v144, s[46:47] offset:3072 nt
	v_add_u32_e32 v144, 0x1000, v144
	s_waitcnt vmcnt(32)
	v_pk_mul_f32 v[242:243], v[80:81], v[80:81]
	v_pk_mul_f32 v[244:245], v[84:85], v[84:85]
	v_pk_mul_f32 v[246:247], v[82:83], v[82:83]
	v_pk_mul_f32 v[248:249], v[86:87], v[86:87]
	v_add_f32_e32 v204, v245, v244
	v_add_f32_e32 v205, v243, v242
	v_add_f32_e32 v204, v248, v204
	v_add_f32_e32 v205, v246, v205
	v_add_f32_e32 v204, v249, v204
	v_add_f32_e32 v205, v247, v205
	v_pk_mul_f32 v[242:243], v[88:89], v[88:89]
	v_pk_mul_f32 v[244:245], v[92:93], v[92:93]
	v_pk_mul_f32 v[246:247], v[90:91], v[90:91]
	v_pk_mul_f32 v[248:249], v[94:95], v[94:95]
	v_add_f32_e32 v206, v243, v242
	v_add_f32_e32 v207, v245, v244
	v_add_f32_e32 v206, v246, v206
	v_add_f32_e32 v207, v248, v207
	v_add_f32_e32 v206, v247, v206
	v_add_f32_e32 v207, v249, v207
	v_add_f32_e32 v204, v205, v204
	v_add_f32_e32 v204, v204, v206
	v_add_f32_e32 v204, v204, v207
	ds_swizzle_b32 v205, v204 offset:swizzle(SWAP,1)
	s_waitcnt lgkmcnt(0)
	v_add_f32_e32 v204, v204, v205
	ds_swizzle_b32 v205, v204 offset:swizzle(SWAP,2)
	s_waitcnt lgkmcnt(0)
	v_add_f32_e32 v204, v204, v205
	ds_swizzle_b32 v205, v204 offset:swizzle(SWAP,4)
	s_waitcnt lgkmcnt(0)
	v_add_f32_e32 v204, v204, v205
	ds_swizzle_b32 v205, v204 offset:swizzle(SWAP,8)
	s_waitcnt lgkmcnt(0)
; __device__ __forceinline__ unsigned pk2(float lo, float hi) { const g_f32x2 f = {lo, hi}; return __builtin_bit_cast(unsigned, __builtin_convertvector(f, g_bf16x2)); }
; __device__ __forceinline__ void p_norm(const float* hlat, const float* hctx, const float* g, const float* modl, int sh_off, int sc_off, bf16_t* A, int M,
;                                        const float* part, const float* cgate, float* hcout) {
;     ...
;         float ss = 0.f;
; #pragma unroll
;         for (int i = 0; i < 4; ++i) {
;             if (part != nullptr && row >= NLAT) {
;                 const size_t po = (size_t)(row - NLAT) * 1024 + i * 256 + lane * 4;
;                 const float4 p0 = *(const float4*)(part + po), p1 = *(const float4*)(part + (size_t)4096 * 1024 + po), cg = *(const float4*)(cgate + i * 256 + lane * 4);
;                 v[i].x += cg.x * (p0.x + p1.x); v[i].y += cg.y * (p0.y + p1.y); v[i].z += cg.z * (p0.z + p1.z); v[i].w += cg.w * (p0.w + p1.w);
;                 *(float4*)(hcout + po) = v[i];
;             }
;             ss += v[i].x * v[i].x + v[i].y * v[i].y + v[i].z * v[i].z + v[i].w * v[i].w; }
;         ss = wave_sum(ss);
;         const float rstd = rsqrtf(ss * (1.0f / 1024.0f) + EPS);
;         const float* mr = modl + (size_t)r * 6144;
; #pragma unroll
;         for (int i = 0; i < 4; ++i) {
;             const int k = i * 256 + lane * 4;
;             const float4 gg = *(const float4*)(g + k), scv = *(const float4*)(mr + sc_off + k), shv = *(const float4*)(mr + sh_off + k);
;             const float o0 = v[i].x * rstd * gg.x * (1.0f + scv.x) + shv.x, o1 = v[i].y * rstd * gg.y * (1.0f + scv.y) + shv.y;
;             const float o2 = v[i].z * rstd * gg.z * (1.0f + scv.z) + shv.z, o3 = v[i].w * rstd * gg.w * (1.0f + scv.w) + shv.w;
;             uint2 w; w.x = pk2(o0, o1); w.y = pk2(o2, o3);
;             *(uint2*)(A + (size_t)row * 1024 + k) = w;
;         }
; #pragma unroll
;         for (int i = 0; i < 4; ++i) v[i] = nv[i];
;         row = nrow;
;     }
	v_add_f32_e32 v204, v204, v205
	ds_swizzle_b32 v205, v204 offset:swizzle(SWAP,16)
	s_waitcnt lgkmcnt(0)
	v_add_f32_e32 v204, v204, v205
	v_mov_b32_e32 v205, v204
	s_nop 1
	v_permlane32_swap_b32_e32 v204, v205
	v_add_f32_e32 v204, v204, v205
	v_mov_b32_e32 v205, 0x358637bd
	v_fmamk_f32 v204, v204, 0x3a800000, v205
	v_rsq_f32_e32 v204, v204
	s_nop 0
	s_waitcnt vmcnt(20)
	v_pk_add_f32 v[34:35], v[34:35], 1.0 op_sel_hi:[1,0]
	v_pk_add_f32 v[36:37], v[36:37], 1.0 op_sel_hi:[1,0]
	v_pk_add_f32 v[38:39], v[38:39], 1.0 op_sel_hi:[1,0]
	v_pk_add_f32 v[40:41], v[40:41], 1.0 op_sel_hi:[1,0]
	v_pk_add_f32 v[42:43], v[42:43], 1.0 op_sel_hi:[1,0]
	v_pk_add_f32 v[44:45], v[44:45], 1.0 op_sel_hi:[1,0]
	v_pk_add_f32 v[46:47], v[46:47], 1.0 op_sel_hi:[1,0]
	v_pk_add_f32 v[48:49], v[48:49], 1.0 op_sel_hi:[1,0]
	v_pk_mul_f32 v[80:81], v[80:81], v[204:205] op_sel_hi:[1,0]
	v_pk_mul_f32 v[82:83], v[82:83], v[204:205] op_sel_hi:[1,0]
	v_pk_mul_f32 v[80:81], v[188:189], v[80:81]
	v_pk_mul_f32 v[82:83], v[190:191], v[82:83]
	v_pk_fma_f32 v[80:81], v[34:35], v[80:81], v[224:225]
	v_pk_fma_f32 v[82:83], v[36:37], v[82:83], v[226:227]
	v_cvt_pk_bf16_f32 v80, v80, v81
	v_cvt_pk_bf16_f32 v81, v82, v83
	global_store_dwordx2 v146, v[80:81], s[66:67]
	v_pk_mul_f32 v[84:85], v[84:85], v[204:205] op_sel_hi:[1,0]
	v_pk_mul_f32 v[86:87], v[86:87], v[204:205] op_sel_hi:[1,0]
	v_pk_mul_f32 v[84:85], v[192:193], v[84:85]
	v_pk_mul_f32 v[86:87], v[194:195], v[86:87]
	v_pk_fma_f32 v[84:85], v[38:39], v[84:85], v[228:229]
	v_pk_fma_f32 v[86:87], v[40:41], v[86:87], v[230:231]
	v_cvt_pk_bf16_f32 v84, v84, v85
	v_cvt_pk_bf16_f32 v85, v86, v87
	global_store_dwordx2 v146, v[84:85], s[66:67] offset:512
	v_pk_mul_f32 v[88:89], v[88:89], v[204:205] op_sel_hi:[1,0]
	v_pk_mul_f32 v[90:91], v[90:91], v[204:205] op_sel_hi:[1,0]
	v_pk_mul_f32 v[88:89], v[196:197], v[88:89]
	v_pk_mul_f32 v[90:91], v[198:199], v[90:91]
	v_pk_fma_f32 v[88:89], v[42:43], v[88:89], v[232:233]
	v_pk_fma_f32 v[90:91], v[44:45], v[90:91], v[234:235]
	v_cvt_pk_bf16_f32 v88, v88, v89
	v_cvt_pk_bf16_f32 v89, v90, v91
	global_store_dwordx2 v146, v[88:89], s[66:67] offset:1024
	v_pk_mul_f32 v[92:93], v[92:93], v[204:205] op_sel_hi:[1,0]
	v_pk_mul_f32 v[94:95], v[94:95], v[204:205] op_sel_hi:[1,0]
	v_pk_mul_f32 v[92:93], v[200:201], v[92:93]
	v_pk_mul_f32 v[94:95], v[202:203], v[94:95]
	v_pk_fma_f32 v[92:93], v[46:47], v[92:93], v[236:237]
	v_pk_fma_f32 v[94:95], v[48:49], v[94:95], v[238:239]
	v_cvt_pk_bf16_f32 v92, v92, v93
	v_cvt_pk_bf16_f32 v93, v94, v95
	global_store_dwordx2 v146, v[92:93], s[66:67] offset:1536
	v_add_u32_e32 v146, 0x800, v146
	global_load_dwordx4 v[80:83], v144, s[46:47] nt
	global_load_dwordx4 v[84:87], v144, s[46:47] offset:1024 nt
	global_load_dwordx4 v[88:91], v144, s[46:47] offset:2048 nt
	global_load_dwordx4 v[92:95], v144, s[46:47] offset:3072 nt
	v_add_u32_e32 v144, 0x1000, v144
	s_waitcnt vmcnt(24)
	v_pk_mul_f32 v[242:243], v[96:97], v[96:97]
	v_pk_mul_f32 v[244:245], v[100:101], v[100:101]
	v_pk_mul_f32 v[246:247], v[98:99], v[98:99]
	v_pk_mul_f32 v[248:249], v[102:103], v[102:103]
	v_add_f32_e32 v204, v245, v244
	v_add_f32_e32 v205, v243, v242
	v_add_f32_e32 v204, v248, v204
	v_add_f32_e32 v205, v246, v205
	v_add_f32_e32 v204, v249, v204
	v_add_f32_e32 v205, v247, v205
	v_pk_mul_f32 v[242:243], v[104:105], v[104:105]
	v_pk_mul_f32 v[244:245], v[108:109], v[108:109]
	v_pk_mul_f32 v[246:247], v[106:107], v[106:107]
	v_pk_mul_f32 v[248:249], v[110:111], v[110:111]
	v_add_f32_e32 v206, v243, v242
	v_add_f32_e32 v207, v245, v244
	v_add_f32_e32 v206, v246, v206
	v_add_f32_e32 v207, v248, v207
	v_add_f32_e32 v206, v247, v206
	v_add_f32_e32 v207, v249, v207
	v_add_f32_e32 v204, v205, v204
	v_add_f32_e32 v204, v204, v206
	v_add_f32_e32 v204, v204, v207
	ds_swizzle_b32 v205, v204 offset:swizzle(SWAP,1)
	s_waitcnt lgkmcnt(0)
	v_add_f32_e32 v204, v204, v205
	ds_swizzle_b32 v205, v204 offset:swizzle(SWAP,2)
	s_waitcnt lgkmcnt(0)
	v_add_f32_e32 v204, v204, v205
	ds_swizzle_b32 v205, v204 offset:swizzle(SWAP,4)
	s_waitcnt lgkmcnt(0)
	v_add_f32_e32 v204, v204, v205
	ds_swizzle_b32 v205, v204 offset:swizzle(SWAP,8)
	s_waitcnt lgkmcnt(0)
	v_add_f32_e32 v204, v204, v205
	ds_swizzle_b32 v205, v204 offset:swizzle(SWAP,16)
	s_waitcnt lgkmcnt(0)
	v_add_f32_e32 v204, v204, v205
	v_mov_b32_e32 v205, v204
	s_nop 1
	v_permlane32_swap_b32_e32 v204, v205
	v_add_f32_e32 v204, v204, v205
	v_mov_b32_e32 v205, 0x358637bd
	v_fmamk_f32 v204, v204, 0x3a800000, v205
	v_rsq_f32_e32 v204, v204
	s_nop 0
	v_pk_mul_f32 v[96:97], v[96:97], v[204:205] op_sel_hi:[1,0]
	v_pk_mul_f32 v[98:99], v[98:99], v[204:205] op_sel_hi:[1,0]
	v_pk_mul_f32 v[96:97], v[188:189], v[96:97]
	v_pk_mul_f32 v[98:99], v[190:191], v[98:99]
	v_pk_fma_f32 v[96:97], v[34:35], v[96:97], v[224:225]
	v_pk_fma_f32 v[98:99], v[36:37], v[98:99], v[226:227]
	v_cvt_pk_bf16_f32 v96, v96, v97
	v_cvt_pk_bf16_f32 v97, v98, v99
	global_store_dwordx2 v146, v[96:97], s[66:67]
	v_pk_mul_f32 v[100:101], v[100:101], v[204:205] op_sel_hi:[1,0]
	v_pk_mul_f32 v[102:103], v[102:103], v[204:205] op_sel_hi:[1,0]
	v_pk_mul_f32 v[100:101], v[192:193], v[100:101]
	v_pk_mul_f32 v[102:103], v[194:195], v[102:103]
	v_pk_fma_f32 v[100:101], v[38:39], v[100:101], v[228:229]
	v_pk_fma_f32 v[102:103], v[40:41], v[102:103], v[230:231]
	v_cvt_pk_bf16_f32 v100, v100, v101
	v_cvt_pk_bf16_f32 v101, v102, v103
	global_store_dwordx2 v146, v[100:101], s[66:67] offset:512
	v_pk_mul_f32 v[104:105], v[104:105], v[204:205] op_sel_hi:[1,0]
	v_pk_mul_f32 v[106:107], v[106:107], v[204:205] op_sel_hi:[1,0]
	v_pk_mul_f32 v[104:105], v[196:197], v[104:105]
	v_pk_mul_f32 v[106:107], v[198:199], v[106:107]
	v_pk_fma_f32 v[104:105], v[42:43], v[104:105], v[232:233]
	v_pk_fma_f32 v[106:107], v[44:45], v[106:107], v[234:235]
	v_cvt_pk_bf16_f32 v104, v104, v105
	v_cvt_pk_bf16_f32 v105, v106, v107
	global_store_dwordx2 v146, v[104:105], s[66:67] offset:1024
	v_pk_mul_f32 v[108:109], v[108:109], v[204:205] op_sel_hi:[1,0]
	v_pk_mul_f32 v[110:111], v[110:111], v[204:205] op_sel_hi:[1,0]
	v_pk_mul_f32 v[108:109], v[200:201], v[108:109]
	v_pk_mul_f32 v[110:111], v[202:203], v[110:111]
	v_pk_fma_f32 v[108:109], v[46:47], v[108:109], v[236:237]
	v_pk_fma_f32 v[110:111], v[48:49], v[110:111], v[238:239]
	v_cvt_pk_bf16_f32 v108, v108, v109
	v_cvt_pk_bf16_f32 v109, v110, v111
	global_store_dwordx2 v146, v[108:109], s[66:67] offset:1536
	v_add_u32_e32 v146, 0x800, v146
	global_load_dwordx4 v[96:99], v144, s[46:47] nt
	global_load_dwordx4 v[100:103], v144, s[46:47] offset:1024 nt
	global_load_dwordx4 v[104:107], v144, s[46:47] offset:2048 nt
	global_load_dwordx4 v[108:111], v144, s[46:47] offset:3072 nt
	v_add_u32_e32 v144, 0x1000, v144
	s_waitcnt vmcnt(28)
; __device__ __forceinline__ unsigned pk2(float lo, float hi) { const g_f32x2 f = {lo, hi}; return __builtin_bit_cast(unsigned, __builtin_convertvector(f, g_bf16x2)); }
; __device__ __forceinline__ void p_norm(const float* hlat, const float* hctx, const float* g, const float* modl, int sh_off, int sc_off, bf16_t* A, int M,
;                                        const float* part, const float* cgate, float* hcout) {
;     ...
;     if (row < M) PN_LOAD(v, row);
;     while (row < M) {
;         const int nrow = row + stride;
;         if (nrow < M) PN_LOAD(nv, nrow);
;         const int r = row < NLAT ? (row >> 11) : 16;
;         float ss = 0.f;
; #pragma unroll
;         for (int i = 0; i < 4; ++i) {
;             if (part != nullptr && row >= NLAT) {
;                 const size_t po = (size_t)(row - NLAT) * 1024 + i * 256 + lane * 4;
;                 const float4 p0 = *(const float4*)(part + po), p1 = *(const float4*)(part + (size_t)4096 * 1024 + po), cg = *(const float4*)(cgate + i * 256 + lane * 4);
;                 v[i].x += cg.x * (p0.x + p1.x); v[i].y += cg.y * (p0.y + p1.y); v[i].z += cg.z * (p0.z + p1.z); v[i].w += cg.w * (p0.w + p1.w);
;                 *(float4*)(hcout + po) = v[i];
;             }
;             ss += v[i].x * v[i].x + v[i].y * v[i].y + v[i].z * v[i].z + v[i].w * v[i].w; }
;         ss = wave_sum(ss);
;         const float rstd = rsqrtf(ss * (1.0f / 1024.0f) + EPS);
;         const float* mr = modl + (size_t)r * 6144;
; #pragma unroll
;         for (int i = 0; i < 4; ++i) {
;             const int k = i * 256 + lane * 4;
;             const float4 gg = *(const float4*)(g + k), scv = *(const float4*)(mr + sc_off + k), shv = *(const float4*)(mr + sh_off + k);
;             const float o0 = v[i].x * rstd * gg.x * (1.0f + scv.x) + shv.x, o1 = v[i].y * rstd * gg.y * (1.0f + scv.y) + shv.y;
;             const float o2 = v[i].z * rstd * gg.z * (1.0f + scv.z) + shv.z, o3 = v[i].w * rstd * gg.w * (1.0f + scv.w) + shv.w;
;             uint2 w; w.x = pk2(o0, o1); w.y = pk2(o2, o3);
;             *(uint2*)(A + (size_t)row * 1024 + k) = w;
;         }
; #pragma unroll
;         for (int i = 0; i < 4; ++i) v[i] = nv[i];
;         row = nrow;
;     }
	v_pk_mul_f32 v[242:243], v[112:113], v[112:113]
	v_pk_mul_f32 v[244:245], v[116:117], v[116:117]
	v_pk_mul_f32 v[246:247], v[114:115], v[114:115]
	v_pk_mul_f32 v[248:249], v[118:119], v[118:119]
	v_add_f32_e32 v204, v245, v244
	v_add_f32_e32 v205, v243, v242
	v_add_f32_e32 v204, v248, v204
	v_add_f32_e32 v205, v246, v205
	v_add_f32_e32 v204, v249, v204
	v_add_f32_e32 v205, v247, v205
	v_pk_mul_f32 v[242:243], v[120:121], v[120:121]
	v_pk_mul_f32 v[244:245], v[124:125], v[124:125]
	v_pk_mul_f32 v[246:247], v[122:123], v[122:123]
	v_pk_mul_f32 v[248:249], v[126:127], v[126:127]
	v_add_f32_e32 v206, v243, v242
	v_add_f32_e32 v207, v245, v244
	v_add_f32_e32 v206, v246, v206
	v_add_f32_e32 v207, v248, v207
	v_add_f32_e32 v206, v247, v206
	v_add_f32_e32 v207, v249, v207
	v_add_f32_e32 v204, v205, v204
	v_add_f32_e32 v204, v204, v206
	v_add_f32_e32 v204, v204, v207
	ds_swizzle_b32 v205, v204 offset:swizzle(SWAP,1)
	s_waitcnt lgkmcnt(0)
	v_add_f32_e32 v204, v204, v205
	ds_swizzle_b32 v205, v204 offset:swizzle(SWAP,2)
	s_waitcnt lgkmcnt(0)
	v_add_f32_e32 v204, v204, v205
	ds_swizzle_b32 v205, v204 offset:swizzle(SWAP,4)
	s_waitcnt lgkmcnt(0)
	v_add_f32_e32 v204, v204, v205
	ds_swizzle_b32 v205, v204 offset:swizzle(SWAP,8)
	s_waitcnt lgkmcnt(0)
	v_add_f32_e32 v204, v204, v205
	ds_swizzle_b32 v205, v204 offset:swizzle(SWAP,16)
	s_waitcnt lgkmcnt(0)
	v_add_f32_e32 v204, v204, v205
	v_mov_b32_e32 v205, v204
	s_nop 1
	v_permlane32_swap_b32_e32 v204, v205
	v_add_f32_e32 v204, v204, v205
	v_mov_b32_e32 v205, 0x358637bd
	v_fmamk_f32 v204, v204, 0x3a800000, v205
	v_rsq_f32_e32 v204, v204
	s_nop 0
	v_pk_mul_f32 v[112:113], v[112:113], v[204:205] op_sel_hi:[1,0]
	v_pk_mul_f32 v[114:115], v[114:115], v[204:205] op_sel_hi:[1,0]
	v_pk_mul_f32 v[112:113], v[188:189], v[112:113]
	v_pk_mul_f32 v[114:115], v[190:191], v[114:115]
	v_pk_fma_f32 v[112:113], v[34:35], v[112:113], v[224:225]
	v_pk_fma_f32 v[114:115], v[36:37], v[114:115], v[226:227]
	v_cvt_pk_bf16_f32 v112, v112, v113
	v_cvt_pk_bf16_f32 v113, v114, v115
	global_store_dwordx2 v146, v[112:113], s[66:67]
	v_pk_mul_f32 v[116:117], v[116:117], v[204:205] op_sel_hi:[1,0]
	v_pk_mul_f32 v[118:119], v[118:119], v[204:205] op_sel_hi:[1,0]
	v_pk_mul_f32 v[116:117], v[192:193], v[116:117]
	v_pk_mul_f32 v[118:119], v[194:195], v[118:119]
	v_pk_fma_f32 v[116:117], v[38:39], v[116:117], v[228:229]
	v_pk_fma_f32 v[118:119], v[40:41], v[118:119], v[230:231]
	v_cvt_pk_bf16_f32 v116, v116, v117
	v_cvt_pk_bf16_f32 v117, v118, v119
	global_store_dwordx2 v146, v[116:117], s[66:67] offset:512
	v_pk_mul_f32 v[120:121], v[120:121], v[204:205] op_sel_hi:[1,0]
	v_pk_mul_f32 v[122:123], v[122:123], v[204:205] op_sel_hi:[1,0]
	v_pk_mul_f32 v[120:121], v[196:197], v[120:121]
	v_pk_mul_f32 v[122:123], v[198:199], v[122:123]
	v_pk_fma_f32 v[120:121], v[42:43], v[120:121], v[232:233]
	v_pk_fma_f32 v[122:123], v[44:45], v[122:123], v[234:235]
	v_cvt_pk_bf16_f32 v120, v120, v121
	v_cvt_pk_bf16_f32 v121, v122, v123
	global_store_dwordx2 v146, v[120:121], s[66:67] offset:1024
	v_pk_mul_f32 v[124:125], v[124:125], v[204:205] op_sel_hi:[1,0]
	v_pk_mul_f32 v[126:127], v[126:127], v[204:205] op_sel_hi:[1,0]
	v_pk_mul_f32 v[124:125], v[200:201], v[124:125]
	v_pk_mul_f32 v[126:127], v[202:203], v[126:127]
	v_pk_fma_f32 v[124:125], v[46:47], v[124:125], v[236:237]
	v_pk_fma_f32 v[126:127], v[48:49], v[126:127], v[238:239]
	v_cvt_pk_bf16_f32 v124, v124, v125
	v_cvt_pk_bf16_f32 v125, v126, v127
	global_store_dwordx2 v146, v[124:125], s[66:67] offset:1536
	v_add_u32_e32 v146, 0x800, v146
	v_lshl_add_u32 v144, v50, 13, v241
	v_mov_b32_e32 v152, v144
	v_add_u32_e32 v150, 0x1000000, v144
	global_load_dwordx4 v[112:115], v144, s[16:17]
	global_load_dwordx4 v[116:119], v144, s[16:17] offset:1024
	global_load_dwordx4 v[120:123], v144, s[16:17] offset:2048
	global_load_dwordx4 v[124:127], v144, s[16:17] offset:3072
	v_add_u32_e32 v144, 0x1000, v144
	s_waitcnt vmcnt(32)
	v_pk_mul_f32 v[242:243], v[128:129], v[128:129]
	v_pk_mul_f32 v[244:245], v[132:133], v[132:133]
	v_pk_mul_f32 v[246:247], v[130:131], v[130:131]
	v_pk_mul_f32 v[248:249], v[134:135], v[134:135]
	v_add_f32_e32 v204, v245, v244
	v_add_f32_e32 v205, v243, v242
	v_add_f32_e32 v204, v248, v204
	v_add_f32_e32 v205, v246, v205
	v_add_f32_e32 v204, v249, v204
	v_add_f32_e32 v205, v247, v205
	v_pk_mul_f32 v[242:243], v[136:137], v[136:137]
	v_pk_mul_f32 v[244:245], v[140:141], v[140:141]
	v_pk_mul_f32 v[246:247], v[138:139], v[138:139]
	v_pk_mul_f32 v[248:249], v[142:143], v[142:143]
	v_add_f32_e32 v206, v243, v242
	v_add_f32_e32 v207, v245, v244
	v_add_f32_e32 v206, v246, v206
	v_add_f32_e32 v207, v248, v207
	v_add_f32_e32 v206, v247, v206
	v_add_f32_e32 v207, v249, v207
	v_add_f32_e32 v204, v205, v204
	v_add_f32_e32 v204, v204, v206
	v_add_f32_e32 v204, v204, v207
	ds_swizzle_b32 v205, v204 offset:swizzle(SWAP,1)
	s_waitcnt lgkmcnt(0)
	v_add_f32_e32 v204, v204, v205
	ds_swizzle_b32 v205, v204 offset:swizzle(SWAP,2)
	s_waitcnt lgkmcnt(0)
	v_add_f32_e32 v204, v204, v205
	ds_swizzle_b32 v205, v204 offset:swizzle(SWAP,4)
	s_waitcnt lgkmcnt(0)
	v_add_f32_e32 v204, v204, v205
	ds_swizzle_b32 v205, v204 offset:swizzle(SWAP,8)
	s_waitcnt lgkmcnt(0)
	v_add_f32_e32 v204, v204, v205
	ds_swizzle_b32 v205, v204 offset:swizzle(SWAP,16)
	s_waitcnt lgkmcnt(0)
; __device__ __forceinline__ unsigned pk2(float lo, float hi) { const g_f32x2 f = {lo, hi}; return __builtin_bit_cast(unsigned, __builtin_convertvector(f, g_bf16x2)); }
; __device__ __forceinline__ void p_norm(const float* hlat, const float* hctx, const float* g, const float* modl, int sh_off, int sc_off, bf16_t* A, int M,
;                                        const float* part, const float* cgate, float* hcout) {
;     ...
;         float ss = 0.f;
; #pragma unroll
;         for (int i = 0; i < 4; ++i) {
;             if (part != nullptr && row >= NLAT) {
;                 const size_t po = (size_t)(row - NLAT) * 1024 + i * 256 + lane * 4;
;                 const float4 p0 = *(const float4*)(part + po), p1 = *(const float4*)(part + (size_t)4096 * 1024 + po), cg = *(const float4*)(cgate + i * 256 + lane * 4);
;                 v[i].x += cg.x * (p0.x + p1.x); v[i].y += cg.y * (p0.y + p1.y); v[i].z += cg.z * (p0.z + p1.z); v[i].w += cg.w * (p0.w + p1.w);
;                 *(float4*)(hcout + po) = v[i];
;             }
;             ss += v[i].x * v[i].x + v[i].y * v[i].y + v[i].z * v[i].z + v[i].w * v[i].w; }
;         ss = wave_sum(ss);
;         const float rstd = rsqrtf(ss * (1.0f / 1024.0f) + EPS);
;         const float* mr = modl + (size_t)r * 6144;
; #pragma unroll
;         for (int i = 0; i < 4; ++i) {
;             const int k = i * 256 + lane * 4;
;             const float4 gg = *(const float4*)(g + k), scv = *(const float4*)(mr + sc_off + k), shv = *(const float4*)(mr + sh_off + k);
;             const float o0 = v[i].x * rstd * gg.x * (1.0f + scv.x) + shv.x, o1 = v[i].y * rstd * gg.y * (1.0f + scv.y) + shv.y;
;             const float o2 = v[i].z * rstd * gg.z * (1.0f + scv.z) + shv.z, o3 = v[i].w * rstd * gg.w * (1.0f + scv.w) + shv.w;
;             uint2 w; w.x = pk2(o0, o1); w.y = pk2(o2, o3);
;             *(uint2*)(A + (size_t)row * 1024 + k) = w;
;         }
; #pragma unroll
;         for (int i = 0; i < 4; ++i) v[i] = nv[i];
;         row = nrow;
;     }
	v_add_f32_e32 v204, v204, v205
	v_mov_b32_e32 v205, v204
	s_nop 1
	v_permlane32_swap_b32_e32 v204, v205
	v_add_f32_e32 v204, v204, v205
	v_mov_b32_e32 v205, 0x358637bd
	v_fmamk_f32 v204, v204, 0x3a800000, v205
	v_rsq_f32_e32 v204, v204
	s_nop 0
	v_pk_mul_f32 v[128:129], v[128:129], v[204:205] op_sel_hi:[1,0]
	v_pk_mul_f32 v[130:131], v[130:131], v[204:205] op_sel_hi:[1,0]
	v_pk_mul_f32 v[128:129], v[188:189], v[128:129]
	v_pk_mul_f32 v[130:131], v[190:191], v[130:131]
	v_pk_fma_f32 v[128:129], v[34:35], v[128:129], v[224:225]
	v_pk_fma_f32 v[130:131], v[36:37], v[130:131], v[226:227]
	v_cvt_pk_bf16_f32 v128, v128, v129
	v_cvt_pk_bf16_f32 v129, v130, v131
	global_store_dwordx2 v146, v[128:129], s[66:67]
	v_pk_mul_f32 v[132:133], v[132:133], v[204:205] op_sel_hi:[1,0]
	v_pk_mul_f32 v[134:135], v[134:135], v[204:205] op_sel_hi:[1,0]
	v_pk_mul_f32 v[132:133], v[192:193], v[132:133]
	v_pk_mul_f32 v[134:135], v[194:195], v[134:135]
	v_pk_fma_f32 v[132:133], v[38:39], v[132:133], v[228:229]
	v_pk_fma_f32 v[134:135], v[40:41], v[134:135], v[230:231]
	v_cvt_pk_bf16_f32 v132, v132, v133
	v_cvt_pk_bf16_f32 v133, v134, v135
	global_store_dwordx2 v146, v[132:133], s[66:67] offset:512
	v_pk_mul_f32 v[136:137], v[136:137], v[204:205] op_sel_hi:[1,0]
	v_pk_mul_f32 v[138:139], v[138:139], v[204:205] op_sel_hi:[1,0]
	v_pk_mul_f32 v[136:137], v[196:197], v[136:137]
	v_pk_mul_f32 v[138:139], v[198:199], v[138:139]
	v_pk_fma_f32 v[136:137], v[42:43], v[136:137], v[232:233]
	v_pk_fma_f32 v[138:139], v[44:45], v[138:139], v[234:235]
	v_cvt_pk_bf16_f32 v136, v136, v137
	v_cvt_pk_bf16_f32 v137, v138, v139
	global_store_dwordx2 v146, v[136:137], s[66:67] offset:1024
	v_pk_mul_f32 v[140:141], v[140:141], v[204:205] op_sel_hi:[1,0]
	v_pk_mul_f32 v[142:143], v[142:143], v[204:205] op_sel_hi:[1,0]
	v_pk_mul_f32 v[140:141], v[200:201], v[140:141]
	v_pk_mul_f32 v[142:143], v[202:203], v[142:143]
	v_pk_fma_f32 v[140:141], v[46:47], v[140:141], v[236:237]
	v_pk_fma_f32 v[142:143], v[48:49], v[142:143], v[238:239]
	v_cvt_pk_bf16_f32 v140, v140, v141
	v_cvt_pk_bf16_f32 v141, v142, v143
	global_store_dwordx2 v146, v[140:141], s[66:67] offset:1536
	v_add_u32_e32 v146, 0x800, v146
	global_load_dwordx4 v[128:131], v144, s[16:17]
	global_load_dwordx4 v[132:135], v144, s[16:17] offset:1024
	global_load_dwordx4 v[136:139], v144, s[16:17] offset:2048
	global_load_dwordx4 v[140:143], v144, s[16:17] offset:3072
	v_add_u32_e32 v144, 0x1000, v144
	s_waitcnt vmcnt(36)
	v_pk_mul_f32 v[242:243], v[156:157], v[156:157]
	v_pk_mul_f32 v[244:245], v[160:161], v[160:161]
	v_pk_mul_f32 v[246:247], v[158:159], v[158:159]
	v_pk_mul_f32 v[248:249], v[162:163], v[162:163]
	v_add_f32_e32 v204, v245, v244
	v_add_f32_e32 v205, v243, v242
	v_add_f32_e32 v204, v248, v204
	v_add_f32_e32 v205, v246, v205
	v_add_f32_e32 v204, v249, v204
	v_add_f32_e32 v205, v247, v205
	v_pk_mul_f32 v[242:243], v[164:165], v[164:165]
	v_pk_mul_f32 v[244:245], v[168:169], v[168:169]
	v_pk_mul_f32 v[246:247], v[166:167], v[166:167]
	v_pk_mul_f32 v[248:249], v[170:171], v[170:171]
	v_add_f32_e32 v206, v243, v242
	v_add_f32_e32 v207, v245, v244
	v_add_f32_e32 v206, v246, v206
	v_add_f32_e32 v207, v248, v207
	v_add_f32_e32 v206, v247, v206
	v_add_f32_e32 v207, v249, v207
	v_add_f32_e32 v204, v205, v204
	v_add_f32_e32 v204, v204, v206
	v_add_f32_e32 v204, v204, v207
	ds_swizzle_b32 v205, v204 offset:swizzle(SWAP,1)
	s_waitcnt lgkmcnt(0)
	v_add_f32_e32 v204, v204, v205
	ds_swizzle_b32 v205, v204 offset:swizzle(SWAP,2)
	s_waitcnt lgkmcnt(0)
	v_add_f32_e32 v204, v204, v205
	ds_swizzle_b32 v205, v204 offset:swizzle(SWAP,4)
	s_waitcnt lgkmcnt(0)
	v_add_f32_e32 v204, v204, v205
	ds_swizzle_b32 v205, v204 offset:swizzle(SWAP,8)
	s_waitcnt lgkmcnt(0)
	v_add_f32_e32 v204, v204, v205
	ds_swizzle_b32 v205, v204 offset:swizzle(SWAP,16)
	s_waitcnt lgkmcnt(0)
	v_add_f32_e32 v204, v204, v205
	v_mov_b32_e32 v205, v204
	s_nop 1
	v_permlane32_swap_b32_e32 v204, v205
	v_add_f32_e32 v204, v204, v205
	v_mov_b32_e32 v205, 0x358637bd
	v_fmamk_f32 v204, v204, 0x3a800000, v205
	v_rsq_f32_e32 v204, v204
	s_nop 0
	v_pk_mul_f32 v[156:157], v[156:157], v[204:205] op_sel_hi:[1,0]
	v_pk_mul_f32 v[158:159], v[158:159], v[204:205] op_sel_hi:[1,0]
	v_pk_mul_f32 v[156:157], v[188:189], v[156:157]
	v_pk_mul_f32 v[158:159], v[190:191], v[158:159]
	v_pk_fma_f32 v[156:157], v[34:35], v[156:157], v[224:225]
	v_pk_fma_f32 v[158:159], v[36:37], v[158:159], v[226:227]
	v_cvt_pk_bf16_f32 v156, v156, v157
	v_cvt_pk_bf16_f32 v157, v158, v159
	global_store_dwordx2 v146, v[156:157], s[66:67]
	v_pk_mul_f32 v[160:161], v[160:161], v[204:205] op_sel_hi:[1,0]
	v_pk_mul_f32 v[162:163], v[162:163], v[204:205] op_sel_hi:[1,0]
	v_pk_mul_f32 v[160:161], v[192:193], v[160:161]
	v_pk_mul_f32 v[162:163], v[194:195], v[162:163]
	v_pk_fma_f32 v[160:161], v[38:39], v[160:161], v[228:229]
	v_pk_fma_f32 v[162:163], v[40:41], v[162:163], v[230:231]
	v_cvt_pk_bf16_f32 v160, v160, v161
	v_cvt_pk_bf16_f32 v161, v162, v163
	global_store_dwordx2 v146, v[160:161], s[66:67] offset:512
	v_pk_mul_f32 v[164:165], v[164:165], v[204:205] op_sel_hi:[1,0]
	v_pk_mul_f32 v[166:167], v[166:167], v[204:205] op_sel_hi:[1,0]
	v_pk_mul_f32 v[164:165], v[196:197], v[164:165]
	v_pk_mul_f32 v[166:167], v[198:199], v[166:167]
	v_pk_fma_f32 v[164:165], v[42:43], v[164:165], v[232:233]
	v_pk_fma_f32 v[166:167], v[44:45], v[166:167], v[234:235]
	v_cvt_pk_bf16_f32 v164, v164, v165
	v_cvt_pk_bf16_f32 v165, v166, v167
	global_store_dwordx2 v146, v[164:165], s[66:67] offset:1024
	v_pk_mul_f32 v[168:169], v[168:169], v[204:205] op_sel_hi:[1,0]
	v_pk_mul_f32 v[170:171], v[170:171], v[204:205] op_sel_hi:[1,0]
	v_pk_mul_f32 v[168:169], v[200:201], v[168:169]
	v_pk_mul_f32 v[170:171], v[202:203], v[170:171]
	v_pk_fma_f32 v[168:169], v[46:47], v[168:169], v[236:237]
	v_pk_fma_f32 v[170:171], v[48:49], v[170:171], v[238:239]
	v_cvt_pk_bf16_f32 v168, v168, v169
	v_cvt_pk_bf16_f32 v169, v170, v171
	global_store_dwordx2 v146, v[168:169], s[66:67] offset:1536
	v_add_u32_e32 v146, 0x800, v146
	global_load_dwordx4 v[8:11], v241, s[20:21]
	global_load_dwordx4 v[52:55], v241, s[20:21] offset:1024
	global_load_dwordx4 v[60:63], v241, s[20:21] offset:2048
	global_load_dwordx4 v[64:67], v241, s[20:21] offset:3072
	s_waitcnt vmcnt(40)
; __device__ __forceinline__ unsigned pk2(float lo, float hi) { const g_f32x2 f = {lo, hi}; return __builtin_bit_cast(unsigned, __builtin_convertvector(f, g_bf16x2)); }
; __device__ __forceinline__ void p_norm(const float* hlat, const float* hctx, const float* g, const float* modl, int sh_off, int sc_off, bf16_t* A, int M,
;                                        const float* part, const float* cgate, float* hcout) {
;     ...
;     if (row < M) PN_LOAD(v, row);
;     while (row < M) {
;         const int nrow = row + stride;
;         if (nrow < M) PN_LOAD(nv, nrow);
;         const int r = row < NLAT ? (row >> 11) : 16;
;         float ss = 0.f;
; #pragma unroll
;         for (int i = 0; i < 4; ++i) {
;             if (part != nullptr && row >= NLAT) {
;                 const size_t po = (size_t)(row - NLAT) * 1024 + i * 256 + lane * 4;
;                 const float4 p0 = *(const float4*)(part + po), p1 = *(const float4*)(part + (size_t)4096 * 1024 + po), cg = *(const float4*)(cgate + i * 256 + lane * 4);
;                 v[i].x += cg.x * (p0.x + p1.x); v[i].y += cg.y * (p0.y + p1.y); v[i].z += cg.z * (p0.z + p1.z); v[i].w += cg.w * (p0.w + p1.w);
;                 *(float4*)(hcout + po) = v[i];
;             }
;             ss += v[i].x * v[i].x + v[i].y * v[i].y + v[i].z * v[i].z + v[i].w * v[i].w; }
;         ss = wave_sum(ss);
;         const float rstd = rsqrtf(ss * (1.0f / 1024.0f) + EPS);
;         const float* mr = modl + (size_t)r * 6144;
; #pragma unroll
;         for (int i = 0; i < 4; ++i) {
;             const int k = i * 256 + lane * 4;
;             const float4 gg = *(const float4*)(g + k), scv = *(const float4*)(mr + sc_off + k), shv = *(const float4*)(mr + sh_off + k);
;             const float o0 = v[i].x * rstd * gg.x * (1.0f + scv.x) + shv.x, o1 = v[i].y * rstd * gg.y * (1.0f + scv.y) + shv.y;
;             const float o2 = v[i].z * rstd * gg.z * (1.0f + scv.z) + shv.z, o3 = v[i].w * rstd * gg.w * (1.0f + scv.w) + shv.w;
;             uint2 w; w.x = pk2(o0, o1); w.y = pk2(o2, o3);
;             *(uint2*)(A + (size_t)row * 1024 + k) = w;
;         }
; #pragma unroll
;         for (int i = 0; i < 4; ++i) v[i] = nv[i];
;         row = nrow;
;     }
	v_pk_mul_f32 v[242:243], v[172:173], v[172:173]
	v_pk_mul_f32 v[244:245], v[176:177], v[176:177]
	v_pk_mul_f32 v[246:247], v[174:175], v[174:175]
	v_pk_mul_f32 v[248:249], v[178:179], v[178:179]
	v_add_f32_e32 v204, v245, v244
	v_add_f32_e32 v205, v243, v242
	v_add_f32_e32 v204, v248, v204
	v_add_f32_e32 v205, v246, v205
	v_add_f32_e32 v204, v249, v204
	v_add_f32_e32 v205, v247, v205
	v_pk_mul_f32 v[242:243], v[180:181], v[180:181]
	v_pk_mul_f32 v[244:245], v[184:185], v[184:185]
	v_pk_mul_f32 v[246:247], v[182:183], v[182:183]
	v_pk_mul_f32 v[248:249], v[186:187], v[186:187]
	v_add_f32_e32 v206, v243, v242
	v_add_f32_e32 v207, v245, v244
	v_add_f32_e32 v206, v246, v206
	v_add_f32_e32 v207, v248, v207
	v_add_f32_e32 v206, v247, v206
	v_add_f32_e32 v207, v249, v207
	v_add_f32_e32 v204, v205, v204
	v_add_f32_e32 v204, v204, v206
	v_add_f32_e32 v204, v204, v207
	ds_swizzle_b32 v205, v204 offset:swizzle(SWAP,1)
	s_waitcnt lgkmcnt(0)
	v_add_f32_e32 v204, v204, v205
	ds_swizzle_b32 v205, v204 offset:swizzle(SWAP,2)
	s_waitcnt lgkmcnt(0)
	v_add_f32_e32 v204, v204, v205
	ds_swizzle_b32 v205, v204 offset:swizzle(SWAP,4)
	s_waitcnt lgkmcnt(0)
	v_add_f32_e32 v204, v204, v205
	ds_swizzle_b32 v205, v204 offset:swizzle(SWAP,8)
	s_waitcnt lgkmcnt(0)
	v_add_f32_e32 v204, v204, v205
	ds_swizzle_b32 v205, v204 offset:swizzle(SWAP,16)
	s_waitcnt lgkmcnt(0)
	v_add_f32_e32 v204, v204, v205
	v_mov_b32_e32 v205, v204
	s_nop 1
	v_permlane32_swap_b32_e32 v204, v205
	v_add_f32_e32 v204, v204, v205
	v_mov_b32_e32 v205, 0x358637bd
	v_fmamk_f32 v204, v204, 0x3a800000, v205
	v_rsq_f32_e32 v204, v204
	s_nop 0
	v_pk_mul_f32 v[172:173], v[172:173], v[204:205] op_sel_hi:[1,0]
	v_pk_mul_f32 v[174:175], v[174:175], v[204:205] op_sel_hi:[1,0]
	v_pk_mul_f32 v[172:173], v[188:189], v[172:173]
	v_pk_mul_f32 v[174:175], v[190:191], v[174:175]
	v_pk_fma_f32 v[172:173], v[34:35], v[172:173], v[224:225]
	v_pk_fma_f32 v[174:175], v[36:37], v[174:175], v[226:227]
	v_cvt_pk_bf16_f32 v172, v172, v173
	v_cvt_pk_bf16_f32 v173, v174, v175
	global_store_dwordx2 v146, v[172:173], s[66:67]
	v_pk_mul_f32 v[176:177], v[176:177], v[204:205] op_sel_hi:[1,0]
	v_pk_mul_f32 v[178:179], v[178:179], v[204:205] op_sel_hi:[1,0]
	v_pk_mul_f32 v[176:177], v[192:193], v[176:177]
	v_pk_mul_f32 v[178:179], v[194:195], v[178:179]
	v_pk_fma_f32 v[176:177], v[38:39], v[176:177], v[228:229]
	v_pk_fma_f32 v[178:179], v[40:41], v[178:179], v[230:231]
	v_cvt_pk_bf16_f32 v176, v176, v177
	v_cvt_pk_bf16_f32 v177, v178, v179
	global_store_dwordx2 v146, v[176:177], s[66:67] offset:512
	v_pk_mul_f32 v[180:181], v[180:181], v[204:205] op_sel_hi:[1,0]
	v_pk_mul_f32 v[182:183], v[182:183], v[204:205] op_sel_hi:[1,0]
	v_pk_mul_f32 v[180:181], v[196:197], v[180:181]
	v_pk_mul_f32 v[182:183], v[198:199], v[182:183]
	v_pk_fma_f32 v[180:181], v[42:43], v[180:181], v[232:233]
	v_pk_fma_f32 v[182:183], v[44:45], v[182:183], v[234:235]
	v_cvt_pk_bf16_f32 v180, v180, v181
	v_cvt_pk_bf16_f32 v181, v182, v183
	global_store_dwordx2 v146, v[180:181], s[66:67] offset:1024
	v_pk_mul_f32 v[184:185], v[184:185], v[204:205] op_sel_hi:[1,0]
	v_pk_mul_f32 v[186:187], v[186:187], v[204:205] op_sel_hi:[1,0]
	v_pk_mul_f32 v[184:185], v[200:201], v[184:185]
	v_pk_mul_f32 v[186:187], v[202:203], v[186:187]
	v_pk_fma_f32 v[184:185], v[46:47], v[184:185], v[236:237]
	v_pk_fma_f32 v[186:187], v[48:49], v[186:187], v[238:239]
	v_cvt_pk_bf16_f32 v184, v184, v185
	v_cvt_pk_bf16_f32 v185, v186, v187
	global_store_dwordx2 v146, v[184:185], s[66:67] offset:1536
	v_add_u32_e32 v146, 0x800, v146
	global_load_dwordx4 v[156:159], v152, s[70:71]
	global_load_dwordx4 v[160:163], v152, s[70:71] offset:1024
	global_load_dwordx4 v[164:167], v152, s[70:71] offset:2048
	global_load_dwordx4 v[168:171], v152, s[70:71] offset:3072
	global_load_dwordx4 v[172:175], v150, s[70:71]
	global_load_dwordx4 v[176:179], v150, s[70:71] offset:1024
	global_load_dwordx4 v[180:183], v150, s[70:71] offset:2048
	global_load_dwordx4 v[184:187], v150, s[70:71] offset:3072
	s_waitcnt vmcnt(44)
	v_pk_mul_f32 v[242:243], v[80:81], v[80:81]
	v_pk_mul_f32 v[244:245], v[84:85], v[84:85]
	v_pk_mul_f32 v[246:247], v[82:83], v[82:83]
	v_pk_mul_f32 v[248:249], v[86:87], v[86:87]
	v_add_f32_e32 v204, v245, v244
	v_add_f32_e32 v205, v243, v242
	v_add_f32_e32 v204, v248, v204
	v_add_f32_e32 v205, v246, v205
	v_add_f32_e32 v204, v249, v204
	v_add_f32_e32 v205, v247, v205
	v_pk_mul_f32 v[242:243], v[88:89], v[88:89]
	v_pk_mul_f32 v[244:245], v[92:93], v[92:93]
	v_pk_mul_f32 v[246:247], v[90:91], v[90:91]
	v_pk_mul_f32 v[248:249], v[94:95], v[94:95]
	v_add_f32_e32 v206, v243, v242
	v_add_f32_e32 v207, v245, v244
	v_add_f32_e32 v206, v246, v206
	v_add_f32_e32 v207, v248, v207
	v_add_f32_e32 v206, v247, v206
	v_add_f32_e32 v207, v249, v207
	v_add_f32_e32 v204, v205, v204
	v_add_f32_e32 v204, v204, v206
	v_add_f32_e32 v204, v204, v207
	ds_swizzle_b32 v205, v204 offset:swizzle(SWAP,1)
	s_waitcnt lgkmcnt(0)
	v_add_f32_e32 v204, v204, v205
	ds_swizzle_b32 v205, v204 offset:swizzle(SWAP,2)
	s_waitcnt lgkmcnt(0)
	v_add_f32_e32 v204, v204, v205
	ds_swizzle_b32 v205, v204 offset:swizzle(SWAP,4)
	s_waitcnt lgkmcnt(0)
	v_add_f32_e32 v204, v204, v205
	ds_swizzle_b32 v205, v204 offset:swizzle(SWAP,8)
	s_waitcnt lgkmcnt(0)
	v_add_f32_e32 v204, v204, v205
	ds_swizzle_b32 v205, v204 offset:swizzle(SWAP,16)
	s_waitcnt lgkmcnt(0)
; __device__ __forceinline__ unsigned pk2(float lo, float hi) { const g_f32x2 f = {lo, hi}; return __builtin_bit_cast(unsigned, __builtin_convertvector(f, g_bf16x2)); }
; __device__ __forceinline__ void p_norm(const float* hlat, const float* hctx, const float* g, const float* modl, int sh_off, int sc_off, bf16_t* A, int M,
;                                        const float* part, const float* cgate, float* hcout) {
;     ...
;     if (row < M) PN_LOAD(v, row);
;     while (row < M) {
;         const int nrow = row + stride;
;         if (nrow < M) PN_LOAD(nv, nrow);
;         const int r = row < NLAT ? (row >> 11) : 16;
;         float ss = 0.f;
; #pragma unroll
;         for (int i = 0; i < 4; ++i) {
;             if (part != nullptr && row >= NLAT) {
;                 const size_t po = (size_t)(row - NLAT) * 1024 + i * 256 + lane * 4;
;                 const float4 p0 = *(const float4*)(part + po), p1 = *(const float4*)(part + (size_t)4096 * 1024 + po), cg = *(const float4*)(cgate + i * 256 + lane * 4);
;                 v[i].x += cg.x * (p0.x + p1.x); v[i].y += cg.y * (p0.y + p1.y); v[i].z += cg.z * (p0.z + p1.z); v[i].w += cg.w * (p0.w + p1.w);
;                 *(float4*)(hcout + po) = v[i];
;             }
;             ss += v[i].x * v[i].x + v[i].y * v[i].y + v[i].z * v[i].z + v[i].w * v[i].w; }
;         ss = wave_sum(ss);
;         const float rstd = rsqrtf(ss * (1.0f / 1024.0f) + EPS);
;         const float* mr = modl + (size_t)r * 6144;
; #pragma unroll
;         for (int i = 0; i < 4; ++i) {
;             const int k = i * 256 + lane * 4;
;             const float4 gg = *(const float4*)(g + k), scv = *(const float4*)(mr + sc_off + k), shv = *(const float4*)(mr + sh_off + k);
;             const float o0 = v[i].x * rstd * gg.x * (1.0f + scv.x) + shv.x, o1 = v[i].y * rstd * gg.y * (1.0f + scv.y) + shv.y;
;             const float o2 = v[i].z * rstd * gg.z * (1.0f + scv.z) + shv.z, o3 = v[i].w * rstd * gg.w * (1.0f + scv.w) + shv.w;
;             uint2 w; w.x = pk2(o0, o1); w.y = pk2(o2, o3);
;             *(uint2*)(A + (size_t)row * 1024 + k) = w;
;         }
; #pragma unroll
;         for (int i = 0; i < 4; ++i) v[i] = nv[i];
;         row = nrow;
;     }
	v_add_f32_e32 v204, v204, v205
	v_mov_b32_e32 v205, v204
	s_nop 1
	v_permlane32_swap_b32_e32 v204, v205
	v_add_f32_e32 v204, v204, v205
	v_mov_b32_e32 v205, 0x358637bd
	v_fmamk_f32 v204, v204, 0x3a800000, v205
	v_rsq_f32_e32 v204, v204
	s_nop 0
	v_pk_mul_f32 v[80:81], v[80:81], v[204:205] op_sel_hi:[1,0]
	v_pk_mul_f32 v[82:83], v[82:83], v[204:205] op_sel_hi:[1,0]
	v_pk_mul_f32 v[80:81], v[188:189], v[80:81]
	v_pk_mul_f32 v[82:83], v[190:191], v[82:83]
	v_pk_fma_f32 v[80:81], v[34:35], v[80:81], v[224:225]
	v_pk_fma_f32 v[82:83], v[36:37], v[82:83], v[226:227]
	v_cvt_pk_bf16_f32 v80, v80, v81
	v_cvt_pk_bf16_f32 v81, v82, v83
	global_store_dwordx2 v146, v[80:81], s[66:67]
	v_pk_mul_f32 v[84:85], v[84:85], v[204:205] op_sel_hi:[1,0]
	v_pk_mul_f32 v[86:87], v[86:87], v[204:205] op_sel_hi:[1,0]
	v_pk_mul_f32 v[84:85], v[192:193], v[84:85]
	v_pk_mul_f32 v[86:87], v[194:195], v[86:87]
	v_pk_fma_f32 v[84:85], v[38:39], v[84:85], v[228:229]
	v_pk_fma_f32 v[86:87], v[40:41], v[86:87], v[230:231]
	v_cvt_pk_bf16_f32 v84, v84, v85
	v_cvt_pk_bf16_f32 v85, v86, v87
	global_store_dwordx2 v146, v[84:85], s[66:67] offset:512
	v_pk_mul_f32 v[88:89], v[88:89], v[204:205] op_sel_hi:[1,0]
	v_pk_mul_f32 v[90:91], v[90:91], v[204:205] op_sel_hi:[1,0]
	v_pk_mul_f32 v[88:89], v[196:197], v[88:89]
	v_pk_mul_f32 v[90:91], v[198:199], v[90:91]
	v_pk_fma_f32 v[88:89], v[42:43], v[88:89], v[232:233]
	v_pk_fma_f32 v[90:91], v[44:45], v[90:91], v[234:235]
	v_cvt_pk_bf16_f32 v88, v88, v89
	v_cvt_pk_bf16_f32 v89, v90, v91
	global_store_dwordx2 v146, v[88:89], s[66:67] offset:1024
	v_pk_mul_f32 v[92:93], v[92:93], v[204:205] op_sel_hi:[1,0]
	v_pk_mul_f32 v[94:95], v[94:95], v[204:205] op_sel_hi:[1,0]
	v_pk_mul_f32 v[92:93], v[200:201], v[92:93]
	v_pk_mul_f32 v[94:95], v[202:203], v[94:95]
	v_pk_fma_f32 v[92:93], v[46:47], v[92:93], v[236:237]
	v_pk_fma_f32 v[94:95], v[48:49], v[94:95], v[238:239]
	v_cvt_pk_bf16_f32 v92, v92, v93
	v_cvt_pk_bf16_f32 v93, v94, v95
	global_store_dwordx2 v146, v[92:93], s[66:67] offset:1536
	v_add_u32_e32 v146, 0x800, v146
	v_add_u32_e32 v207, 0x1000, v152
	global_load_dwordx4 v[80:83], v207, s[70:71]
	global_load_dwordx4 v[84:87], v207, s[70:71] offset:1024
	global_load_dwordx4 v[88:91], v207, s[70:71] offset:2048
	global_load_dwordx4 v[92:95], v207, s[70:71] offset:3072
	s_waitcnt vmcnt(44)
	v_pk_mul_f32 v[242:243], v[96:97], v[96:97]
	v_pk_mul_f32 v[244:245], v[100:101], v[100:101]
	v_pk_mul_f32 v[246:247], v[98:99], v[98:99]
	v_pk_mul_f32 v[248:249], v[102:103], v[102:103]
	v_add_f32_e32 v204, v245, v244
	v_add_f32_e32 v205, v243, v242
	v_add_f32_e32 v204, v248, v204
	v_add_f32_e32 v205, v246, v205
	v_add_f32_e32 v204, v249, v204
	v_add_f32_e32 v205, v247, v205
	v_pk_mul_f32 v[242:243], v[104:105], v[104:105]
	v_pk_mul_f32 v[244:245], v[108:109], v[108:109]
	v_pk_mul_f32 v[246:247], v[106:107], v[106:107]
	v_pk_mul_f32 v[248:249], v[110:111], v[110:111]
	v_add_f32_e32 v206, v243, v242
	v_add_f32_e32 v207, v245, v244
	v_add_f32_e32 v206, v246, v206
	v_add_f32_e32 v207, v248, v207
	v_add_f32_e32 v206, v247, v206
	v_add_f32_e32 v207, v249, v207
	v_add_f32_e32 v204, v205, v204
	v_add_f32_e32 v204, v204, v206
	v_add_f32_e32 v204, v204, v207
	ds_swizzle_b32 v205, v204 offset:swizzle(SWAP,1)
	s_waitcnt lgkmcnt(0)
	v_add_f32_e32 v204, v204, v205
	ds_swizzle_b32 v205, v204 offset:swizzle(SWAP,2)
	s_waitcnt lgkmcnt(0)
	v_add_f32_e32 v204, v204, v205
	ds_swizzle_b32 v205, v204 offset:swizzle(SWAP,4)
	s_waitcnt lgkmcnt(0)
	v_add_f32_e32 v204, v204, v205
	ds_swizzle_b32 v205, v204 offset:swizzle(SWAP,8)
	s_waitcnt lgkmcnt(0)
	v_add_f32_e32 v204, v204, v205
	ds_swizzle_b32 v205, v204 offset:swizzle(SWAP,16)
	s_waitcnt lgkmcnt(0)
	v_add_f32_e32 v204, v204, v205
	v_mov_b32_e32 v205, v204
	s_nop 1
	v_permlane32_swap_b32_e32 v204, v205
	v_add_f32_e32 v204, v204, v205
	v_mov_b32_e32 v205, 0x358637bd
	v_fmamk_f32 v204, v204, 0x3a800000, v205
	v_rsq_f32_e32 v204, v204
	s_nop 0
	v_pk_mul_f32 v[96:97], v[96:97], v[204:205] op_sel_hi:[1,0]
	v_pk_mul_f32 v[98:99], v[98:99], v[204:205] op_sel_hi:[1,0]
	v_pk_mul_f32 v[96:97], v[188:189], v[96:97]
	v_pk_mul_f32 v[98:99], v[190:191], v[98:99]
	v_pk_fma_f32 v[96:97], v[34:35], v[96:97], v[224:225]
	v_pk_fma_f32 v[98:99], v[36:37], v[98:99], v[226:227]
	v_cvt_pk_bf16_f32 v96, v96, v97
	v_cvt_pk_bf16_f32 v97, v98, v99
	global_store_dwordx2 v146, v[96:97], s[66:67]
	v_pk_mul_f32 v[100:101], v[100:101], v[204:205] op_sel_hi:[1,0]
	v_pk_mul_f32 v[102:103], v[102:103], v[204:205] op_sel_hi:[1,0]
	v_pk_mul_f32 v[100:101], v[192:193], v[100:101]
	v_pk_mul_f32 v[102:103], v[194:195], v[102:103]
	v_pk_fma_f32 v[100:101], v[38:39], v[100:101], v[228:229]
	v_pk_fma_f32 v[102:103], v[40:41], v[102:103], v[230:231]
	v_cvt_pk_bf16_f32 v100, v100, v101
	v_cvt_pk_bf16_f32 v101, v102, v103
	global_store_dwordx2 v146, v[100:101], s[66:67] offset:512
	v_pk_mul_f32 v[104:105], v[104:105], v[204:205] op_sel_hi:[1,0]
	v_pk_mul_f32 v[106:107], v[106:107], v[204:205] op_sel_hi:[1,0]
	v_pk_mul_f32 v[104:105], v[196:197], v[104:105]
	v_pk_mul_f32 v[106:107], v[198:199], v[106:107]
	v_pk_fma_f32 v[104:105], v[42:43], v[104:105], v[232:233]
	v_pk_fma_f32 v[106:107], v[44:45], v[106:107], v[234:235]
	v_cvt_pk_bf16_f32 v104, v104, v105
	v_cvt_pk_bf16_f32 v105, v106, v107
	global_store_dwordx2 v146, v[104:105], s[66:67] offset:1024
	v_pk_mul_f32 v[108:109], v[108:109], v[204:205] op_sel_hi:[1,0]
	v_pk_mul_f32 v[110:111], v[110:111], v[204:205] op_sel_hi:[1,0]
	v_pk_mul_f32 v[108:109], v[200:201], v[108:109]
	v_pk_mul_f32 v[110:111], v[202:203], v[110:111]
	v_pk_fma_f32 v[108:109], v[46:47], v[108:109], v[236:237]
	v_pk_fma_f32 v[110:111], v[48:49], v[110:111], v[238:239]
	v_cvt_pk_bf16_f32 v108, v108, v109
	v_cvt_pk_bf16_f32 v109, v110, v111
	global_store_dwordx2 v146, v[108:109], s[66:67] offset:1536
	v_add_u32_e32 v146, 0x800, v146
	v_add_u32_e32 v151, 0x60000, v241
	global_load_dwordx4 v[34:37], v151, s[98:99]
	global_load_dwordx4 v[38:41], v151, s[98:99] offset:1024
	global_load_dwordx4 v[42:45], v151, s[98:99] offset:2048
	global_load_dwordx4 v[46:49], v151, s[98:99] offset:3072
	global_load_dwordx4 v[224:227], v151, s[50:51]
	global_load_dwordx4 v[228:231], v151, s[50:51] offset:1024
	global_load_dwordx4 v[232:235], v151, s[50:51] offset:2048
	global_load_dwordx4 v[236:239], v151, s[50:51] offset:3072
	v_add_u32_e32 v207, 0x1000, v150
	global_load_dwordx4 v[96:99], v207, s[70:71]
	global_load_dwordx4 v[100:103], v207, s[70:71] offset:1024
	global_load_dwordx4 v[104:107], v207, s[70:71] offset:2048
	global_load_dwordx4 v[108:111], v207, s[70:71] offset:3072
	s_waitcnt vmcnt(24)
; __device__ __forceinline__ unsigned pk2(float lo, float hi) { const g_f32x2 f = {lo, hi}; return __builtin_bit_cast(unsigned, __builtin_convertvector(f, g_bf16x2)); }
; __device__ __forceinline__ void p_norm(const float* hlat, const float* hctx, const float* g, const float* modl, int sh_off, int sc_off, bf16_t* A, int M,
;                                        const float* part, const float* cgate, float* hcout) {
;     ...
;             if (part != nullptr && row >= NLAT) {
;                 const size_t po = (size_t)(row - NLAT) * 1024 + i * 256 + lane * 4;
;                 const float4 p0 = *(const float4*)(part + po), p1 = *(const float4*)(part + (size_t)4096 * 1024 + po), cg = *(const float4*)(cgate + i * 256 + lane * 4);
;                 v[i].x += cg.x * (p0.x + p1.x); v[i].y += cg.y * (p0.y + p1.y); v[i].z += cg.z * (p0.z + p1.z); v[i].w += cg.w * (p0.w + p1.w);
;                 *(float4*)(hcout + po) = v[i];
;             }
;             ss += v[i].x * v[i].x + v[i].y * v[i].y + v[i].z * v[i].z + v[i].w * v[i].w; }
;         ss = wave_sum(ss);
;         const float rstd = rsqrtf(ss * (1.0f / 1024.0f) + EPS);
;         const float* mr = modl + (size_t)r * 6144;
; #pragma unroll
;         for (int i = 0; i < 4; ++i) {
;             const int k = i * 256 + lane * 4;
;             const float4 gg = *(const float4*)(g + k), scv = *(const float4*)(mr + sc_off + k), shv = *(const float4*)(mr + sh_off + k);
;             const float o0 = v[i].x * rstd * gg.x * (1.0f + scv.x) + shv.x, o1 = v[i].y * rstd * gg.y * (1.0f + scv.y) + shv.y;
;             const float o2 = v[i].z * rstd * gg.z * (1.0f + scv.z) + shv.z, o3 = v[i].w * rstd * gg.w * (1.0f + scv.w) + shv.w;
;             uint2 w; w.x = pk2(o0, o1); w.y = pk2(o2, o3);
;             *(uint2*)(A + (size_t)row * 1024 + k) = w;
	v_pk_add_f32 v[156:157], v[156:157], v[172:173]
	v_pk_add_f32 v[158:159], v[158:159], v[174:175]
	v_pk_fma_f32 v[112:113], v[156:157], v[8:9], v[112:113]
	v_pk_fma_f32 v[114:115], v[158:159], v[10:11], v[114:115]
	global_store_dwordx4 v152, v[112:115], s[64:65]
	v_pk_add_f32 v[160:161], v[160:161], v[176:177]
	v_pk_add_f32 v[162:163], v[162:163], v[178:179]
	v_pk_fma_f32 v[116:117], v[160:161], v[52:53], v[116:117]
	v_pk_fma_f32 v[118:119], v[162:163], v[54:55], v[118:119]
	global_store_dwordx4 v152, v[116:119], s[64:65] offset:1024
	v_pk_add_f32 v[164:165], v[164:165], v[180:181]
	v_pk_add_f32 v[166:167], v[166:167], v[182:183]
	v_pk_fma_f32 v[120:121], v[164:165], v[60:61], v[120:121]
	v_pk_fma_f32 v[122:123], v[166:167], v[62:63], v[122:123]
	global_store_dwordx4 v152, v[120:123], s[64:65] offset:2048
	v_pk_add_f32 v[168:169], v[168:169], v[184:185]
	v_pk_add_f32 v[170:171], v[170:171], v[186:187]
	v_pk_fma_f32 v[124:125], v[168:169], v[64:65], v[124:125]
	v_pk_fma_f32 v[126:127], v[170:171], v[66:67], v[126:127]
	global_store_dwordx4 v152, v[124:127], s[64:65] offset:3072
	v_add_u32_e32 v152, 0x1000, v152
	v_pk_mul_f32 v[242:243], v[112:113], v[112:113]
	v_pk_mul_f32 v[244:245], v[116:117], v[116:117]
	v_pk_mul_f32 v[246:247], v[114:115], v[114:115]
	v_pk_mul_f32 v[248:249], v[118:119], v[118:119]
	v_add_f32_e32 v204, v245, v244
	v_add_f32_e32 v205, v243, v242
	v_add_f32_e32 v204, v248, v204
	v_add_f32_e32 v205, v246, v205
	v_add_f32_e32 v204, v249, v204
	v_add_f32_e32 v205, v247, v205
	v_pk_mul_f32 v[242:243], v[120:121], v[120:121]
	v_pk_mul_f32 v[244:245], v[124:125], v[124:125]
	v_pk_mul_f32 v[246:247], v[122:123], v[122:123]
	v_pk_mul_f32 v[248:249], v[126:127], v[126:127]
	v_add_f32_e32 v206, v243, v242
	v_add_f32_e32 v207, v245, v244
	v_add_f32_e32 v206, v246, v206
	v_add_f32_e32 v207, v248, v207
	v_add_f32_e32 v206, v247, v206
	v_add_f32_e32 v207, v249, v207
	v_add_f32_e32 v204, v205, v204
	v_add_f32_e32 v204, v204, v206
	v_add_f32_e32 v204, v204, v207
	ds_swizzle_b32 v205, v204 offset:swizzle(SWAP,1)
	s_waitcnt lgkmcnt(0)
	v_add_f32_e32 v204, v204, v205
	ds_swizzle_b32 v205, v204 offset:swizzle(SWAP,2)
	s_waitcnt lgkmcnt(0)
	v_add_f32_e32 v204, v204, v205
	ds_swizzle_b32 v205, v204 offset:swizzle(SWAP,4)
	s_waitcnt lgkmcnt(0)
	v_add_f32_e32 v204, v204, v205
	ds_swizzle_b32 v205, v204 offset:swizzle(SWAP,8)
	s_waitcnt lgkmcnt(0)
	v_add_f32_e32 v204, v204, v205
	ds_swizzle_b32 v205, v204 offset:swizzle(SWAP,16)
	s_waitcnt lgkmcnt(0)
	v_add_f32_e32 v204, v204, v205
	v_mov_b32_e32 v205, v204
	s_nop 1
	v_permlane32_swap_b32_e32 v204, v205
	v_add_f32_e32 v204, v204, v205
	v_mov_b32_e32 v205, 0x358637bd
	v_fmamk_f32 v204, v204, 0x3a800000, v205
	v_rsq_f32_e32 v204, v204
	s_nop 0
	s_waitcnt vmcnt(8)
	v_pk_add_f32 v[34:35], v[34:35], 1.0 op_sel_hi:[1,0]
	v_pk_add_f32 v[36:37], v[36:37], 1.0 op_sel_hi:[1,0]
	v_pk_add_f32 v[38:39], v[38:39], 1.0 op_sel_hi:[1,0]
	v_pk_add_f32 v[40:41], v[40:41], 1.0 op_sel_hi:[1,0]
	v_pk_add_f32 v[42:43], v[42:43], 1.0 op_sel_hi:[1,0]
	v_pk_add_f32 v[44:45], v[44:45], 1.0 op_sel_hi:[1,0]
	v_pk_add_f32 v[46:47], v[46:47], 1.0 op_sel_hi:[1,0]
	v_pk_add_f32 v[48:49], v[48:49], 1.0 op_sel_hi:[1,0]
	v_lshlrev_b32_e32 v146, 12, v50
	v_lshl_add_u32 v146, v240, 3, v146
	v_add_u32_e32 v146, 0x4000000, v146
	v_pk_mul_f32 v[112:113], v[112:113], v[204:205] op_sel_hi:[1,0]
	v_pk_mul_f32 v[114:115], v[114:115], v[204:205] op_sel_hi:[1,0]
	v_pk_mul_f32 v[112:113], v[188:189], v[112:113]
	v_pk_mul_f32 v[114:115], v[190:191], v[114:115]
	v_pk_fma_f32 v[112:113], v[34:35], v[112:113], v[224:225]
	v_pk_fma_f32 v[114:115], v[36:37], v[114:115], v[226:227]
	v_cvt_pk_bf16_f32 v112, v112, v113
	v_cvt_pk_bf16_f32 v113, v114, v115
	global_store_dwordx2 v146, v[112:113], s[66:67]
	v_pk_mul_f32 v[116:117], v[116:117], v[204:205] op_sel_hi:[1,0]
	v_pk_mul_f32 v[118:119], v[118:119], v[204:205] op_sel_hi:[1,0]
	v_pk_mul_f32 v[116:117], v[192:193], v[116:117]
	v_pk_mul_f32 v[118:119], v[194:195], v[118:119]
	v_pk_fma_f32 v[116:117], v[38:39], v[116:117], v[228:229]
	v_pk_fma_f32 v[118:119], v[40:41], v[118:119], v[230:231]
	v_cvt_pk_bf16_f32 v116, v116, v117
	v_cvt_pk_bf16_f32 v117, v118, v119
	global_store_dwordx2 v146, v[116:117], s[66:67] offset:512
	v_pk_mul_f32 v[120:121], v[120:121], v[204:205] op_sel_hi:[1,0]
	v_pk_mul_f32 v[122:123], v[122:123], v[204:205] op_sel_hi:[1,0]
	v_pk_mul_f32 v[120:121], v[196:197], v[120:121]
	v_pk_mul_f32 v[122:123], v[198:199], v[122:123]
	v_pk_fma_f32 v[120:121], v[42:43], v[120:121], v[232:233]
	v_pk_fma_f32 v[122:123], v[44:45], v[122:123], v[234:235]
	v_cvt_pk_bf16_f32 v120, v120, v121
	v_cvt_pk_bf16_f32 v121, v122, v123
	global_store_dwordx2 v146, v[120:121], s[66:67] offset:1024
	v_pk_mul_f32 v[124:125], v[124:125], v[204:205] op_sel_hi:[1,0]
	v_pk_mul_f32 v[126:127], v[126:127], v[204:205] op_sel_hi:[1,0]
	v_pk_mul_f32 v[124:125], v[200:201], v[124:125]
	v_pk_mul_f32 v[126:127], v[202:203], v[126:127]
	v_pk_fma_f32 v[124:125], v[46:47], v[124:125], v[236:237]
	v_pk_fma_f32 v[126:127], v[48:49], v[126:127], v[238:239]
	v_cvt_pk_bf16_f32 v124, v124, v125
	v_cvt_pk_bf16_f32 v125, v126, v127
	global_store_dwordx2 v146, v[124:125], s[66:67] offset:1536
	v_add_u32_e32 v146, 0x800, v146
	s_waitcnt vmcnt(8)
; __device__ __forceinline__ unsigned pk2(float lo, float hi) { const g_f32x2 f = {lo, hi}; return __builtin_bit_cast(unsigned, __builtin_convertvector(f, g_bf16x2)); }
; __device__ __forceinline__ void p_norm(const float* hlat, const float* hctx, const float* g, const float* modl, int sh_off, int sc_off, bf16_t* A, int M,
;                                        const float* part, const float* cgate, float* hcout) {
;     ...
;             if (part != nullptr && row >= NLAT) {
;                 const size_t po = (size_t)(row - NLAT) * 1024 + i * 256 + lane * 4;
;                 const float4 p0 = *(const float4*)(part + po), p1 = *(const float4*)(part + (size_t)4096 * 1024 + po), cg = *(const float4*)(cgate + i * 256 + lane * 4);
;                 v[i].x += cg.x * (p0.x + p1.x); v[i].y += cg.y * (p0.y + p1.y); v[i].z += cg.z * (p0.z + p1.z); v[i].w += cg.w * (p0.w + p1.w);
;                 *(float4*)(hcout + po) = v[i];
;             }
;             ss += v[i].x * v[i].x + v[i].y * v[i].y + v[i].z * v[i].z + v[i].w * v[i].w; }
;         ss = wave_sum(ss);
;         const float rstd = rsqrtf(ss * (1.0f / 1024.0f) + EPS);
;         const float* mr = modl + (size_t)r * 6144;
; #pragma unroll
;         for (int i = 0; i < 4; ++i) {
;             const int k = i * 256 + lane * 4;
;             const float4 gg = *(const float4*)(g + k), scv = *(const float4*)(mr + sc_off + k), shv = *(const float4*)(mr + sh_off + k);
;             const float o0 = v[i].x * rstd * gg.x * (1.0f + scv.x) + shv.x, o1 = v[i].y * rstd * gg.y * (1.0f + scv.y) + shv.y;
;             const float o2 = v[i].z * rstd * gg.z * (1.0f + scv.z) + shv.z, o3 = v[i].w * rstd * gg.w * (1.0f + scv.w) + shv.w;
;             uint2 w; w.x = pk2(o0, o1); w.y = pk2(o2, o3);
;             *(uint2*)(A + (size_t)row * 1024 + k) = w;
	v_pk_add_f32 v[80:81], v[80:81], v[96:97]
	v_pk_add_f32 v[82:83], v[82:83], v[98:99]
	v_pk_fma_f32 v[128:129], v[80:81], v[8:9], v[128:129]
	v_pk_fma_f32 v[130:131], v[82:83], v[10:11], v[130:131]
	global_store_dwordx4 v152, v[128:131], s[64:65]
	v_pk_add_f32 v[84:85], v[84:85], v[100:101]
	v_pk_add_f32 v[86:87], v[86:87], v[102:103]
	v_pk_fma_f32 v[132:133], v[84:85], v[52:53], v[132:133]
	v_pk_fma_f32 v[134:135], v[86:87], v[54:55], v[134:135]
	global_store_dwordx4 v152, v[132:135], s[64:65] offset:1024
	v_pk_add_f32 v[88:89], v[88:89], v[104:105]
	v_pk_add_f32 v[90:91], v[90:91], v[106:107]
	v_pk_fma_f32 v[136:137], v[88:89], v[60:61], v[136:137]
	v_pk_fma_f32 v[138:139], v[90:91], v[62:63], v[138:139]
	global_store_dwordx4 v152, v[136:139], s[64:65] offset:2048
	v_pk_add_f32 v[92:93], v[92:93], v[108:109]
	v_pk_add_f32 v[94:95], v[94:95], v[110:111]
	v_pk_fma_f32 v[140:141], v[92:93], v[64:65], v[140:141]
	v_pk_fma_f32 v[142:143], v[94:95], v[66:67], v[142:143]
	global_store_dwordx4 v152, v[140:143], s[64:65] offset:3072
	v_add_u32_e32 v152, 0x1000, v152
	v_pk_mul_f32 v[242:243], v[128:129], v[128:129]
	v_pk_mul_f32 v[244:245], v[132:133], v[132:133]
	v_pk_mul_f32 v[246:247], v[130:131], v[130:131]
	v_pk_mul_f32 v[248:249], v[134:135], v[134:135]
	v_add_f32_e32 v204, v245, v244
	v_add_f32_e32 v205, v243, v242
	v_add_f32_e32 v204, v248, v204
	v_add_f32_e32 v205, v246, v205
	v_add_f32_e32 v204, v249, v204
	v_add_f32_e32 v205, v247, v205
	v_pk_mul_f32 v[242:243], v[136:137], v[136:137]
	v_pk_mul_f32 v[244:245], v[140:141], v[140:141]
	v_pk_mul_f32 v[246:247], v[138:139], v[138:139]
	v_pk_mul_f32 v[248:249], v[142:143], v[142:143]
	v_add_f32_e32 v206, v243, v242
	v_add_f32_e32 v207, v245, v244
	v_add_f32_e32 v206, v246, v206
	v_add_f32_e32 v207, v248, v207
	v_add_f32_e32 v206, v247, v206
	v_add_f32_e32 v207, v249, v207
	v_add_f32_e32 v204, v205, v204
	v_add_f32_e32 v204, v204, v206
	v_add_f32_e32 v204, v204, v207
	ds_swizzle_b32 v205, v204 offset:swizzle(SWAP,1)
	s_waitcnt lgkmcnt(0)
	v_add_f32_e32 v204, v204, v205
	ds_swizzle_b32 v205, v204 offset:swizzle(SWAP,2)
	s_waitcnt lgkmcnt(0)
	v_add_f32_e32 v204, v204, v205
	ds_swizzle_b32 v205, v204 offset:swizzle(SWAP,4)
	s_waitcnt lgkmcnt(0)
	v_add_f32_e32 v204, v204, v205
	ds_swizzle_b32 v205, v204 offset:swizzle(SWAP,8)
	s_waitcnt lgkmcnt(0)
	v_add_f32_e32 v204, v204, v205
	ds_swizzle_b32 v205, v204 offset:swizzle(SWAP,16)
	s_waitcnt lgkmcnt(0)
	v_add_f32_e32 v204, v204, v205
	v_mov_b32_e32 v205, v204
	s_nop 1
	v_permlane32_swap_b32_e32 v204, v205
	v_add_f32_e32 v204, v204, v205
	v_mov_b32_e32 v205, 0x358637bd
	v_fmamk_f32 v204, v204, 0x3a800000, v205
	v_rsq_f32_e32 v204, v204
	s_nop 0
	v_pk_mul_f32 v[128:129], v[128:129], v[204:205] op_sel_hi:[1,0]
	v_pk_mul_f32 v[130:131], v[130:131], v[204:205] op_sel_hi:[1,0]
	v_pk_mul_f32 v[128:129], v[188:189], v[128:129]
	v_pk_mul_f32 v[130:131], v[190:191], v[130:131]
	v_pk_fma_f32 v[128:129], v[34:35], v[128:129], v[224:225]
	v_pk_fma_f32 v[130:131], v[36:37], v[130:131], v[226:227]
	v_cvt_pk_bf16_f32 v128, v128, v129
	v_cvt_pk_bf16_f32 v129, v130, v131
	global_store_dwordx2 v146, v[128:129], s[66:67]
	v_pk_mul_f32 v[132:133], v[132:133], v[204:205] op_sel_hi:[1,0]
	v_pk_mul_f32 v[134:135], v[134:135], v[204:205] op_sel_hi:[1,0]
	v_pk_mul_f32 v[132:133], v[192:193], v[132:133]
	v_pk_mul_f32 v[134:135], v[194:195], v[134:135]
	v_pk_fma_f32 v[132:133], v[38:39], v[132:133], v[228:229]
	v_pk_fma_f32 v[134:135], v[40:41], v[134:135], v[230:231]
	v_cvt_pk_bf16_f32 v132, v132, v133
	v_cvt_pk_bf16_f32 v133, v134, v135
	global_store_dwordx2 v146, v[132:133], s[66:67] offset:512
	v_pk_mul_f32 v[136:137], v[136:137], v[204:205] op_sel_hi:[1,0]
	v_pk_mul_f32 v[138:139], v[138:139], v[204:205] op_sel_hi:[1,0]
	v_pk_mul_f32 v[136:137], v[196:197], v[136:137]
	v_pk_mul_f32 v[138:139], v[198:199], v[138:139]
	v_pk_fma_f32 v[136:137], v[42:43], v[136:137], v[232:233]
	v_pk_fma_f32 v[138:139], v[44:45], v[138:139], v[234:235]
	v_cvt_pk_bf16_f32 v136, v136, v137
	v_cvt_pk_bf16_f32 v137, v138, v139
	global_store_dwordx2 v146, v[136:137], s[66:67] offset:1024
	v_pk_mul_f32 v[140:141], v[140:141], v[204:205] op_sel_hi:[1,0]
	v_pk_mul_f32 v[142:143], v[142:143], v[204:205] op_sel_hi:[1,0]
	v_pk_mul_f32 v[140:141], v[200:201], v[140:141]
	v_pk_mul_f32 v[142:143], v[202:203], v[142:143]
	v_pk_fma_f32 v[140:141], v[46:47], v[140:141], v[236:237]
	v_pk_fma_f32 v[142:143], v[48:49], v[142:143], v[238:239]
	v_cvt_pk_bf16_f32 v140, v140, v141
	v_cvt_pk_bf16_f32 v141, v142, v143
	global_store_dwordx2 v146, v[140:141], s[66:67] offset:1536
	v_add_u32_e32 v146, 0x800, v146
	s_branch .Lnorm_P1_end

; __device__ __forceinline__ unsigned pk2(float lo, float hi) { const g_f32x2 f = {lo, hi}; return __builtin_bit_cast(unsigned, __builtin_convertvector(f, g_bf16x2)); }
; __device__ __forceinline__ int obid() { int b = blockIdx.x; asm volatile("" : "+s"(b)); return b; }
; __device__ __forceinline__ void p_norm(const float* hlat, const float* hctx, const float* g, const float* modl, int sh_off, int sc_off, bf16_t* A, int M,
;                                        const float* part, const float* cgate, float* hcout) {
;     ...
;     int row = obid() * 8 + wave;
;     float4 v[4], nv[4];
;     ...
;     if (row < M) PN_LOAD(v, row);
;     while (row < M) {
;         const int nrow = row + stride;
;         if (nrow < M) PN_LOAD(nv, nrow);
;         const int r = row < NLAT ? (row >> 11) : 16;
;         float ss = 0.f;
; #pragma unroll
;         for (int i = 0; i < 4; ++i) {
;             if (part != nullptr && row >= NLAT) {
;                 const size_t po = (size_t)(row - NLAT) * 1024 + i * 256 + lane * 4;
;                 const float4 p0 = *(const float4*)(part + po), p1 = *(const float4*)(part + (size_t)4096 * 1024 + po), cg = *(const float4*)(cgate + i * 256 + lane * 4);
;                 v[i].x += cg.x * (p0.x + p1.x); v[i].y += cg.y * (p0.y + p1.y); v[i].z += cg.z * (p0.z + p1.z); v[i].w += cg.w * (p0.w + p1.w);
;                 *(float4*)(hcout + po) = v[i];
;             }
;             ss += v[i].x * v[i].x + v[i].y * v[i].y + v[i].z * v[i].z + v[i].w * v[i].w; }
;         ss = wave_sum(ss);
;         const float rstd = rsqrtf(ss * (1.0f / 1024.0f) + EPS);
;         const float* mr = modl + (size_t)r * 6144;
; #pragma unroll
;         for (int i = 0; i < 4; ++i) {
;             const int k = i * 256 + lane * 4;
;             const float4 gg = *(const float4*)(g + k), scv = *(const float4*)(mr + sc_off + k), shv = *(const float4*)(mr + sh_off + k);
;             const float o0 = v[i].x * rstd * gg.x * (1.0f + scv.x) + shv.x, o1 = v[i].y * rstd * gg.y * (1.0f + scv.y) + shv.y;
;             const float o2 = v[i].z * rstd * gg.z * (1.0f + scv.z) + shv.z, o3 = v[i].w * rstd * gg.w * (1.0f + scv.w) + shv.w;
;             uint2 w; w.x = pk2(o0, o1); w.y = pk2(o2, o3);
;             *(uint2*)(A + (size_t)row * 1024 + k) = w;
.Lfz_pass:
	s_sub_i32 s101, s63, 0x80
	s_lshl_b32 s101, s101, 1
	s_add_i32 s101, s101, s97
	s_lshl_b32 s101, s101, 3
	v_lshrrev_b32_e32 v204, 6, v253
	v_add_u32_e32 v153, s101, v204
	v_lshrrev_b32_e32 v148, 7, v153
	v_lshlrev_b32_e32 v146, 4, v153
	v_lshl_add_u32 v144, v146, 12, v241
	v_lshlrev_b32_e32 v146, 11, v146
	v_lshl_add_u32 v146, v240, 3, v146
	v_mul_u32_u24_e32 v148, 0x6000, v148
	v_add_u32_e32 v148, v148, v241
	global_load_dwordx4 v[80:83], v144, s[46:47] nt
	global_load_dwordx4 v[84:87], v144, s[46:47] offset:1024 nt
	global_load_dwordx4 v[88:91], v144, s[46:47] offset:2048 nt
	global_load_dwordx4 v[92:95], v144, s[46:47] offset:3072 nt
	v_add_u32_e32 v144, 0x1000, v144
	global_load_dwordx4 v[34:37], v148, s[98:99]
	global_load_dwordx4 v[38:41], v148, s[98:99] offset:1024
	global_load_dwordx4 v[42:45], v148, s[98:99] offset:2048
	global_load_dwordx4 v[46:49], v148, s[98:99] offset:3072
	global_load_dwordx4 v[224:227], v148, s[50:51]
	global_load_dwordx4 v[228:231], v148, s[50:51] offset:1024
	global_load_dwordx4 v[232:235], v148, s[50:51] offset:2048
	global_load_dwordx4 v[236:239], v148, s[50:51] offset:3072
	global_load_dwordx4 v[188:191], v241, s[48:49]
	global_load_dwordx4 v[192:195], v241, s[48:49] offset:1024
	global_load_dwordx4 v[196:199], v241, s[48:49] offset:2048
	global_load_dwordx4 v[200:203], v241, s[48:49] offset:3072
	global_load_dwordx4 v[96:99], v144, s[46:47] nt
	global_load_dwordx4 v[100:103], v144, s[46:47] offset:1024 nt
	global_load_dwordx4 v[104:107], v144, s[46:47] offset:2048 nt
	global_load_dwordx4 v[108:111], v144, s[46:47] offset:3072 nt
	v_add_u32_e32 v144, 0x1000, v144
	global_load_dwordx4 v[112:115], v144, s[46:47] nt
	global_load_dwordx4 v[116:119], v144, s[46:47] offset:1024 nt
	global_load_dwordx4 v[120:123], v144, s[46:47] offset:2048 nt
	global_load_dwordx4 v[124:127], v144, s[46:47] offset:3072 nt
	v_add_u32_e32 v144, 0x1000, v144
	global_load_dwordx4 v[128:131], v144, s[46:47] nt
	global_load_dwordx4 v[132:135], v144, s[46:47] offset:1024 nt
	global_load_dwordx4 v[136:139], v144, s[46:47] offset:2048 nt
	global_load_dwordx4 v[140:143], v144, s[46:47] offset:3072 nt
	v_add_u32_e32 v144, 0x1000, v144
	global_load_dwordx4 v[156:159], v144, s[46:47] nt
	global_load_dwordx4 v[160:163], v144, s[46:47] offset:1024 nt
	global_load_dwordx4 v[164:167], v144, s[46:47] offset:2048 nt
	global_load_dwordx4 v[168:171], v144, s[46:47] offset:3072 nt
	v_add_u32_e32 v144, 0x1000, v144
	global_load_dwordx4 v[172:175], v144, s[46:47] nt
	global_load_dwordx4 v[176:179], v144, s[46:47] offset:1024 nt
	global_load_dwordx4 v[180:183], v144, s[46:47] offset:2048 nt
	global_load_dwordx4 v[184:187], v144, s[46:47] offset:3072 nt
	v_add_u32_e32 v144, 0x1000, v144
	s_waitcnt vmcnt(32)
	v_pk_mul_f32 v[242:243], v[80:81], v[80:81]
	v_pk_mul_f32 v[244:245], v[84:85], v[84:85]
	v_pk_mul_f32 v[246:247], v[82:83], v[82:83]
	v_pk_mul_f32 v[248:249], v[86:87], v[86:87]
	v_add_f32_e32 v204, v245, v244
	v_add_f32_e32 v205, v243, v242
	v_add_f32_e32 v204, v248, v204
	v_add_f32_e32 v205, v246, v205
	v_add_f32_e32 v204, v249, v204
	v_add_f32_e32 v205, v247, v205
	v_pk_mul_f32 v[242:243], v[88:89], v[88:89]
	v_pk_mul_f32 v[244:245], v[92:93], v[92:93]
	v_pk_mul_f32 v[246:247], v[90:91], v[90:91]
	v_pk_mul_f32 v[248:249], v[94:95], v[94:95]
	v_add_f32_e32 v206, v243, v242
	v_add_f32_e32 v207, v245, v244
	v_add_f32_e32 v206, v246, v206
	v_add_f32_e32 v207, v248, v207
	v_add_f32_e32 v206, v247, v206
	v_add_f32_e32 v207, v249, v207
	v_add_f32_e32 v204, v205, v204
	v_add_f32_e32 v204, v204, v206
	v_add_f32_e32 v204, v204, v207
	ds_swizzle_b32 v205, v204 offset:swizzle(SWAP,1)
	s_waitcnt lgkmcnt(0)
	v_add_f32_e32 v204, v204, v205
	ds_swizzle_b32 v205, v204 offset:swizzle(SWAP,2)
	s_waitcnt lgkmcnt(0)
	v_add_f32_e32 v204, v204, v205
	ds_swizzle_b32 v205, v204 offset:swizzle(SWAP,4)
	s_waitcnt lgkmcnt(0)
	v_add_f32_e32 v204, v204, v205
	ds_swizzle_b32 v205, v204 offset:swizzle(SWAP,8)
	s_waitcnt lgkmcnt(0)
	v_add_f32_e32 v204, v204, v205
	ds_swizzle_b32 v205, v204 offset:swizzle(SWAP,16)
	s_waitcnt lgkmcnt(0)
	v_add_f32_e32 v204, v204, v205
	v_mov_b32_e32 v205, v204
	s_nop 1
	v_permlane32_swap_b32_e32 v204, v205
	v_add_f32_e32 v204, v204, v205
	v_mov_b32_e32 v205, 0x358637bd
	v_fmamk_f32 v204, v204, 0x3a800000, v205
	v_rsq_f32_e32 v204, v204
	s_nop 0
	s_waitcnt vmcnt(20)
	v_pk_add_f32 v[34:35], v[34:35], 1.0 op_sel_hi:[1,0]
	v_pk_add_f32 v[36:37], v[36:37], 1.0 op_sel_hi:[1,0]
	v_pk_add_f32 v[38:39], v[38:39], 1.0 op_sel_hi:[1,0]
	v_pk_add_f32 v[40:41], v[40:41], 1.0 op_sel_hi:[1,0]
	v_pk_add_f32 v[42:43], v[42:43], 1.0 op_sel_hi:[1,0]
	v_pk_add_f32 v[44:45], v[44:45], 1.0 op_sel_hi:[1,0]
	v_pk_add_f32 v[46:47], v[46:47], 1.0 op_sel_hi:[1,0]
	v_pk_add_f32 v[48:49], v[48:49], 1.0 op_sel_hi:[1,0]
	v_pk_mul_f32 v[80:81], v[80:81], v[204:205] op_sel_hi:[1,0]
	v_pk_mul_f32 v[82:83], v[82:83], v[204:205] op_sel_hi:[1,0]
	v_pk_mul_f32 v[80:81], v[188:189], v[80:81]
	v_pk_mul_f32 v[82:83], v[190:191], v[82:83]
	v_pk_fma_f32 v[80:81], v[34:35], v[80:81], v[224:225]
	v_pk_fma_f32 v[82:83], v[36:37], v[82:83], v[226:227]
	v_cvt_pk_bf16_f32 v80, v80, v81
	v_cvt_pk_bf16_f32 v81, v82, v83
	global_store_dwordx2 v146, v[80:81], s[66:67]
	v_pk_mul_f32 v[84:85], v[84:85], v[204:205] op_sel_hi:[1,0]
	v_pk_mul_f32 v[86:87], v[86:87], v[204:205] op_sel_hi:[1,0]
	v_pk_mul_f32 v[84:85], v[192:193], v[84:85]
	v_pk_mul_f32 v[86:87], v[194:195], v[86:87]
	v_pk_fma_f32 v[84:85], v[38:39], v[84:85], v[228:229]
	v_pk_fma_f32 v[86:87], v[40:41], v[86:87], v[230:231]
	v_cvt_pk_bf16_f32 v84, v84, v85
	v_cvt_pk_bf16_f32 v85, v86, v87
	global_store_dwordx2 v146, v[84:85], s[66:67] offset:512
	v_pk_mul_f32 v[88:89], v[88:89], v[204:205] op_sel_hi:[1,0]
	v_pk_mul_f32 v[90:91], v[90:91], v[204:205] op_sel_hi:[1,0]
	v_pk_mul_f32 v[88:89], v[196:197], v[88:89]
	v_pk_mul_f32 v[90:91], v[198:199], v[90:91]
	v_pk_fma_f32 v[88:89], v[42:43], v[88:89], v[232:233]
	v_pk_fma_f32 v[90:91], v[44:45], v[90:91], v[234:235]
	v_cvt_pk_bf16_f32 v88, v88, v89
	v_cvt_pk_bf16_f32 v89, v90, v91
	global_store_dwordx2 v146, v[88:89], s[66:67] offset:1024
	v_pk_mul_f32 v[92:93], v[92:93], v[204:205] op_sel_hi:[1,0]
	v_pk_mul_f32 v[94:95], v[94:95], v[204:205] op_sel_hi:[1,0]
	v_pk_mul_f32 v[92:93], v[200:201], v[92:93]
	v_pk_mul_f32 v[94:95], v[202:203], v[94:95]
	v_pk_fma_f32 v[92:93], v[46:47], v[92:93], v[236:237]
	v_pk_fma_f32 v[94:95], v[48:49], v[94:95], v[238:239]
	v_cvt_pk_bf16_f32 v92, v92, v93
	v_cvt_pk_bf16_f32 v93, v94, v95
	global_store_dwordx2 v146, v[92:93], s[66:67] offset:1536
	v_add_u32_e32 v146, 0x800, v146
	global_load_dwordx4 v[80:83], v144, s[46:47] nt
	global_load_dwordx4 v[84:87], v144, s[46:47] offset:1024 nt
	global_load_dwordx4 v[88:91], v144, s[46:47] offset:2048 nt
	global_load_dwordx4 v[92:95], v144, s[46:47] offset:3072 nt
	v_add_u32_e32 v144, 0x1000, v144
	s_waitcnt vmcnt(24)
; __device__ __forceinline__ unsigned pk2(float lo, float hi) { const g_f32x2 f = {lo, hi}; return __builtin_bit_cast(unsigned, __builtin_convertvector(f, g_bf16x2)); }
; __device__ __forceinline__ void p_norm(const float* hlat, const float* hctx, const float* g, const float* modl, int sh_off, int sc_off, bf16_t* A, int M,
;                                        const float* part, const float* cgate, float* hcout) {
;     ...
;             ss += v[i].x * v[i].x + v[i].y * v[i].y + v[i].z * v[i].z + v[i].w * v[i].w; }
;         ss = wave_sum(ss);
;         const float rstd = rsqrtf(ss * (1.0f / 1024.0f) + EPS);
;         const float* mr = modl + (size_t)r * 6144;
; #pragma unroll
;         for (int i = 0; i < 4; ++i) {
;             const int k = i * 256 + lane * 4;
;             const float4 gg = *(const float4*)(g + k), scv = *(const float4*)(mr + sc_off + k), shv = *(const float4*)(mr + sh_off + k);
;             const float o0 = v[i].x * rstd * gg.x * (1.0f + scv.x) + shv.x, o1 = v[i].y * rstd * gg.y * (1.0f + scv.y) + shv.y;
;             const float o2 = v[i].z * rstd * gg.z * (1.0f + scv.z) + shv.z, o3 = v[i].w * rstd * gg.w * (1.0f + scv.w) + shv.w;
;             uint2 w; w.x = pk2(o0, o1); w.y = pk2(o2, o3);
;             *(uint2*)(A + (size_t)row * 1024 + k) = w;
	v_pk_mul_f32 v[242:243], v[96:97], v[96:97]
	v_pk_mul_f32 v[244:245], v[100:101], v[100:101]
	v_pk_mul_f32 v[246:247], v[98:99], v[98:99]
	v_pk_mul_f32 v[248:249], v[102:103], v[102:103]
	v_add_f32_e32 v204, v245, v244
	v_add_f32_e32 v205, v243, v242
	v_add_f32_e32 v204, v248, v204
	v_add_f32_e32 v205, v246, v205
	v_add_f32_e32 v204, v249, v204
	v_add_f32_e32 v205, v247, v205
	v_pk_mul_f32 v[242:243], v[104:105], v[104:105]
	v_pk_mul_f32 v[244:245], v[108:109], v[108:109]
	v_pk_mul_f32 v[246:247], v[106:107], v[106:107]
	v_pk_mul_f32 v[248:249], v[110:111], v[110:111]
	v_add_f32_e32 v206, v243, v242
	v_add_f32_e32 v207, v245, v244
	v_add_f32_e32 v206, v246, v206
	v_add_f32_e32 v207, v248, v207
	v_add_f32_e32 v206, v247, v206
	v_add_f32_e32 v207, v249, v207
	v_add_f32_e32 v204, v205, v204
	v_add_f32_e32 v204, v204, v206
	v_add_f32_e32 v204, v204, v207
	ds_swizzle_b32 v205, v204 offset:swizzle(SWAP,1)
	s_waitcnt lgkmcnt(0)
	v_add_f32_e32 v204, v204, v205
	ds_swizzle_b32 v205, v204 offset:swizzle(SWAP,2)
	s_waitcnt lgkmcnt(0)
	v_add_f32_e32 v204, v204, v205
	ds_swizzle_b32 v205, v204 offset:swizzle(SWAP,4)
	s_waitcnt lgkmcnt(0)
	v_add_f32_e32 v204, v204, v205
	ds_swizzle_b32 v205, v204 offset:swizzle(SWAP,8)
	s_waitcnt lgkmcnt(0)
	v_add_f32_e32 v204, v204, v205
	ds_swizzle_b32 v205, v204 offset:swizzle(SWAP,16)
	s_waitcnt lgkmcnt(0)
	v_add_f32_e32 v204, v204, v205
	v_mov_b32_e32 v205, v204
	s_nop 1
	v_permlane32_swap_b32_e32 v204, v205
	v_add_f32_e32 v204, v204, v205
	v_mov_b32_e32 v205, 0x358637bd
	v_fmamk_f32 v204, v204, 0x3a800000, v205
	v_rsq_f32_e32 v204, v204
	s_nop 0
	v_pk_mul_f32 v[96:97], v[96:97], v[204:205] op_sel_hi:[1,0]
	v_pk_mul_f32 v[98:99], v[98:99], v[204:205] op_sel_hi:[1,0]
	v_pk_mul_f32 v[96:97], v[188:189], v[96:97]
	v_pk_mul_f32 v[98:99], v[190:191], v[98:99]
	v_pk_fma_f32 v[96:97], v[34:35], v[96:97], v[224:225]
	v_pk_fma_f32 v[98:99], v[36:37], v[98:99], v[226:227]
	v_cvt_pk_bf16_f32 v96, v96, v97
	v_cvt_pk_bf16_f32 v97, v98, v99
	global_store_dwordx2 v146, v[96:97], s[66:67]
	v_pk_mul_f32 v[100:101], v[100:101], v[204:205] op_sel_hi:[1,0]
	v_pk_mul_f32 v[102:103], v[102:103], v[204:205] op_sel_hi:[1,0]
	v_pk_mul_f32 v[100:101], v[192:193], v[100:101]
	v_pk_mul_f32 v[102:103], v[194:195], v[102:103]
	v_pk_fma_f32 v[100:101], v[38:39], v[100:101], v[228:229]
	v_pk_fma_f32 v[102:103], v[40:41], v[102:103], v[230:231]
	v_cvt_pk_bf16_f32 v100, v100, v101
	v_cvt_pk_bf16_f32 v101, v102, v103
	global_store_dwordx2 v146, v[100:101], s[66:67] offset:512
	v_pk_mul_f32 v[104:105], v[104:105], v[204:205] op_sel_hi:[1,0]
	v_pk_mul_f32 v[106:107], v[106:107], v[204:205] op_sel_hi:[1,0]
	v_pk_mul_f32 v[104:105], v[196:197], v[104:105]
	v_pk_mul_f32 v[106:107], v[198:199], v[106:107]
	v_pk_fma_f32 v[104:105], v[42:43], v[104:105], v[232:233]
	v_pk_fma_f32 v[106:107], v[44:45], v[106:107], v[234:235]
	v_cvt_pk_bf16_f32 v104, v104, v105
	v_cvt_pk_bf16_f32 v105, v106, v107
	global_store_dwordx2 v146, v[104:105], s[66:67] offset:1024
	v_pk_mul_f32 v[108:109], v[108:109], v[204:205] op_sel_hi:[1,0]
	v_pk_mul_f32 v[110:111], v[110:111], v[204:205] op_sel_hi:[1,0]
	v_pk_mul_f32 v[108:109], v[200:201], v[108:109]
	v_pk_mul_f32 v[110:111], v[202:203], v[110:111]
	v_pk_fma_f32 v[108:109], v[46:47], v[108:109], v[236:237]
	v_pk_fma_f32 v[110:111], v[48:49], v[110:111], v[238:239]
	v_cvt_pk_bf16_f32 v108, v108, v109
	v_cvt_pk_bf16_f32 v109, v110, v111
	global_store_dwordx2 v146, v[108:109], s[66:67] offset:1536
	v_add_u32_e32 v146, 0x800, v146
	global_load_dwordx4 v[96:99], v144, s[46:47] nt
	global_load_dwordx4 v[100:103], v144, s[46:47] offset:1024 nt
	global_load_dwordx4 v[104:107], v144, s[46:47] offset:2048 nt
	global_load_dwordx4 v[108:111], v144, s[46:47] offset:3072 nt
	v_add_u32_e32 v144, 0x1000, v144
	s_waitcnt vmcnt(28)
	v_pk_mul_f32 v[242:243], v[112:113], v[112:113]
	v_pk_mul_f32 v[244:245], v[116:117], v[116:117]
	v_pk_mul_f32 v[246:247], v[114:115], v[114:115]
	v_pk_mul_f32 v[248:249], v[118:119], v[118:119]
	v_add_f32_e32 v204, v245, v244
	v_add_f32_e32 v205, v243, v242
	v_add_f32_e32 v204, v248, v204
	v_add_f32_e32 v205, v246, v205
	v_add_f32_e32 v204, v249, v204
	v_add_f32_e32 v205, v247, v205
	v_pk_mul_f32 v[242:243], v[120:121], v[120:121]
	v_pk_mul_f32 v[244:245], v[124:125], v[124:125]
	v_pk_mul_f32 v[246:247], v[122:123], v[122:123]
	v_pk_mul_f32 v[248:249], v[126:127], v[126:127]
	v_add_f32_e32 v206, v243, v242
	v_add_f32_e32 v207, v245, v244
	v_add_f32_e32 v206, v246, v206
	v_add_f32_e32 v207, v248, v207
	v_add_f32_e32 v206, v247, v206
	v_add_f32_e32 v207, v249, v207
	v_add_f32_e32 v204, v205, v204
	v_add_f32_e32 v204, v204, v206
	v_add_f32_e32 v204, v204, v207
	ds_swizzle_b32 v205, v204 offset:swizzle(SWAP,1)
	s_waitcnt lgkmcnt(0)
	v_add_f32_e32 v204, v204, v205
	ds_swizzle_b32 v205, v204 offset:swizzle(SWAP,2)
	s_waitcnt lgkmcnt(0)
	v_add_f32_e32 v204, v204, v205
	ds_swizzle_b32 v205, v204 offset:swizzle(SWAP,4)
	s_waitcnt lgkmcnt(0)
	v_add_f32_e32 v204, v204, v205
	ds_swizzle_b32 v205, v204 offset:swizzle(SWAP,8)
	s_waitcnt lgkmcnt(0)
	v_add_f32_e32 v204, v204, v205
	ds_swizzle_b32 v205, v204 offset:swizzle(SWAP,16)
	s_waitcnt lgkmcnt(0)
; __device__ __forceinline__ unsigned pk2(float lo, float hi) { const g_f32x2 f = {lo, hi}; return __builtin_bit_cast(unsigned, __builtin_convertvector(f, g_bf16x2)); }
; __device__ __forceinline__ void p_norm(const float* hlat, const float* hctx, const float* g, const float* modl, int sh_off, int sc_off, bf16_t* A, int M,
;                                        const float* part, const float* cgate, float* hcout) {
;     ...
;             ss += v[i].x * v[i].x + v[i].y * v[i].y + v[i].z * v[i].z + v[i].w * v[i].w; }
;         ss = wave_sum(ss);
;         const float rstd = rsqrtf(ss * (1.0f / 1024.0f) + EPS);
;         const float* mr = modl + (size_t)r * 6144;
; #pragma unroll
;         for (int i = 0; i < 4; ++i) {
;             const int k = i * 256 + lane * 4;
;             const float4 gg = *(const float4*)(g + k), scv = *(const float4*)(mr + sc_off + k), shv = *(const float4*)(mr + sh_off + k);
;             const float o0 = v[i].x * rstd * gg.x * (1.0f + scv.x) + shv.x, o1 = v[i].y * rstd * gg.y * (1.0f + scv.y) + shv.y;
;             const float o2 = v[i].z * rstd * gg.z * (1.0f + scv.z) + shv.z, o3 = v[i].w * rstd * gg.w * (1.0f + scv.w) + shv.w;
;             uint2 w; w.x = pk2(o0, o1); w.y = pk2(o2, o3);
;             *(uint2*)(A + (size_t)row * 1024 + k) = w;
	v_add_f32_e32 v204, v204, v205
	v_mov_b32_e32 v205, v204
	s_nop 1
	v_permlane32_swap_b32_e32 v204, v205
	v_add_f32_e32 v204, v204, v205
	v_mov_b32_e32 v205, 0x358637bd
	v_fmamk_f32 v204, v204, 0x3a800000, v205
	v_rsq_f32_e32 v204, v204
	s_nop 0
	v_pk_mul_f32 v[112:113], v[112:113], v[204:205] op_sel_hi:[1,0]
	v_pk_mul_f32 v[114:115], v[114:115], v[204:205] op_sel_hi:[1,0]
	v_pk_mul_f32 v[112:113], v[188:189], v[112:113]
	v_pk_mul_f32 v[114:115], v[190:191], v[114:115]
	v_pk_fma_f32 v[112:113], v[34:35], v[112:113], v[224:225]
	v_pk_fma_f32 v[114:115], v[36:37], v[114:115], v[226:227]
	v_cvt_pk_bf16_f32 v112, v112, v113
	v_cvt_pk_bf16_f32 v113, v114, v115
	global_store_dwordx2 v146, v[112:113], s[66:67]
	v_pk_mul_f32 v[116:117], v[116:117], v[204:205] op_sel_hi:[1,0]
	v_pk_mul_f32 v[118:119], v[118:119], v[204:205] op_sel_hi:[1,0]
	v_pk_mul_f32 v[116:117], v[192:193], v[116:117]
	v_pk_mul_f32 v[118:119], v[194:195], v[118:119]
	v_pk_fma_f32 v[116:117], v[38:39], v[116:117], v[228:229]
	v_pk_fma_f32 v[118:119], v[40:41], v[118:119], v[230:231]
	v_cvt_pk_bf16_f32 v116, v116, v117
	v_cvt_pk_bf16_f32 v117, v118, v119
	global_store_dwordx2 v146, v[116:117], s[66:67] offset:512
	v_pk_mul_f32 v[120:121], v[120:121], v[204:205] op_sel_hi:[1,0]
	v_pk_mul_f32 v[122:123], v[122:123], v[204:205] op_sel_hi:[1,0]
	v_pk_mul_f32 v[120:121], v[196:197], v[120:121]
	v_pk_mul_f32 v[122:123], v[198:199], v[122:123]
	v_pk_fma_f32 v[120:121], v[42:43], v[120:121], v[232:233]
	v_pk_fma_f32 v[122:123], v[44:45], v[122:123], v[234:235]
	v_cvt_pk_bf16_f32 v120, v120, v121
	v_cvt_pk_bf16_f32 v121, v122, v123
	global_store_dwordx2 v146, v[120:121], s[66:67] offset:1024
	v_pk_mul_f32 v[124:125], v[124:125], v[204:205] op_sel_hi:[1,0]
	v_pk_mul_f32 v[126:127], v[126:127], v[204:205] op_sel_hi:[1,0]
	v_pk_mul_f32 v[124:125], v[200:201], v[124:125]
	v_pk_mul_f32 v[126:127], v[202:203], v[126:127]
	v_pk_fma_f32 v[124:125], v[46:47], v[124:125], v[236:237]
	v_pk_fma_f32 v[126:127], v[48:49], v[126:127], v[238:239]
	v_cvt_pk_bf16_f32 v124, v124, v125
	v_cvt_pk_bf16_f32 v125, v126, v127
	global_store_dwordx2 v146, v[124:125], s[66:67] offset:1536
	v_add_u32_e32 v146, 0x800, v146
	global_load_dwordx4 v[112:115], v144, s[46:47] nt
	global_load_dwordx4 v[116:119], v144, s[46:47] offset:1024 nt
	global_load_dwordx4 v[120:123], v144, s[46:47] offset:2048 nt
	global_load_dwordx4 v[124:127], v144, s[46:47] offset:3072 nt
	v_add_u32_e32 v144, 0x1000, v144
	s_waitcnt vmcnt(32)
	v_pk_mul_f32 v[242:243], v[128:129], v[128:129]
	v_pk_mul_f32 v[244:245], v[132:133], v[132:133]
	v_pk_mul_f32 v[246:247], v[130:131], v[130:131]
	v_pk_mul_f32 v[248:249], v[134:135], v[134:135]
	v_add_f32_e32 v204, v245, v244
	v_add_f32_e32 v205, v243, v242
	v_add_f32_e32 v204, v248, v204
	v_add_f32_e32 v205, v246, v205
	v_add_f32_e32 v204, v249, v204
	v_add_f32_e32 v205, v247, v205
	v_pk_mul_f32 v[242:243], v[136:137], v[136:137]
	v_pk_mul_f32 v[244:245], v[140:141], v[140:141]
	v_pk_mul_f32 v[246:247], v[138:139], v[138:139]
	v_pk_mul_f32 v[248:249], v[142:143], v[142:143]
	v_add_f32_e32 v206, v243, v242
	v_add_f32_e32 v207, v245, v244
	v_add_f32_e32 v206, v246, v206
	v_add_f32_e32 v207, v248, v207
	v_add_f32_e32 v206, v247, v206
	v_add_f32_e32 v207, v249, v207
	v_add_f32_e32 v204, v205, v204
	v_add_f32_e32 v204, v204, v206
	v_add_f32_e32 v204, v204, v207
	ds_swizzle_b32 v205, v204 offset:swizzle(SWAP,1)
	s_waitcnt lgkmcnt(0)
	v_add_f32_e32 v204, v204, v205
	ds_swizzle_b32 v205, v204 offset:swizzle(SWAP,2)
	s_waitcnt lgkmcnt(0)
	v_add_f32_e32 v204, v204, v205
	ds_swizzle_b32 v205, v204 offset:swizzle(SWAP,4)
	s_waitcnt lgkmcnt(0)
	v_add_f32_e32 v204, v204, v205
	ds_swizzle_b32 v205, v204 offset:swizzle(SWAP,8)
	s_waitcnt lgkmcnt(0)
	v_add_f32_e32 v204, v204, v205
	ds_swizzle_b32 v205, v204 offset:swizzle(SWAP,16)
	s_waitcnt lgkmcnt(0)
	v_add_f32_e32 v204, v204, v205
	v_mov_b32_e32 v205, v204
	s_nop 1
	v_permlane32_swap_b32_e32 v204, v205
	v_add_f32_e32 v204, v204, v205
	v_mov_b32_e32 v205, 0x358637bd
	v_fmamk_f32 v204, v204, 0x3a800000, v205
	v_rsq_f32_e32 v204, v204
	s_nop 0
	v_pk_mul_f32 v[128:129], v[128:129], v[204:205] op_sel_hi:[1,0]
	v_pk_mul_f32 v[130:131], v[130:131], v[204:205] op_sel_hi:[1,0]
	v_pk_mul_f32 v[128:129], v[188:189], v[128:129]
	v_pk_mul_f32 v[130:131], v[190:191], v[130:131]
	v_pk_fma_f32 v[128:129], v[34:35], v[128:129], v[224:225]
	v_pk_fma_f32 v[130:131], v[36:37], v[130:131], v[226:227]
	v_cvt_pk_bf16_f32 v128, v128, v129
	v_cvt_pk_bf16_f32 v129, v130, v131
	global_store_dwordx2 v146, v[128:129], s[66:67]
	v_pk_mul_f32 v[132:133], v[132:133], v[204:205] op_sel_hi:[1,0]
	v_pk_mul_f32 v[134:135], v[134:135], v[204:205] op_sel_hi:[1,0]
	v_pk_mul_f32 v[132:133], v[192:193], v[132:133]
	v_pk_mul_f32 v[134:135], v[194:195], v[134:135]
	v_pk_fma_f32 v[132:133], v[38:39], v[132:133], v[228:229]
	v_pk_fma_f32 v[134:135], v[40:41], v[134:135], v[230:231]
	v_cvt_pk_bf16_f32 v132, v132, v133
	v_cvt_pk_bf16_f32 v133, v134, v135
	global_store_dwordx2 v146, v[132:133], s[66:67] offset:512
	v_pk_mul_f32 v[136:137], v[136:137], v[204:205] op_sel_hi:[1,0]
	v_pk_mul_f32 v[138:139], v[138:139], v[204:205] op_sel_hi:[1,0]
	v_pk_mul_f32 v[136:137], v[196:197], v[136:137]
	v_pk_mul_f32 v[138:139], v[198:199], v[138:139]
	v_pk_fma_f32 v[136:137], v[42:43], v[136:137], v[232:233]
	v_pk_fma_f32 v[138:139], v[44:45], v[138:139], v[234:235]
	v_cvt_pk_bf16_f32 v136, v136, v137
	v_cvt_pk_bf16_f32 v137, v138, v139
	global_store_dwordx2 v146, v[136:137], s[66:67] offset:1024
	v_pk_mul_f32 v[140:141], v[140:141], v[204:205] op_sel_hi:[1,0]
	v_pk_mul_f32 v[142:143], v[142:143], v[204:205] op_sel_hi:[1,0]
	v_pk_mul_f32 v[140:141], v[200:201], v[140:141]
	v_pk_mul_f32 v[142:143], v[202:203], v[142:143]
	v_pk_fma_f32 v[140:141], v[46:47], v[140:141], v[236:237]
	v_pk_fma_f32 v[142:143], v[48:49], v[142:143], v[238:239]
	v_cvt_pk_bf16_f32 v140, v140, v141
	v_cvt_pk_bf16_f32 v141, v142, v143
	global_store_dwordx2 v146, v[140:141], s[66:67] offset:1536
	v_add_u32_e32 v146, 0x800, v146
	global_load_dwordx4 v[128:131], v144, s[46:47] nt
	global_load_dwordx4 v[132:135], v144, s[46:47] offset:1024 nt
	global_load_dwordx4 v[136:139], v144, s[46:47] offset:2048 nt
	global_load_dwordx4 v[140:143], v144, s[46:47] offset:3072 nt
	v_add_u32_e32 v144, 0x1000, v144
	s_waitcnt vmcnt(36)
; __device__ __forceinline__ unsigned pk2(float lo, float hi) { const g_f32x2 f = {lo, hi}; return __builtin_bit_cast(unsigned, __builtin_convertvector(f, g_bf16x2)); }
; __device__ __forceinline__ void p_norm(const float* hlat, const float* hctx, const float* g, const float* modl, int sh_off, int sc_off, bf16_t* A, int M,
;                                        const float* part, const float* cgate, float* hcout) {
;     ...
;             ss += v[i].x * v[i].x + v[i].y * v[i].y + v[i].z * v[i].z + v[i].w * v[i].w; }
;         ss = wave_sum(ss);
;         const float rstd = rsqrtf(ss * (1.0f / 1024.0f) + EPS);
;         const float* mr = modl + (size_t)r * 6144;
; #pragma unroll
;         for (int i = 0; i < 4; ++i) {
;             const int k = i * 256 + lane * 4;
;             const float4 gg = *(const float4*)(g + k), scv = *(const float4*)(mr + sc_off + k), shv = *(const float4*)(mr + sh_off + k);
;             const float o0 = v[i].x * rstd * gg.x * (1.0f + scv.x) + shv.x, o1 = v[i].y * rstd * gg.y * (1.0f + scv.y) + shv.y;
;             const float o2 = v[i].z * rstd * gg.z * (1.0f + scv.z) + shv.z, o3 = v[i].w * rstd * gg.w * (1.0f + scv.w) + shv.w;
;             uint2 w; w.x = pk2(o0, o1); w.y = pk2(o2, o3);
;             *(uint2*)(A + (size_t)row * 1024 + k) = w;
	v_pk_mul_f32 v[242:243], v[156:157], v[156:157]
	v_pk_mul_f32 v[244:245], v[160:161], v[160:161]
	v_pk_mul_f32 v[246:247], v[158:159], v[158:159]
	v_pk_mul_f32 v[248:249], v[162:163], v[162:163]
	v_add_f32_e32 v204, v245, v244
	v_add_f32_e32 v205, v243, v242
	v_add_f32_e32 v204, v248, v204
	v_add_f32_e32 v205, v246, v205
	v_add_f32_e32 v204, v249, v204
	v_add_f32_e32 v205, v247, v205
	v_pk_mul_f32 v[242:243], v[164:165], v[164:165]
	v_pk_mul_f32 v[244:245], v[168:169], v[168:169]
	v_pk_mul_f32 v[246:247], v[166:167], v[166:167]
	v_pk_mul_f32 v[248:249], v[170:171], v[170:171]
	v_add_f32_e32 v206, v243, v242
	v_add_f32_e32 v207, v245, v244
	v_add_f32_e32 v206, v246, v206
	v_add_f32_e32 v207, v248, v207
	v_add_f32_e32 v206, v247, v206
	v_add_f32_e32 v207, v249, v207
	v_add_f32_e32 v204, v205, v204
	v_add_f32_e32 v204, v204, v206
	v_add_f32_e32 v204, v204, v207
	ds_swizzle_b32 v205, v204 offset:swizzle(SWAP,1)
	s_waitcnt lgkmcnt(0)
	v_add_f32_e32 v204, v204, v205
	ds_swizzle_b32 v205, v204 offset:swizzle(SWAP,2)
	s_waitcnt lgkmcnt(0)
	v_add_f32_e32 v204, v204, v205
	ds_swizzle_b32 v205, v204 offset:swizzle(SWAP,4)
	s_waitcnt lgkmcnt(0)
	v_add_f32_e32 v204, v204, v205
	ds_swizzle_b32 v205, v204 offset:swizzle(SWAP,8)
	s_waitcnt lgkmcnt(0)
	v_add_f32_e32 v204, v204, v205
	ds_swizzle_b32 v205, v204 offset:swizzle(SWAP,16)
	s_waitcnt lgkmcnt(0)
	v_add_f32_e32 v204, v204, v205
	v_mov_b32_e32 v205, v204
	s_nop 1
	v_permlane32_swap_b32_e32 v204, v205
	v_add_f32_e32 v204, v204, v205
	v_mov_b32_e32 v205, 0x358637bd
	v_fmamk_f32 v204, v204, 0x3a800000, v205
	v_rsq_f32_e32 v204, v204
	s_nop 0
	v_pk_mul_f32 v[156:157], v[156:157], v[204:205] op_sel_hi:[1,0]
	v_pk_mul_f32 v[158:159], v[158:159], v[204:205] op_sel_hi:[1,0]
	v_pk_mul_f32 v[156:157], v[188:189], v[156:157]
	v_pk_mul_f32 v[158:159], v[190:191], v[158:159]
	v_pk_fma_f32 v[156:157], v[34:35], v[156:157], v[224:225]
	v_pk_fma_f32 v[158:159], v[36:37], v[158:159], v[226:227]
	v_cvt_pk_bf16_f32 v156, v156, v157
	v_cvt_pk_bf16_f32 v157, v158, v159
	global_store_dwordx2 v146, v[156:157], s[66:67]
	v_pk_mul_f32 v[160:161], v[160:161], v[204:205] op_sel_hi:[1,0]
	v_pk_mul_f32 v[162:163], v[162:163], v[204:205] op_sel_hi:[1,0]
	v_pk_mul_f32 v[160:161], v[192:193], v[160:161]
	v_pk_mul_f32 v[162:163], v[194:195], v[162:163]
	v_pk_fma_f32 v[160:161], v[38:39], v[160:161], v[228:229]
	v_pk_fma_f32 v[162:163], v[40:41], v[162:163], v[230:231]
	v_cvt_pk_bf16_f32 v160, v160, v161
	v_cvt_pk_bf16_f32 v161, v162, v163
	global_store_dwordx2 v146, v[160:161], s[66:67] offset:512
	v_pk_mul_f32 v[164:165], v[164:165], v[204:205] op_sel_hi:[1,0]
	v_pk_mul_f32 v[166:167], v[166:167], v[204:205] op_sel_hi:[1,0]
	v_pk_mul_f32 v[164:165], v[196:197], v[164:165]
	v_pk_mul_f32 v[166:167], v[198:199], v[166:167]
	v_pk_fma_f32 v[164:165], v[42:43], v[164:165], v[232:233]
	v_pk_fma_f32 v[166:167], v[44:45], v[166:167], v[234:235]
	v_cvt_pk_bf16_f32 v164, v164, v165
	v_cvt_pk_bf16_f32 v165, v166, v167
	global_store_dwordx2 v146, v[164:165], s[66:67] offset:1024
	v_pk_mul_f32 v[168:169], v[168:169], v[204:205] op_sel_hi:[1,0]
	v_pk_mul_f32 v[170:171], v[170:171], v[204:205] op_sel_hi:[1,0]
	v_pk_mul_f32 v[168:169], v[200:201], v[168:169]
	v_pk_mul_f32 v[170:171], v[202:203], v[170:171]
	v_pk_fma_f32 v[168:169], v[46:47], v[168:169], v[236:237]
	v_pk_fma_f32 v[170:171], v[48:49], v[170:171], v[238:239]
	v_cvt_pk_bf16_f32 v168, v168, v169
	v_cvt_pk_bf16_f32 v169, v170, v171
	global_store_dwordx2 v146, v[168:169], s[66:67] offset:1536
	v_add_u32_e32 v146, 0x800, v146
	global_load_dwordx4 v[156:159], v144, s[46:47] nt
	global_load_dwordx4 v[160:163], v144, s[46:47] offset:1024 nt
	global_load_dwordx4 v[164:167], v144, s[46:47] offset:2048 nt
	global_load_dwordx4 v[168:171], v144, s[46:47] offset:3072 nt
	v_add_u32_e32 v144, 0x1000, v144
	s_waitcnt vmcnt(40)
	v_pk_mul_f32 v[242:243], v[172:173], v[172:173]
	v_pk_mul_f32 v[244:245], v[176:177], v[176:177]
	v_pk_mul_f32 v[246:247], v[174:175], v[174:175]
	v_pk_mul_f32 v[248:249], v[178:179], v[178:179]
	v_add_f32_e32 v204, v245, v244
	v_add_f32_e32 v205, v243, v242
	v_add_f32_e32 v204, v248, v204
	v_add_f32_e32 v205, v246, v205
	v_add_f32_e32 v204, v249, v204
	v_add_f32_e32 v205, v247, v205
	v_pk_mul_f32 v[242:243], v[180:181], v[180:181]
	v_pk_mul_f32 v[244:245], v[184:185], v[184:185]
	v_pk_mul_f32 v[246:247], v[182:183], v[182:183]
	v_pk_mul_f32 v[248:249], v[186:187], v[186:187]
	v_add_f32_e32 v206, v243, v242
	v_add_f32_e32 v207, v245, v244
	v_add_f32_e32 v206, v246, v206
	v_add_f32_e32 v207, v248, v207
	v_add_f32_e32 v206, v247, v206
	v_add_f32_e32 v207, v249, v207
	v_add_f32_e32 v204, v205, v204
	v_add_f32_e32 v204, v204, v206
	v_add_f32_e32 v204, v204, v207
	ds_swizzle_b32 v205, v204 offset:swizzle(SWAP,1)
	s_waitcnt lgkmcnt(0)
	v_add_f32_e32 v204, v204, v205
	ds_swizzle_b32 v205, v204 offset:swizzle(SWAP,2)
	s_waitcnt lgkmcnt(0)
	v_add_f32_e32 v204, v204, v205
	ds_swizzle_b32 v205, v204 offset:swizzle(SWAP,4)
	s_waitcnt lgkmcnt(0)
	v_add_f32_e32 v204, v204, v205
	ds_swizzle_b32 v205, v204 offset:swizzle(SWAP,8)
	s_waitcnt lgkmcnt(0)
	v_add_f32_e32 v204, v204, v205
	ds_swizzle_b32 v205, v204 offset:swizzle(SWAP,16)
	s_waitcnt lgkmcnt(0)
; __device__ __forceinline__ unsigned pk2(float lo, float hi) { const g_f32x2 f = {lo, hi}; return __builtin_bit_cast(unsigned, __builtin_convertvector(f, g_bf16x2)); }
; __device__ __forceinline__ void p_norm(const float* hlat, const float* hctx, const float* g, const float* modl, int sh_off, int sc_off, bf16_t* A, int M,
;                                        const float* part, const float* cgate, float* hcout) {
;     ...
;             ss += v[i].x * v[i].x + v[i].y * v[i].y + v[i].z * v[i].z + v[i].w * v[i].w; }
;         ss = wave_sum(ss);
;         const float rstd = rsqrtf(ss * (1.0f / 1024.0f) + EPS);
;         const float* mr = modl + (size_t)r * 6144;
; #pragma unroll
;         for (int i = 0; i < 4; ++i) {
;             const int k = i * 256 + lane * 4;
;             const float4 gg = *(const float4*)(g + k), scv = *(const float4*)(mr + sc_off + k), shv = *(const float4*)(mr + sh_off + k);
;             const float o0 = v[i].x * rstd * gg.x * (1.0f + scv.x) + shv.x, o1 = v[i].y * rstd * gg.y * (1.0f + scv.y) + shv.y;
;             const float o2 = v[i].z * rstd * gg.z * (1.0f + scv.z) + shv.z, o3 = v[i].w * rstd * gg.w * (1.0f + scv.w) + shv.w;
;             uint2 w; w.x = pk2(o0, o1); w.y = pk2(o2, o3);
;             *(uint2*)(A + (size_t)row * 1024 + k) = w;
	v_add_f32_e32 v204, v204, v205
	v_mov_b32_e32 v205, v204
	s_nop 1
	v_permlane32_swap_b32_e32 v204, v205
	v_add_f32_e32 v204, v204, v205
	v_mov_b32_e32 v205, 0x358637bd
	v_fmamk_f32 v204, v204, 0x3a800000, v205
	v_rsq_f32_e32 v204, v204
	s_nop 0
	v_pk_mul_f32 v[172:173], v[172:173], v[204:205] op_sel_hi:[1,0]
	v_pk_mul_f32 v[174:175], v[174:175], v[204:205] op_sel_hi:[1,0]
	v_pk_mul_f32 v[172:173], v[188:189], v[172:173]
	v_pk_mul_f32 v[174:175], v[190:191], v[174:175]
	v_pk_fma_f32 v[172:173], v[34:35], v[172:173], v[224:225]
	v_pk_fma_f32 v[174:175], v[36:37], v[174:175], v[226:227]
	v_cvt_pk_bf16_f32 v172, v172, v173
	v_cvt_pk_bf16_f32 v173, v174, v175
	global_store_dwordx2 v146, v[172:173], s[66:67]
	v_pk_mul_f32 v[176:177], v[176:177], v[204:205] op_sel_hi:[1,0]
	v_pk_mul_f32 v[178:179], v[178:179], v[204:205] op_sel_hi:[1,0]
	v_pk_mul_f32 v[176:177], v[192:193], v[176:177]
	v_pk_mul_f32 v[178:179], v[194:195], v[178:179]
	v_pk_fma_f32 v[176:177], v[38:39], v[176:177], v[228:229]
	v_pk_fma_f32 v[178:179], v[40:41], v[178:179], v[230:231]
	v_cvt_pk_bf16_f32 v176, v176, v177
	v_cvt_pk_bf16_f32 v177, v178, v179
	global_store_dwordx2 v146, v[176:177], s[66:67] offset:512
	v_pk_mul_f32 v[180:181], v[180:181], v[204:205] op_sel_hi:[1,0]
	v_pk_mul_f32 v[182:183], v[182:183], v[204:205] op_sel_hi:[1,0]
	v_pk_mul_f32 v[180:181], v[196:197], v[180:181]
	v_pk_mul_f32 v[182:183], v[198:199], v[182:183]
	v_pk_fma_f32 v[180:181], v[42:43], v[180:181], v[232:233]
	v_pk_fma_f32 v[182:183], v[44:45], v[182:183], v[234:235]
	v_cvt_pk_bf16_f32 v180, v180, v181
	v_cvt_pk_bf16_f32 v181, v182, v183
	global_store_dwordx2 v146, v[180:181], s[66:67] offset:1024
	v_pk_mul_f32 v[184:185], v[184:185], v[204:205] op_sel_hi:[1,0]
	v_pk_mul_f32 v[186:187], v[186:187], v[204:205] op_sel_hi:[1,0]
	v_pk_mul_f32 v[184:185], v[200:201], v[184:185]
	v_pk_mul_f32 v[186:187], v[202:203], v[186:187]
	v_pk_fma_f32 v[184:185], v[46:47], v[184:185], v[236:237]
	v_pk_fma_f32 v[186:187], v[48:49], v[186:187], v[238:239]
	v_cvt_pk_bf16_f32 v184, v184, v185
	v_cvt_pk_bf16_f32 v185, v186, v187
	global_store_dwordx2 v146, v[184:185], s[66:67] offset:1536
	v_add_u32_e32 v146, 0x800, v146
	global_load_dwordx4 v[172:175], v144, s[46:47] nt
	global_load_dwordx4 v[176:179], v144, s[46:47] offset:1024 nt
	global_load_dwordx4 v[180:183], v144, s[46:47] offset:2048 nt
	global_load_dwordx4 v[184:187], v144, s[46:47] offset:3072 nt
	v_add_u32_e32 v144, 0x1000, v144
	s_waitcnt vmcnt(40)
	v_pk_mul_f32 v[242:243], v[80:81], v[80:81]
	v_pk_mul_f32 v[244:245], v[84:85], v[84:85]
	v_pk_mul_f32 v[246:247], v[82:83], v[82:83]
	v_pk_mul_f32 v[248:249], v[86:87], v[86:87]
	v_add_f32_e32 v204, v245, v244
	v_add_f32_e32 v205, v243, v242
	v_add_f32_e32 v204, v248, v204
	v_add_f32_e32 v205, v246, v205
	v_add_f32_e32 v204, v249, v204
	v_add_f32_e32 v205, v247, v205
	v_pk_mul_f32 v[242:243], v[88:89], v[88:89]
	v_pk_mul_f32 v[244:245], v[92:93], v[92:93]
	v_pk_mul_f32 v[246:247], v[90:91], v[90:91]
	v_pk_mul_f32 v[248:249], v[94:95], v[94:95]
	v_add_f32_e32 v206, v243, v242
	v_add_f32_e32 v207, v245, v244
	v_add_f32_e32 v206, v246, v206
	v_add_f32_e32 v207, v248, v207
	v_add_f32_e32 v206, v247, v206
	v_add_f32_e32 v207, v249, v207
	v_add_f32_e32 v204, v205, v204
	v_add_f32_e32 v204, v204, v206
	v_add_f32_e32 v204, v204, v207
	ds_swizzle_b32 v205, v204 offset:swizzle(SWAP,1)
	s_waitcnt lgkmcnt(0)
	v_add_f32_e32 v204, v204, v205
	ds_swizzle_b32 v205, v204 offset:swizzle(SWAP,2)
	s_waitcnt lgkmcnt(0)
	v_add_f32_e32 v204, v204, v205
	ds_swizzle_b32 v205, v204 offset:swizzle(SWAP,4)
	s_waitcnt lgkmcnt(0)
	v_add_f32_e32 v204, v204, v205
	ds_swizzle_b32 v205, v204 offset:swizzle(SWAP,8)
	s_waitcnt lgkmcnt(0)
	v_add_f32_e32 v204, v204, v205
	ds_swizzle_b32 v205, v204 offset:swizzle(SWAP,16)
	s_waitcnt lgkmcnt(0)
	v_add_f32_e32 v204, v204, v205
	v_mov_b32_e32 v205, v204
	s_nop 1
	v_permlane32_swap_b32_e32 v204, v205
	v_add_f32_e32 v204, v204, v205
	v_mov_b32_e32 v205, 0x358637bd
	v_fmamk_f32 v204, v204, 0x3a800000, v205
	v_rsq_f32_e32 v204, v204
	s_nop 0
	v_pk_mul_f32 v[80:81], v[80:81], v[204:205] op_sel_hi:[1,0]
	v_pk_mul_f32 v[82:83], v[82:83], v[204:205] op_sel_hi:[1,0]
	v_pk_mul_f32 v[80:81], v[188:189], v[80:81]
	v_pk_mul_f32 v[82:83], v[190:191], v[82:83]
	v_pk_fma_f32 v[80:81], v[34:35], v[80:81], v[224:225]
	v_pk_fma_f32 v[82:83], v[36:37], v[82:83], v[226:227]
	v_cvt_pk_bf16_f32 v80, v80, v81
	v_cvt_pk_bf16_f32 v81, v82, v83
	global_store_dwordx2 v146, v[80:81], s[66:67]
	v_pk_mul_f32 v[84:85], v[84:85], v[204:205] op_sel_hi:[1,0]
	v_pk_mul_f32 v[86:87], v[86:87], v[204:205] op_sel_hi:[1,0]
	v_pk_mul_f32 v[84:85], v[192:193], v[84:85]
	v_pk_mul_f32 v[86:87], v[194:195], v[86:87]
	v_pk_fma_f32 v[84:85], v[38:39], v[84:85], v[228:229]
	v_pk_fma_f32 v[86:87], v[40:41], v[86:87], v[230:231]
	v_cvt_pk_bf16_f32 v84, v84, v85
	v_cvt_pk_bf16_f32 v85, v86, v87
	global_store_dwordx2 v146, v[84:85], s[66:67] offset:512
	v_pk_mul_f32 v[88:89], v[88:89], v[204:205] op_sel_hi:[1,0]
	v_pk_mul_f32 v[90:91], v[90:91], v[204:205] op_sel_hi:[1,0]
	v_pk_mul_f32 v[88:89], v[196:197], v[88:89]
	v_pk_mul_f32 v[90:91], v[198:199], v[90:91]
	v_pk_fma_f32 v[88:89], v[42:43], v[88:89], v[232:233]
	v_pk_fma_f32 v[90:91], v[44:45], v[90:91], v[234:235]
	v_cvt_pk_bf16_f32 v88, v88, v89
	v_cvt_pk_bf16_f32 v89, v90, v91
	global_store_dwordx2 v146, v[88:89], s[66:67] offset:1024
	v_pk_mul_f32 v[92:93], v[92:93], v[204:205] op_sel_hi:[1,0]
	v_pk_mul_f32 v[94:95], v[94:95], v[204:205] op_sel_hi:[1,0]
	v_pk_mul_f32 v[92:93], v[200:201], v[92:93]
	v_pk_mul_f32 v[94:95], v[202:203], v[94:95]
	v_pk_fma_f32 v[92:93], v[46:47], v[92:93], v[236:237]
	v_pk_fma_f32 v[94:95], v[48:49], v[94:95], v[238:239]
	v_cvt_pk_bf16_f32 v92, v92, v93
	v_cvt_pk_bf16_f32 v93, v94, v95
	global_store_dwordx2 v146, v[92:93], s[66:67] offset:1536
	v_add_u32_e32 v146, 0x800, v146
	global_load_dwordx4 v[80:83], v144, s[46:47] nt
	global_load_dwordx4 v[84:87], v144, s[46:47] offset:1024 nt
	global_load_dwordx4 v[88:91], v144, s[46:47] offset:2048 nt
	global_load_dwordx4 v[92:95], v144, s[46:47] offset:3072 nt
	v_add_u32_e32 v144, 0x1000, v144
	s_waitcnt vmcnt(40)
; __device__ __forceinline__ unsigned pk2(float lo, float hi) { const g_f32x2 f = {lo, hi}; return __builtin_bit_cast(unsigned, __builtin_convertvector(f, g_bf16x2)); }
; __device__ __forceinline__ void p_norm(const float* hlat, const float* hctx, const float* g, const float* modl, int sh_off, int sc_off, bf16_t* A, int M,
;                                        const float* part, const float* cgate, float* hcout) {
;     ...
;             ss += v[i].x * v[i].x + v[i].y * v[i].y + v[i].z * v[i].z + v[i].w * v[i].w; }
;         ss = wave_sum(ss);
;         const float rstd = rsqrtf(ss * (1.0f / 1024.0f) + EPS);
;         const float* mr = modl + (size_t)r * 6144;
; #pragma unroll
;         for (int i = 0; i < 4; ++i) {
;             const int k = i * 256 + lane * 4;
;             const float4 gg = *(const float4*)(g + k), scv = *(const float4*)(mr + sc_off + k), shv = *(const float4*)(mr + sh_off + k);
;             const float o0 = v[i].x * rstd * gg.x * (1.0f + scv.x) + shv.x, o1 = v[i].y * rstd * gg.y * (1.0f + scv.y) + shv.y;
;             const float o2 = v[i].z * rstd * gg.z * (1.0f + scv.z) + shv.z, o3 = v[i].w * rstd * gg.w * (1.0f + scv.w) + shv.w;
;             uint2 w; w.x = pk2(o0, o1); w.y = pk2(o2, o3);
;             *(uint2*)(A + (size_t)row * 1024 + k) = w;
	v_pk_mul_f32 v[242:243], v[96:97], v[96:97]
	v_pk_mul_f32 v[244:245], v[100:101], v[100:101]
	v_pk_mul_f32 v[246:247], v[98:99], v[98:99]
	v_pk_mul_f32 v[248:249], v[102:103], v[102:103]
	v_add_f32_e32 v204, v245, v244
	v_add_f32_e32 v205, v243, v242
	v_add_f32_e32 v204, v248, v204
	v_add_f32_e32 v205, v246, v205
	v_add_f32_e32 v204, v249, v204
	v_add_f32_e32 v205, v247, v205
	v_pk_mul_f32 v[242:243], v[104:105], v[104:105]
	v_pk_mul_f32 v[244:245], v[108:109], v[108:109]
	v_pk_mul_f32 v[246:247], v[106:107], v[106:107]
	v_pk_mul_f32 v[248:249], v[110:111], v[110:111]
	v_add_f32_e32 v206, v243, v242
	v_add_f32_e32 v207, v245, v244
	v_add_f32_e32 v206, v246, v206
	v_add_f32_e32 v207, v248, v207
	v_add_f32_e32 v206, v247, v206
	v_add_f32_e32 v207, v249, v207
	v_add_f32_e32 v204, v205, v204
	v_add_f32_e32 v204, v204, v206
	v_add_f32_e32 v204, v204, v207
	ds_swizzle_b32 v205, v204 offset:swizzle(SWAP,1)
	s_waitcnt lgkmcnt(0)
	v_add_f32_e32 v204, v204, v205
	ds_swizzle_b32 v205, v204 offset:swizzle(SWAP,2)
	s_waitcnt lgkmcnt(0)
	v_add_f32_e32 v204, v204, v205
	ds_swizzle_b32 v205, v204 offset:swizzle(SWAP,4)
	s_waitcnt lgkmcnt(0)
	v_add_f32_e32 v204, v204, v205
	ds_swizzle_b32 v205, v204 offset:swizzle(SWAP,8)
	s_waitcnt lgkmcnt(0)
	v_add_f32_e32 v204, v204, v205
	ds_swizzle_b32 v205, v204 offset:swizzle(SWAP,16)
	s_waitcnt lgkmcnt(0)
	v_add_f32_e32 v204, v204, v205
	v_mov_b32_e32 v205, v204
	s_nop 1
	v_permlane32_swap_b32_e32 v204, v205
	v_add_f32_e32 v204, v204, v205
	v_mov_b32_e32 v205, 0x358637bd
	v_fmamk_f32 v204, v204, 0x3a800000, v205
	v_rsq_f32_e32 v204, v204
	s_nop 0
	v_pk_mul_f32 v[96:97], v[96:97], v[204:205] op_sel_hi:[1,0]
	v_pk_mul_f32 v[98:99], v[98:99], v[204:205] op_sel_hi:[1,0]
	v_pk_mul_f32 v[96:97], v[188:189], v[96:97]
	v_pk_mul_f32 v[98:99], v[190:191], v[98:99]
	v_pk_fma_f32 v[96:97], v[34:35], v[96:97], v[224:225]
	v_pk_fma_f32 v[98:99], v[36:37], v[98:99], v[226:227]
	v_cvt_pk_bf16_f32 v96, v96, v97
	v_cvt_pk_bf16_f32 v97, v98, v99
	global_store_dwordx2 v146, v[96:97], s[66:67]
	v_pk_mul_f32 v[100:101], v[100:101], v[204:205] op_sel_hi:[1,0]
	v_pk_mul_f32 v[102:103], v[102:103], v[204:205] op_sel_hi:[1,0]
	v_pk_mul_f32 v[100:101], v[192:193], v[100:101]
	v_pk_mul_f32 v[102:103], v[194:195], v[102:103]
	v_pk_fma_f32 v[100:101], v[38:39], v[100:101], v[228:229]
	v_pk_fma_f32 v[102:103], v[40:41], v[102:103], v[230:231]
	v_cvt_pk_bf16_f32 v100, v100, v101
	v_cvt_pk_bf16_f32 v101, v102, v103
	global_store_dwordx2 v146, v[100:101], s[66:67] offset:512
	v_pk_mul_f32 v[104:105], v[104:105], v[204:205] op_sel_hi:[1,0]
	v_pk_mul_f32 v[106:107], v[106:107], v[204:205] op_sel_hi:[1,0]
	v_pk_mul_f32 v[104:105], v[196:197], v[104:105]
	v_pk_mul_f32 v[106:107], v[198:199], v[106:107]
	v_pk_fma_f32 v[104:105], v[42:43], v[104:105], v[232:233]
	v_pk_fma_f32 v[106:107], v[44:45], v[106:107], v[234:235]
	v_cvt_pk_bf16_f32 v104, v104, v105
	v_cvt_pk_bf16_f32 v105, v106, v107
	global_store_dwordx2 v146, v[104:105], s[66:67] offset:1024
	v_pk_mul_f32 v[108:109], v[108:109], v[204:205] op_sel_hi:[1,0]
	v_pk_mul_f32 v[110:111], v[110:111], v[204:205] op_sel_hi:[1,0]
	v_pk_mul_f32 v[108:109], v[200:201], v[108:109]
	v_pk_mul_f32 v[110:111], v[202:203], v[110:111]
	v_pk_fma_f32 v[108:109], v[46:47], v[108:109], v[236:237]
	v_pk_fma_f32 v[110:111], v[48:49], v[110:111], v[238:239]
	v_cvt_pk_bf16_f32 v108, v108, v109
	v_cvt_pk_bf16_f32 v109, v110, v111
	global_store_dwordx2 v146, v[108:109], s[66:67] offset:1536
	v_add_u32_e32 v146, 0x800, v146
	global_load_dwordx4 v[96:99], v144, s[46:47] nt
	global_load_dwordx4 v[100:103], v144, s[46:47] offset:1024 nt
	global_load_dwordx4 v[104:107], v144, s[46:47] offset:2048 nt
	global_load_dwordx4 v[108:111], v144, s[46:47] offset:3072 nt
	v_add_u32_e32 v144, 0x1000, v144
	s_waitcnt vmcnt(40)
	v_pk_mul_f32 v[242:243], v[112:113], v[112:113]
	v_pk_mul_f32 v[244:245], v[116:117], v[116:117]
	v_pk_mul_f32 v[246:247], v[114:115], v[114:115]
	v_pk_mul_f32 v[248:249], v[118:119], v[118:119]
	v_add_f32_e32 v204, v245, v244
	v_add_f32_e32 v205, v243, v242
	v_add_f32_e32 v204, v248, v204
	v_add_f32_e32 v205, v246, v205
	v_add_f32_e32 v204, v249, v204
	v_add_f32_e32 v205, v247, v205
	v_pk_mul_f32 v[242:243], v[120:121], v[120:121]
	v_pk_mul_f32 v[244:245], v[124:125], v[124:125]
	v_pk_mul_f32 v[246:247], v[122:123], v[122:123]
	v_pk_mul_f32 v[248:249], v[126:127], v[126:127]
	v_add_f32_e32 v206, v243, v242
	v_add_f32_e32 v207, v245, v244
	v_add_f32_e32 v206, v246, v206
	v_add_f32_e32 v207, v248, v207
	v_add_f32_e32 v206, v247, v206
	v_add_f32_e32 v207, v249, v207
	v_add_f32_e32 v204, v205, v204
	v_add_f32_e32 v204, v204, v206
	v_add_f32_e32 v204, v204, v207
	ds_swizzle_b32 v205, v204 offset:swizzle(SWAP,1)
	s_waitcnt lgkmcnt(0)
	v_add_f32_e32 v204, v204, v205
	ds_swizzle_b32 v205, v204 offset:swizzle(SWAP,2)
	s_waitcnt lgkmcnt(0)
	v_add_f32_e32 v204, v204, v205
	ds_swizzle_b32 v205, v204 offset:swizzle(SWAP,4)
	s_waitcnt lgkmcnt(0)
	v_add_f32_e32 v204, v204, v205
	ds_swizzle_b32 v205, v204 offset:swizzle(SWAP,8)
	s_waitcnt lgkmcnt(0)
	v_add_f32_e32 v204, v204, v205
	ds_swizzle_b32 v205, v204 offset:swizzle(SWAP,16)
	s_waitcnt lgkmcnt(0)
; __device__ __forceinline__ unsigned pk2(float lo, float hi) { const g_f32x2 f = {lo, hi}; return __builtin_bit_cast(unsigned, __builtin_convertvector(f, g_bf16x2)); }
; __device__ __forceinline__ void p_norm(const float* hlat, const float* hctx, const float* g, const float* modl, int sh_off, int sc_off, bf16_t* A, int M,
;                                        const float* part, const float* cgate, float* hcout) {
;     ...
;             ss += v[i].x * v[i].x + v[i].y * v[i].y + v[i].z * v[i].z + v[i].w * v[i].w; }
;         ss = wave_sum(ss);
;         const float rstd = rsqrtf(ss * (1.0f / 1024.0f) + EPS);
;         const float* mr = modl + (size_t)r * 6144;
; #pragma unroll
;         for (int i = 0; i < 4; ++i) {
;             const int k = i * 256 + lane * 4;
;             const float4 gg = *(const float4*)(g + k), scv = *(const float4*)(mr + sc_off + k), shv = *(const float4*)(mr + sh_off + k);
;             const float o0 = v[i].x * rstd * gg.x * (1.0f + scv.x) + shv.x, o1 = v[i].y * rstd * gg.y * (1.0f + scv.y) + shv.y;
;             const float o2 = v[i].z * rstd * gg.z * (1.0f + scv.z) + shv.z, o3 = v[i].w * rstd * gg.w * (1.0f + scv.w) + shv.w;
;             uint2 w; w.x = pk2(o0, o1); w.y = pk2(o2, o3);
;             *(uint2*)(A + (size_t)row * 1024 + k) = w;
	v_add_f32_e32 v204, v204, v205
	v_mov_b32_e32 v205, v204
	s_nop 1
	v_permlane32_swap_b32_e32 v204, v205
	v_add_f32_e32 v204, v204, v205
	v_mov_b32_e32 v205, 0x358637bd
	v_fmamk_f32 v204, v204, 0x3a800000, v205
	v_rsq_f32_e32 v204, v204
	s_nop 0
	v_pk_mul_f32 v[112:113], v[112:113], v[204:205] op_sel_hi:[1,0]
	v_pk_mul_f32 v[114:115], v[114:115], v[204:205] op_sel_hi:[1,0]
	v_pk_mul_f32 v[112:113], v[188:189], v[112:113]
	v_pk_mul_f32 v[114:115], v[190:191], v[114:115]
	v_pk_fma_f32 v[112:113], v[34:35], v[112:113], v[224:225]
	v_pk_fma_f32 v[114:115], v[36:37], v[114:115], v[226:227]
	v_cvt_pk_bf16_f32 v112, v112, v113
	v_cvt_pk_bf16_f32 v113, v114, v115
	global_store_dwordx2 v146, v[112:113], s[66:67]
	v_pk_mul_f32 v[116:117], v[116:117], v[204:205] op_sel_hi:[1,0]
	v_pk_mul_f32 v[118:119], v[118:119], v[204:205] op_sel_hi:[1,0]
	v_pk_mul_f32 v[116:117], v[192:193], v[116:117]
	v_pk_mul_f32 v[118:119], v[194:195], v[118:119]
	v_pk_fma_f32 v[116:117], v[38:39], v[116:117], v[228:229]
	v_pk_fma_f32 v[118:119], v[40:41], v[118:119], v[230:231]
	v_cvt_pk_bf16_f32 v116, v116, v117
	v_cvt_pk_bf16_f32 v117, v118, v119
	global_store_dwordx2 v146, v[116:117], s[66:67] offset:512
	v_pk_mul_f32 v[120:121], v[120:121], v[204:205] op_sel_hi:[1,0]
	v_pk_mul_f32 v[122:123], v[122:123], v[204:205] op_sel_hi:[1,0]
	v_pk_mul_f32 v[120:121], v[196:197], v[120:121]
	v_pk_mul_f32 v[122:123], v[198:199], v[122:123]
	v_pk_fma_f32 v[120:121], v[42:43], v[120:121], v[232:233]
	v_pk_fma_f32 v[122:123], v[44:45], v[122:123], v[234:235]
	v_cvt_pk_bf16_f32 v120, v120, v121
	v_cvt_pk_bf16_f32 v121, v122, v123
	global_store_dwordx2 v146, v[120:121], s[66:67] offset:1024
	v_pk_mul_f32 v[124:125], v[124:125], v[204:205] op_sel_hi:[1,0]
	v_pk_mul_f32 v[126:127], v[126:127], v[204:205] op_sel_hi:[1,0]
	v_pk_mul_f32 v[124:125], v[200:201], v[124:125]
	v_pk_mul_f32 v[126:127], v[202:203], v[126:127]
	v_pk_fma_f32 v[124:125], v[46:47], v[124:125], v[236:237]
	v_pk_fma_f32 v[126:127], v[48:49], v[126:127], v[238:239]
	v_cvt_pk_bf16_f32 v124, v124, v125
	v_cvt_pk_bf16_f32 v125, v126, v127
	global_store_dwordx2 v146, v[124:125], s[66:67] offset:1536
	v_add_u32_e32 v146, 0x800, v146
	global_load_dwordx4 v[112:115], v144, s[46:47] nt
	global_load_dwordx4 v[116:119], v144, s[46:47] offset:1024 nt
	global_load_dwordx4 v[120:123], v144, s[46:47] offset:2048 nt
	global_load_dwordx4 v[124:127], v144, s[46:47] offset:3072 nt
	v_add_u32_e32 v144, 0x1000, v144
	s_waitcnt vmcnt(40)
	v_pk_mul_f32 v[242:243], v[128:129], v[128:129]
	v_pk_mul_f32 v[244:245], v[132:133], v[132:133]
	v_pk_mul_f32 v[246:247], v[130:131], v[130:131]
	v_pk_mul_f32 v[248:249], v[134:135], v[134:135]
	v_add_f32_e32 v204, v245, v244
	v_add_f32_e32 v205, v243, v242
	v_add_f32_e32 v204, v248, v204
	v_add_f32_e32 v205, v246, v205
	v_add_f32_e32 v204, v249, v204
	v_add_f32_e32 v205, v247, v205
	v_pk_mul_f32 v[242:243], v[136:137], v[136:137]
	v_pk_mul_f32 v[244:245], v[140:141], v[140:141]
	v_pk_mul_f32 v[246:247], v[138:139], v[138:139]
	v_pk_mul_f32 v[248:249], v[142:143], v[142:143]
	v_add_f32_e32 v206, v243, v242
	v_add_f32_e32 v207, v245, v244
	v_add_f32_e32 v206, v246, v206
	v_add_f32_e32 v207, v248, v207
	v_add_f32_e32 v206, v247, v206
	v_add_f32_e32 v207, v249, v207
	v_add_f32_e32 v204, v205, v204
	v_add_f32_e32 v204, v204, v206
	v_add_f32_e32 v204, v204, v207
	ds_swizzle_b32 v205, v204 offset:swizzle(SWAP,1)
	s_waitcnt lgkmcnt(0)
	v_add_f32_e32 v204, v204, v205
	ds_swizzle_b32 v205, v204 offset:swizzle(SWAP,2)
	s_waitcnt lgkmcnt(0)
	v_add_f32_e32 v204, v204, v205
	ds_swizzle_b32 v205, v204 offset:swizzle(SWAP,4)
	s_waitcnt lgkmcnt(0)
	v_add_f32_e32 v204, v204, v205
	ds_swizzle_b32 v205, v204 offset:swizzle(SWAP,8)
	s_waitcnt lgkmcnt(0)
	v_add_f32_e32 v204, v204, v205
	ds_swizzle_b32 v205, v204 offset:swizzle(SWAP,16)
	s_waitcnt lgkmcnt(0)
	v_add_f32_e32 v204, v204, v205
	v_mov_b32_e32 v205, v204
	s_nop 1
	v_permlane32_swap_b32_e32 v204, v205
	v_add_f32_e32 v204, v204, v205
	v_mov_b32_e32 v205, 0x358637bd
	v_fmamk_f32 v204, v204, 0x3a800000, v205
	v_rsq_f32_e32 v204, v204
	s_nop 0
	v_pk_mul_f32 v[128:129], v[128:129], v[204:205] op_sel_hi:[1,0]
	v_pk_mul_f32 v[130:131], v[130:131], v[204:205] op_sel_hi:[1,0]
	v_pk_mul_f32 v[128:129], v[188:189], v[128:129]
	v_pk_mul_f32 v[130:131], v[190:191], v[130:131]
	v_pk_fma_f32 v[128:129], v[34:35], v[128:129], v[224:225]
	v_pk_fma_f32 v[130:131], v[36:37], v[130:131], v[226:227]
	v_cvt_pk_bf16_f32 v128, v128, v129
	v_cvt_pk_bf16_f32 v129, v130, v131
	global_store_dwordx2 v146, v[128:129], s[66:67]
	v_pk_mul_f32 v[132:133], v[132:133], v[204:205] op_sel_hi:[1,0]
	v_pk_mul_f32 v[134:135], v[134:135], v[204:205] op_sel_hi:[1,0]
	v_pk_mul_f32 v[132:133], v[192:193], v[132:133]
	v_pk_mul_f32 v[134:135], v[194:195], v[134:135]
	v_pk_fma_f32 v[132:133], v[38:39], v[132:133], v[228:229]
	v_pk_fma_f32 v[134:135], v[40:41], v[134:135], v[230:231]
	v_cvt_pk_bf16_f32 v132, v132, v133
	v_cvt_pk_bf16_f32 v133, v134, v135
	global_store_dwordx2 v146, v[132:133], s[66:67] offset:512
	v_pk_mul_f32 v[136:137], v[136:137], v[204:205] op_sel_hi:[1,0]
	v_pk_mul_f32 v[138:139], v[138:139], v[204:205] op_sel_hi:[1,0]
	v_pk_mul_f32 v[136:137], v[196:197], v[136:137]
	v_pk_mul_f32 v[138:139], v[198:199], v[138:139]
	v_pk_fma_f32 v[136:137], v[42:43], v[136:137], v[232:233]
	v_pk_fma_f32 v[138:139], v[44:45], v[138:139], v[234:235]
	v_cvt_pk_bf16_f32 v136, v136, v137
	v_cvt_pk_bf16_f32 v137, v138, v139
	global_store_dwordx2 v146, v[136:137], s[66:67] offset:1024
	v_pk_mul_f32 v[140:141], v[140:141], v[204:205] op_sel_hi:[1,0]
	v_pk_mul_f32 v[142:143], v[142:143], v[204:205] op_sel_hi:[1,0]
	v_pk_mul_f32 v[140:141], v[200:201], v[140:141]
	v_pk_mul_f32 v[142:143], v[202:203], v[142:143]
	v_pk_fma_f32 v[140:141], v[46:47], v[140:141], v[236:237]
	v_pk_fma_f32 v[142:143], v[48:49], v[142:143], v[238:239]
	v_cvt_pk_bf16_f32 v140, v140, v141
	v_cvt_pk_bf16_f32 v141, v142, v143
	global_store_dwordx2 v146, v[140:141], s[66:67] offset:1536
	v_add_u32_e32 v146, 0x800, v146
	global_load_dwordx4 v[128:131], v144, s[46:47] nt
	global_load_dwordx4 v[132:135], v144, s[46:47] offset:1024 nt
	global_load_dwordx4 v[136:139], v144, s[46:47] offset:2048 nt
	global_load_dwordx4 v[140:143], v144, s[46:47] offset:3072 nt
	v_add_u32_e32 v144, 0x1000, v144
	s_waitcnt vmcnt(40)
; __device__ __forceinline__ unsigned pk2(float lo, float hi) { const g_f32x2 f = {lo, hi}; return __builtin_bit_cast(unsigned, __builtin_convertvector(f, g_bf16x2)); }
; __device__ __forceinline__ void p_norm(const float* hlat, const float* hctx, const float* g, const float* modl, int sh_off, int sc_off, bf16_t* A, int M,
;                                        const float* part, const float* cgate, float* hcout) {
;     ...
;             ss += v[i].x * v[i].x + v[i].y * v[i].y + v[i].z * v[i].z + v[i].w * v[i].w; }
;         ss = wave_sum(ss);
;         const float rstd = rsqrtf(ss * (1.0f / 1024.0f) + EPS);
;         const float* mr = modl + (size_t)r * 6144;
; #pragma unroll
;         for (int i = 0; i < 4; ++i) {
;             const int k = i * 256 + lane * 4;
;             const float4 gg = *(const float4*)(g + k), scv = *(const float4*)(mr + sc_off + k), shv = *(const float4*)(mr + sh_off + k);
;             const float o0 = v[i].x * rstd * gg.x * (1.0f + scv.x) + shv.x, o1 = v[i].y * rstd * gg.y * (1.0f + scv.y) + shv.y;
;             const float o2 = v[i].z * rstd * gg.z * (1.0f + scv.z) + shv.z, o3 = v[i].w * rstd * gg.w * (1.0f + scv.w) + shv.w;
;             uint2 w; w.x = pk2(o0, o1); w.y = pk2(o2, o3);
;             *(uint2*)(A + (size_t)row * 1024 + k) = w;
	v_pk_mul_f32 v[242:243], v[156:157], v[156:157]
	v_pk_mul_f32 v[244:245], v[160:161], v[160:161]
	v_pk_mul_f32 v[246:247], v[158:159], v[158:159]
	v_pk_mul_f32 v[248:249], v[162:163], v[162:163]
	v_add_f32_e32 v204, v245, v244
	v_add_f32_e32 v205, v243, v242
	v_add_f32_e32 v204, v248, v204
	v_add_f32_e32 v205, v246, v205
	v_add_f32_e32 v204, v249, v204
	v_add_f32_e32 v205, v247, v205
	v_pk_mul_f32 v[242:243], v[164:165], v[164:165]
	v_pk_mul_f32 v[244:245], v[168:169], v[168:169]
	v_pk_mul_f32 v[246:247], v[166:167], v[166:167]
	v_pk_mul_f32 v[248:249], v[170:171], v[170:171]
	v_add_f32_e32 v206, v243, v242
	v_add_f32_e32 v207, v245, v244
	v_add_f32_e32 v206, v246, v206
	v_add_f32_e32 v207, v248, v207
	v_add_f32_e32 v206, v247, v206
	v_add_f32_e32 v207, v249, v207
	v_add_f32_e32 v204, v205, v204
	v_add_f32_e32 v204, v204, v206
	v_add_f32_e32 v204, v204, v207
	ds_swizzle_b32 v205, v204 offset:swizzle(SWAP,1)
	s_waitcnt lgkmcnt(0)
	v_add_f32_e32 v204, v204, v205
	ds_swizzle_b32 v205, v204 offset:swizzle(SWAP,2)
	s_waitcnt lgkmcnt(0)
	v_add_f32_e32 v204, v204, v205
	ds_swizzle_b32 v205, v204 offset:swizzle(SWAP,4)
	s_waitcnt lgkmcnt(0)
	v_add_f32_e32 v204, v204, v205
	ds_swizzle_b32 v205, v204 offset:swizzle(SWAP,8)
	s_waitcnt lgkmcnt(0)
	v_add_f32_e32 v204, v204, v205
	ds_swizzle_b32 v205, v204 offset:swizzle(SWAP,16)
	s_waitcnt lgkmcnt(0)
	v_add_f32_e32 v204, v204, v205
	v_mov_b32_e32 v205, v204
	s_nop 1
	v_permlane32_swap_b32_e32 v204, v205
	v_add_f32_e32 v204, v204, v205
	v_mov_b32_e32 v205, 0x358637bd
	v_fmamk_f32 v204, v204, 0x3a800000, v205
	v_rsq_f32_e32 v204, v204
	s_nop 0
	v_pk_mul_f32 v[156:157], v[156:157], v[204:205] op_sel_hi:[1,0]
	v_pk_mul_f32 v[158:159], v[158:159], v[204:205] op_sel_hi:[1,0]
	v_pk_mul_f32 v[156:157], v[188:189], v[156:157]
	v_pk_mul_f32 v[158:159], v[190:191], v[158:159]
	v_pk_fma_f32 v[156:157], v[34:35], v[156:157], v[224:225]
	v_pk_fma_f32 v[158:159], v[36:37], v[158:159], v[226:227]
	v_cvt_pk_bf16_f32 v156, v156, v157
	v_cvt_pk_bf16_f32 v157, v158, v159
	global_store_dwordx2 v146, v[156:157], s[66:67]
	v_pk_mul_f32 v[160:161], v[160:161], v[204:205] op_sel_hi:[1,0]
	v_pk_mul_f32 v[162:163], v[162:163], v[204:205] op_sel_hi:[1,0]
	v_pk_mul_f32 v[160:161], v[192:193], v[160:161]
	v_pk_mul_f32 v[162:163], v[194:195], v[162:163]
	v_pk_fma_f32 v[160:161], v[38:39], v[160:161], v[228:229]
	v_pk_fma_f32 v[162:163], v[40:41], v[162:163], v[230:231]
	v_cvt_pk_bf16_f32 v160, v160, v161
	v_cvt_pk_bf16_f32 v161, v162, v163
	global_store_dwordx2 v146, v[160:161], s[66:67] offset:512
	v_pk_mul_f32 v[164:165], v[164:165], v[204:205] op_sel_hi:[1,0]
	v_pk_mul_f32 v[166:167], v[166:167], v[204:205] op_sel_hi:[1,0]
	v_pk_mul_f32 v[164:165], v[196:197], v[164:165]
	v_pk_mul_f32 v[166:167], v[198:199], v[166:167]
	v_pk_fma_f32 v[164:165], v[42:43], v[164:165], v[232:233]
	v_pk_fma_f32 v[166:167], v[44:45], v[166:167], v[234:235]
	v_cvt_pk_bf16_f32 v164, v164, v165
	v_cvt_pk_bf16_f32 v165, v166, v167
	global_store_dwordx2 v146, v[164:165], s[66:67] offset:1024
	v_pk_mul_f32 v[168:169], v[168:169], v[204:205] op_sel_hi:[1,0]
	v_pk_mul_f32 v[170:171], v[170:171], v[204:205] op_sel_hi:[1,0]
	v_pk_mul_f32 v[168:169], v[200:201], v[168:169]
	v_pk_mul_f32 v[170:171], v[202:203], v[170:171]
	v_pk_fma_f32 v[168:169], v[46:47], v[168:169], v[236:237]
	v_pk_fma_f32 v[170:171], v[48:49], v[170:171], v[238:239]
	v_cvt_pk_bf16_f32 v168, v168, v169
	v_cvt_pk_bf16_f32 v169, v170, v171
	global_store_dwordx2 v146, v[168:169], s[66:67] offset:1536
	v_add_u32_e32 v146, 0x800, v146
	s_waitcnt vmcnt(36)
	v_pk_mul_f32 v[242:243], v[172:173], v[172:173]
	v_pk_mul_f32 v[244:245], v[176:177], v[176:177]
	v_pk_mul_f32 v[246:247], v[174:175], v[174:175]
	v_pk_mul_f32 v[248:249], v[178:179], v[178:179]
	v_add_f32_e32 v204, v245, v244
	v_add_f32_e32 v205, v243, v242
	v_add_f32_e32 v204, v248, v204
	v_add_f32_e32 v205, v246, v205
	v_add_f32_e32 v204, v249, v204
	v_add_f32_e32 v205, v247, v205
	v_pk_mul_f32 v[242:243], v[180:181], v[180:181]
	v_pk_mul_f32 v[244:245], v[184:185], v[184:185]
	v_pk_mul_f32 v[246:247], v[182:183], v[182:183]
	v_pk_mul_f32 v[248:249], v[186:187], v[186:187]
	v_add_f32_e32 v206, v243, v242
	v_add_f32_e32 v207, v245, v244
	v_add_f32_e32 v206, v246, v206
	v_add_f32_e32 v207, v248, v207
	v_add_f32_e32 v206, v247, v206
	v_add_f32_e32 v207, v249, v207
	v_add_f32_e32 v204, v205, v204
	v_add_f32_e32 v204, v204, v206
	v_add_f32_e32 v204, v204, v207
	ds_swizzle_b32 v205, v204 offset:swizzle(SWAP,1)
	s_waitcnt lgkmcnt(0)
	v_add_f32_e32 v204, v204, v205
	ds_swizzle_b32 v205, v204 offset:swizzle(SWAP,2)
	s_waitcnt lgkmcnt(0)
	v_add_f32_e32 v204, v204, v205
	ds_swizzle_b32 v205, v204 offset:swizzle(SWAP,4)
	s_waitcnt lgkmcnt(0)
	v_add_f32_e32 v204, v204, v205
	ds_swizzle_b32 v205, v204 offset:swizzle(SWAP,8)
	s_waitcnt lgkmcnt(0)
	v_add_f32_e32 v204, v204, v205
	ds_swizzle_b32 v205, v204 offset:swizzle(SWAP,16)
	s_waitcnt lgkmcnt(0)
; __device__ __forceinline__ unsigned pk2(float lo, float hi) { const g_f32x2 f = {lo, hi}; return __builtin_bit_cast(unsigned, __builtin_convertvector(f, g_bf16x2)); }
; __device__ __forceinline__ void p_norm(const float* hlat, const float* hctx, const float* g, const float* modl, int sh_off, int sc_off, bf16_t* A, int M,
;                                        const float* part, const float* cgate, float* hcout) {
;     ...
;             ss += v[i].x * v[i].x + v[i].y * v[i].y + v[i].z * v[i].z + v[i].w * v[i].w; }
;         ss = wave_sum(ss);
;         const float rstd = rsqrtf(ss * (1.0f / 1024.0f) + EPS);
;         const float* mr = modl + (size_t)r * 6144;
; #pragma unroll
;         for (int i = 0; i < 4; ++i) {
;             const int k = i * 256 + lane * 4;
;             const float4 gg = *(const float4*)(g + k), scv = *(const float4*)(mr + sc_off + k), shv = *(const float4*)(mr + sh_off + k);
;             const float o0 = v[i].x * rstd * gg.x * (1.0f + scv.x) + shv.x, o1 = v[i].y * rstd * gg.y * (1.0f + scv.y) + shv.y;
;             const float o2 = v[i].z * rstd * gg.z * (1.0f + scv.z) + shv.z, o3 = v[i].w * rstd * gg.w * (1.0f + scv.w) + shv.w;
;             uint2 w; w.x = pk2(o0, o1); w.y = pk2(o2, o3);
;             *(uint2*)(A + (size_t)row * 1024 + k) = w;
	v_add_f32_e32 v204, v204, v205
	v_mov_b32_e32 v205, v204
	s_nop 1
	v_permlane32_swap_b32_e32 v204, v205
	v_add_f32_e32 v204, v204, v205
	v_mov_b32_e32 v205, 0x358637bd
	v_fmamk_f32 v204, v204, 0x3a800000, v205
	v_rsq_f32_e32 v204, v204
	s_nop 0
	v_pk_mul_f32 v[172:173], v[172:173], v[204:205] op_sel_hi:[1,0]
	v_pk_mul_f32 v[174:175], v[174:175], v[204:205] op_sel_hi:[1,0]
	v_pk_mul_f32 v[172:173], v[188:189], v[172:173]
	v_pk_mul_f32 v[174:175], v[190:191], v[174:175]
	v_pk_fma_f32 v[172:173], v[34:35], v[172:173], v[224:225]
	v_pk_fma_f32 v[174:175], v[36:37], v[174:175], v[226:227]
	v_cvt_pk_bf16_f32 v172, v172, v173
	v_cvt_pk_bf16_f32 v173, v174, v175
	global_store_dwordx2 v146, v[172:173], s[66:67]
	v_pk_mul_f32 v[176:177], v[176:177], v[204:205] op_sel_hi:[1,0]
	v_pk_mul_f32 v[178:179], v[178:179], v[204:205] op_sel_hi:[1,0]
	v_pk_mul_f32 v[176:177], v[192:193], v[176:177]
	v_pk_mul_f32 v[178:179], v[194:195], v[178:179]
	v_pk_fma_f32 v[176:177], v[38:39], v[176:177], v[228:229]
	v_pk_fma_f32 v[178:179], v[40:41], v[178:179], v[230:231]
	v_cvt_pk_bf16_f32 v176, v176, v177
	v_cvt_pk_bf16_f32 v177, v178, v179
	global_store_dwordx2 v146, v[176:177], s[66:67] offset:512
	v_pk_mul_f32 v[180:181], v[180:181], v[204:205] op_sel_hi:[1,0]
	v_pk_mul_f32 v[182:183], v[182:183], v[204:205] op_sel_hi:[1,0]
	v_pk_mul_f32 v[180:181], v[196:197], v[180:181]
	v_pk_mul_f32 v[182:183], v[198:199], v[182:183]
	v_pk_fma_f32 v[180:181], v[42:43], v[180:181], v[232:233]
	v_pk_fma_f32 v[182:183], v[44:45], v[182:183], v[234:235]
	v_cvt_pk_bf16_f32 v180, v180, v181
	v_cvt_pk_bf16_f32 v181, v182, v183
	global_store_dwordx2 v146, v[180:181], s[66:67] offset:1024
	v_pk_mul_f32 v[184:185], v[184:185], v[204:205] op_sel_hi:[1,0]
	v_pk_mul_f32 v[186:187], v[186:187], v[204:205] op_sel_hi:[1,0]
	v_pk_mul_f32 v[184:185], v[200:201], v[184:185]
	v_pk_mul_f32 v[186:187], v[202:203], v[186:187]
	v_pk_fma_f32 v[184:185], v[46:47], v[184:185], v[236:237]
	v_pk_fma_f32 v[186:187], v[48:49], v[186:187], v[238:239]
	v_cvt_pk_bf16_f32 v184, v184, v185
	v_cvt_pk_bf16_f32 v185, v186, v187
	global_store_dwordx2 v146, v[184:185], s[66:67] offset:1536
	v_add_u32_e32 v146, 0x800, v146
	s_waitcnt vmcnt(32)
	v_pk_mul_f32 v[242:243], v[80:81], v[80:81]
	v_pk_mul_f32 v[244:245], v[84:85], v[84:85]
	v_pk_mul_f32 v[246:247], v[82:83], v[82:83]
	v_pk_mul_f32 v[248:249], v[86:87], v[86:87]
	v_add_f32_e32 v204, v245, v244
	v_add_f32_e32 v205, v243, v242
	v_add_f32_e32 v204, v248, v204
	v_add_f32_e32 v205, v246, v205
	v_add_f32_e32 v204, v249, v204
	v_add_f32_e32 v205, v247, v205
	v_pk_mul_f32 v[242:243], v[88:89], v[88:89]
	v_pk_mul_f32 v[244:245], v[92:93], v[92:93]
	v_pk_mul_f32 v[246:247], v[90:91], v[90:91]
	v_pk_mul_f32 v[248:249], v[94:95], v[94:95]
	v_add_f32_e32 v206, v243, v242
	v_add_f32_e32 v207, v245, v244
	v_add_f32_e32 v206, v246, v206
	v_add_f32_e32 v207, v248, v207
	v_add_f32_e32 v206, v247, v206
	v_add_f32_e32 v207, v249, v207
	v_add_f32_e32 v204, v205, v204
	v_add_f32_e32 v204, v204, v206
	v_add_f32_e32 v204, v204, v207
	ds_swizzle_b32 v205, v204 offset:swizzle(SWAP,1)
	s_waitcnt lgkmcnt(0)
	v_add_f32_e32 v204, v204, v205
	ds_swizzle_b32 v205, v204 offset:swizzle(SWAP,2)
	s_waitcnt lgkmcnt(0)
	v_add_f32_e32 v204, v204, v205
	ds_swizzle_b32 v205, v204 offset:swizzle(SWAP,4)
	s_waitcnt lgkmcnt(0)
	v_add_f32_e32 v204, v204, v205
	ds_swizzle_b32 v205, v204 offset:swizzle(SWAP,8)
	s_waitcnt lgkmcnt(0)
	v_add_f32_e32 v204, v204, v205
	ds_swizzle_b32 v205, v204 offset:swizzle(SWAP,16)
	s_waitcnt lgkmcnt(0)
	v_add_f32_e32 v204, v204, v205
	v_mov_b32_e32 v205, v204
	s_nop 1
	v_permlane32_swap_b32_e32 v204, v205
	v_add_f32_e32 v204, v204, v205
	v_mov_b32_e32 v205, 0x358637bd
	v_fmamk_f32 v204, v204, 0x3a800000, v205
	v_rsq_f32_e32 v204, v204
	s_nop 0
	v_pk_mul_f32 v[80:81], v[80:81], v[204:205] op_sel_hi:[1,0]
	v_pk_mul_f32 v[82:83], v[82:83], v[204:205] op_sel_hi:[1,0]
	v_pk_mul_f32 v[80:81], v[188:189], v[80:81]
	v_pk_mul_f32 v[82:83], v[190:191], v[82:83]
	v_pk_fma_f32 v[80:81], v[34:35], v[80:81], v[224:225]
	v_pk_fma_f32 v[82:83], v[36:37], v[82:83], v[226:227]
	v_cvt_pk_bf16_f32 v80, v80, v81
	v_cvt_pk_bf16_f32 v81, v82, v83
	global_store_dwordx2 v146, v[80:81], s[66:67]
	v_pk_mul_f32 v[84:85], v[84:85], v[204:205] op_sel_hi:[1,0]
	v_pk_mul_f32 v[86:87], v[86:87], v[204:205] op_sel_hi:[1,0]
	v_pk_mul_f32 v[84:85], v[192:193], v[84:85]
	v_pk_mul_f32 v[86:87], v[194:195], v[86:87]
	v_pk_fma_f32 v[84:85], v[38:39], v[84:85], v[228:229]
	v_pk_fma_f32 v[86:87], v[40:41], v[86:87], v[230:231]
	v_cvt_pk_bf16_f32 v84, v84, v85
	v_cvt_pk_bf16_f32 v85, v86, v87
	global_store_dwordx2 v146, v[84:85], s[66:67] offset:512
	v_pk_mul_f32 v[88:89], v[88:89], v[204:205] op_sel_hi:[1,0]
	v_pk_mul_f32 v[90:91], v[90:91], v[204:205] op_sel_hi:[1,0]
	v_pk_mul_f32 v[88:89], v[196:197], v[88:89]
	v_pk_mul_f32 v[90:91], v[198:199], v[90:91]
	v_pk_fma_f32 v[88:89], v[42:43], v[88:89], v[232:233]
	v_pk_fma_f32 v[90:91], v[44:45], v[90:91], v[234:235]
	v_cvt_pk_bf16_f32 v88, v88, v89
	v_cvt_pk_bf16_f32 v89, v90, v91
	global_store_dwordx2 v146, v[88:89], s[66:67] offset:1024
	v_pk_mul_f32 v[92:93], v[92:93], v[204:205] op_sel_hi:[1,0]
	v_pk_mul_f32 v[94:95], v[94:95], v[204:205] op_sel_hi:[1,0]
	v_pk_mul_f32 v[92:93], v[200:201], v[92:93]
	v_pk_mul_f32 v[94:95], v[202:203], v[94:95]
	v_pk_fma_f32 v[92:93], v[46:47], v[92:93], v[236:237]
	v_pk_fma_f32 v[94:95], v[48:49], v[94:95], v[238:239]
	v_cvt_pk_bf16_f32 v92, v92, v93
	v_cvt_pk_bf16_f32 v93, v94, v95
	global_store_dwordx2 v146, v[92:93], s[66:67] offset:1536
	v_add_u32_e32 v146, 0x800, v146
	s_waitcnt vmcnt(28)
; __device__ __forceinline__ unsigned pk2(float lo, float hi) { const g_f32x2 f = {lo, hi}; return __builtin_bit_cast(unsigned, __builtin_convertvector(f, g_bf16x2)); }
; __device__ __forceinline__ void p_norm(const float* hlat, const float* hctx, const float* g, const float* modl, int sh_off, int sc_off, bf16_t* A, int M,
;                                        const float* part, const float* cgate, float* hcout) {
;     ...
;             ss += v[i].x * v[i].x + v[i].y * v[i].y + v[i].z * v[i].z + v[i].w * v[i].w; }
;         ss = wave_sum(ss);
;         const float rstd = rsqrtf(ss * (1.0f / 1024.0f) + EPS);
;         const float* mr = modl + (size_t)r * 6144;
; #pragma unroll
;         for (int i = 0; i < 4; ++i) {
;             const int k = i * 256 + lane * 4;
;             const float4 gg = *(const float4*)(g + k), scv = *(const float4*)(mr + sc_off + k), shv = *(const float4*)(mr + sh_off + k);
;             const float o0 = v[i].x * rstd * gg.x * (1.0f + scv.x) + shv.x, o1 = v[i].y * rstd * gg.y * (1.0f + scv.y) + shv.y;
;             const float o2 = v[i].z * rstd * gg.z * (1.0f + scv.z) + shv.z, o3 = v[i].w * rstd * gg.w * (1.0f + scv.w) + shv.w;
;             uint2 w; w.x = pk2(o0, o1); w.y = pk2(o2, o3);
;             *(uint2*)(A + (size_t)row * 1024 + k) = w;
	v_pk_mul_f32 v[242:243], v[96:97], v[96:97]
	v_pk_mul_f32 v[244:245], v[100:101], v[100:101]
	v_pk_mul_f32 v[246:247], v[98:99], v[98:99]
	v_pk_mul_f32 v[248:249], v[102:103], v[102:103]
	v_add_f32_e32 v204, v245, v244
	v_add_f32_e32 v205, v243, v242
	v_add_f32_e32 v204, v248, v204
	v_add_f32_e32 v205, v246, v205
	v_add_f32_e32 v204, v249, v204
	v_add_f32_e32 v205, v247, v205
	v_pk_mul_f32 v[242:243], v[104:105], v[104:105]
	v_pk_mul_f32 v[244:245], v[108:109], v[108:109]
	v_pk_mul_f32 v[246:247], v[106:107], v[106:107]
	v_pk_mul_f32 v[248:249], v[110:111], v[110:111]
	v_add_f32_e32 v206, v243, v242
	v_add_f32_e32 v207, v245, v244
	v_add_f32_e32 v206, v246, v206
	v_add_f32_e32 v207, v248, v207
	v_add_f32_e32 v206, v247, v206
	v_add_f32_e32 v207, v249, v207
	v_add_f32_e32 v204, v205, v204
	v_add_f32_e32 v204, v204, v206
	v_add_f32_e32 v204, v204, v207
	ds_swizzle_b32 v205, v204 offset:swizzle(SWAP,1)
	s_waitcnt lgkmcnt(0)
	v_add_f32_e32 v204, v204, v205
	ds_swizzle_b32 v205, v204 offset:swizzle(SWAP,2)
	s_waitcnt lgkmcnt(0)
	v_add_f32_e32 v204, v204, v205
	ds_swizzle_b32 v205, v204 offset:swizzle(SWAP,4)
	s_waitcnt lgkmcnt(0)
	v_add_f32_e32 v204, v204, v205
	ds_swizzle_b32 v205, v204 offset:swizzle(SWAP,8)
	s_waitcnt lgkmcnt(0)
	v_add_f32_e32 v204, v204, v205
	ds_swizzle_b32 v205, v204 offset:swizzle(SWAP,16)
	s_waitcnt lgkmcnt(0)
	v_add_f32_e32 v204, v204, v205
	v_mov_b32_e32 v205, v204
	s_nop 1
	v_permlane32_swap_b32_e32 v204, v205
	v_add_f32_e32 v204, v204, v205
	v_mov_b32_e32 v205, 0x358637bd
	v_fmamk_f32 v204, v204, 0x3a800000, v205
	v_rsq_f32_e32 v204, v204
	s_nop 0
	v_pk_mul_f32 v[96:97], v[96:97], v[204:205] op_sel_hi:[1,0]
	v_pk_mul_f32 v[98:99], v[98:99], v[204:205] op_sel_hi:[1,0]
	v_pk_mul_f32 v[96:97], v[188:189], v[96:97]
	v_pk_mul_f32 v[98:99], v[190:191], v[98:99]
	v_pk_fma_f32 v[96:97], v[34:35], v[96:97], v[224:225]
	v_pk_fma_f32 v[98:99], v[36:37], v[98:99], v[226:227]
	v_cvt_pk_bf16_f32 v96, v96, v97
	v_cvt_pk_bf16_f32 v97, v98, v99
	global_store_dwordx2 v146, v[96:97], s[66:67]
	v_pk_mul_f32 v[100:101], v[100:101], v[204:205] op_sel_hi:[1,0]
	v_pk_mul_f32 v[102:103], v[102:103], v[204:205] op_sel_hi:[1,0]
	v_pk_mul_f32 v[100:101], v[192:193], v[100:101]
	v_pk_mul_f32 v[102:103], v[194:195], v[102:103]
	v_pk_fma_f32 v[100:101], v[38:39], v[100:101], v[228:229]
	v_pk_fma_f32 v[102:103], v[40:41], v[102:103], v[230:231]
	v_cvt_pk_bf16_f32 v100, v100, v101
	v_cvt_pk_bf16_f32 v101, v102, v103
	global_store_dwordx2 v146, v[100:101], s[66:67] offset:512
	v_pk_mul_f32 v[104:105], v[104:105], v[204:205] op_sel_hi:[1,0]
	v_pk_mul_f32 v[106:107], v[106:107], v[204:205] op_sel_hi:[1,0]
	v_pk_mul_f32 v[104:105], v[196:197], v[104:105]
	v_pk_mul_f32 v[106:107], v[198:199], v[106:107]
	v_pk_fma_f32 v[104:105], v[42:43], v[104:105], v[232:233]
	v_pk_fma_f32 v[106:107], v[44:45], v[106:107], v[234:235]
	v_cvt_pk_bf16_f32 v104, v104, v105
	v_cvt_pk_bf16_f32 v105, v106, v107
	global_store_dwordx2 v146, v[104:105], s[66:67] offset:1024
	v_pk_mul_f32 v[108:109], v[108:109], v[204:205] op_sel_hi:[1,0]
	v_pk_mul_f32 v[110:111], v[110:111], v[204:205] op_sel_hi:[1,0]
	v_pk_mul_f32 v[108:109], v[200:201], v[108:109]
	v_pk_mul_f32 v[110:111], v[202:203], v[110:111]
	v_pk_fma_f32 v[108:109], v[46:47], v[108:109], v[236:237]
	v_pk_fma_f32 v[110:111], v[48:49], v[110:111], v[238:239]
	v_cvt_pk_bf16_f32 v108, v108, v109
	v_cvt_pk_bf16_f32 v109, v110, v111
	global_store_dwordx2 v146, v[108:109], s[66:67] offset:1536
	v_add_u32_e32 v146, 0x800, v146
	s_waitcnt vmcnt(24)
	v_pk_mul_f32 v[242:243], v[112:113], v[112:113]
	v_pk_mul_f32 v[244:245], v[116:117], v[116:117]
	v_pk_mul_f32 v[246:247], v[114:115], v[114:115]
	v_pk_mul_f32 v[248:249], v[118:119], v[118:119]
	v_add_f32_e32 v204, v245, v244
	v_add_f32_e32 v205, v243, v242
	v_add_f32_e32 v204, v248, v204
	v_add_f32_e32 v205, v246, v205
	v_add_f32_e32 v204, v249, v204
	v_add_f32_e32 v205, v247, v205
	v_pk_mul_f32 v[242:243], v[120:121], v[120:121]
	v_pk_mul_f32 v[244:245], v[124:125], v[124:125]
	v_pk_mul_f32 v[246:247], v[122:123], v[122:123]
	v_pk_mul_f32 v[248:249], v[126:127], v[126:127]
	v_add_f32_e32 v206, v243, v242
	v_add_f32_e32 v207, v245, v244
	v_add_f32_e32 v206, v246, v206
	v_add_f32_e32 v207, v248, v207
	v_add_f32_e32 v206, v247, v206
	v_add_f32_e32 v207, v249, v207
	v_add_f32_e32 v204, v205, v204
	v_add_f32_e32 v204, v204, v206
	v_add_f32_e32 v204, v204, v207
	ds_swizzle_b32 v205, v204 offset:swizzle(SWAP,1)
	s_waitcnt lgkmcnt(0)
	v_add_f32_e32 v204, v204, v205
	ds_swizzle_b32 v205, v204 offset:swizzle(SWAP,2)
	s_waitcnt lgkmcnt(0)
	v_add_f32_e32 v204, v204, v205
	ds_swizzle_b32 v205, v204 offset:swizzle(SWAP,4)
	s_waitcnt lgkmcnt(0)
	v_add_f32_e32 v204, v204, v205
	ds_swizzle_b32 v205, v204 offset:swizzle(SWAP,8)
	s_waitcnt lgkmcnt(0)
	v_add_f32_e32 v204, v204, v205
	ds_swizzle_b32 v205, v204 offset:swizzle(SWAP,16)
	s_waitcnt lgkmcnt(0)
; __device__ __forceinline__ unsigned pk2(float lo, float hi) { const g_f32x2 f = {lo, hi}; return __builtin_bit_cast(unsigned, __builtin_convertvector(f, g_bf16x2)); }
; __device__ __forceinline__ void p_norm(const float* hlat, const float* hctx, const float* g, const float* modl, int sh_off, int sc_off, bf16_t* A, int M,
;                                        const float* part, const float* cgate, float* hcout) {
;     ...
;             ss += v[i].x * v[i].x + v[i].y * v[i].y + v[i].z * v[i].z + v[i].w * v[i].w; }
;         ss = wave_sum(ss);
;         const float rstd = rsqrtf(ss * (1.0f / 1024.0f) + EPS);
;         const float* mr = modl + (size_t)r * 6144;
; #pragma unroll
;         for (int i = 0; i < 4; ++i) {
;             const int k = i * 256 + lane * 4;
;             const float4 gg = *(const float4*)(g + k), scv = *(const float4*)(mr + sc_off + k), shv = *(const float4*)(mr + sh_off + k);
;             const float o0 = v[i].x * rstd * gg.x * (1.0f + scv.x) + shv.x, o1 = v[i].y * rstd * gg.y * (1.0f + scv.y) + shv.y;
;             const float o2 = v[i].z * rstd * gg.z * (1.0f + scv.z) + shv.z, o3 = v[i].w * rstd * gg.w * (1.0f + scv.w) + shv.w;
;             uint2 w; w.x = pk2(o0, o1); w.y = pk2(o2, o3);
;             *(uint2*)(A + (size_t)row * 1024 + k) = w;
	v_add_f32_e32 v204, v204, v205
	v_mov_b32_e32 v205, v204
	s_nop 1
	v_permlane32_swap_b32_e32 v204, v205
	v_add_f32_e32 v204, v204, v205
	v_mov_b32_e32 v205, 0x358637bd
	v_fmamk_f32 v204, v204, 0x3a800000, v205
	v_rsq_f32_e32 v204, v204
	s_nop 0
	v_pk_mul_f32 v[112:113], v[112:113], v[204:205] op_sel_hi:[1,0]
	v_pk_mul_f32 v[114:115], v[114:115], v[204:205] op_sel_hi:[1,0]
	v_pk_mul_f32 v[112:113], v[188:189], v[112:113]
	v_pk_mul_f32 v[114:115], v[190:191], v[114:115]
	v_pk_fma_f32 v[112:113], v[34:35], v[112:113], v[224:225]
	v_pk_fma_f32 v[114:115], v[36:37], v[114:115], v[226:227]
	v_cvt_pk_bf16_f32 v112, v112, v113
	v_cvt_pk_bf16_f32 v113, v114, v115
	global_store_dwordx2 v146, v[112:113], s[66:67]
	v_pk_mul_f32 v[116:117], v[116:117], v[204:205] op_sel_hi:[1,0]
	v_pk_mul_f32 v[118:119], v[118:119], v[204:205] op_sel_hi:[1,0]
	v_pk_mul_f32 v[116:117], v[192:193], v[116:117]
	v_pk_mul_f32 v[118:119], v[194:195], v[118:119]
	v_pk_fma_f32 v[116:117], v[38:39], v[116:117], v[228:229]
	v_pk_fma_f32 v[118:119], v[40:41], v[118:119], v[230:231]
	v_cvt_pk_bf16_f32 v116, v116, v117
	v_cvt_pk_bf16_f32 v117, v118, v119
	global_store_dwordx2 v146, v[116:117], s[66:67] offset:512
	v_pk_mul_f32 v[120:121], v[120:121], v[204:205] op_sel_hi:[1,0]
	v_pk_mul_f32 v[122:123], v[122:123], v[204:205] op_sel_hi:[1,0]
	v_pk_mul_f32 v[120:121], v[196:197], v[120:121]
	v_pk_mul_f32 v[122:123], v[198:199], v[122:123]
	v_pk_fma_f32 v[120:121], v[42:43], v[120:121], v[232:233]
	v_pk_fma_f32 v[122:123], v[44:45], v[122:123], v[234:235]
	v_cvt_pk_bf16_f32 v120, v120, v121
	v_cvt_pk_bf16_f32 v121, v122, v123
	global_store_dwordx2 v146, v[120:121], s[66:67] offset:1024
	v_pk_mul_f32 v[124:125], v[124:125], v[204:205] op_sel_hi:[1,0]
	v_pk_mul_f32 v[126:127], v[126:127], v[204:205] op_sel_hi:[1,0]
	v_pk_mul_f32 v[124:125], v[200:201], v[124:125]
	v_pk_mul_f32 v[126:127], v[202:203], v[126:127]
	v_pk_fma_f32 v[124:125], v[46:47], v[124:125], v[236:237]
	v_pk_fma_f32 v[126:127], v[48:49], v[126:127], v[238:239]
	v_cvt_pk_bf16_f32 v124, v124, v125
	v_cvt_pk_bf16_f32 v125, v126, v127
	global_store_dwordx2 v146, v[124:125], s[66:67] offset:1536
	v_add_u32_e32 v146, 0x800, v146
	s_waitcnt vmcnt(20)
	v_pk_mul_f32 v[242:243], v[128:129], v[128:129]
	v_pk_mul_f32 v[244:245], v[132:133], v[132:133]
	v_pk_mul_f32 v[246:247], v[130:131], v[130:131]
	v_pk_mul_f32 v[248:249], v[134:135], v[134:135]
	v_add_f32_e32 v204, v245, v244
	v_add_f32_e32 v205, v243, v242
	v_add_f32_e32 v204, v248, v204
	v_add_f32_e32 v205, v246, v205
	v_add_f32_e32 v204, v249, v204
	v_add_f32_e32 v205, v247, v205
	v_pk_mul_f32 v[242:243], v[136:137], v[136:137]
	v_pk_mul_f32 v[244:245], v[140:141], v[140:141]
	v_pk_mul_f32 v[246:247], v[138:139], v[138:139]
	v_pk_mul_f32 v[248:249], v[142:143], v[142:143]
	v_add_f32_e32 v206, v243, v242
	v_add_f32_e32 v207, v245, v244
	v_add_f32_e32 v206, v246, v206
	v_add_f32_e32 v207, v248, v207
	v_add_f32_e32 v206, v247, v206
	v_add_f32_e32 v207, v249, v207
	v_add_f32_e32 v204, v205, v204
	v_add_f32_e32 v204, v204, v206
	v_add_f32_e32 v204, v204, v207
	ds_swizzle_b32 v205, v204 offset:swizzle(SWAP,1)
	s_waitcnt lgkmcnt(0)
	v_add_f32_e32 v204, v204, v205
	ds_swizzle_b32 v205, v204 offset:swizzle(SWAP,2)
	s_waitcnt lgkmcnt(0)
	v_add_f32_e32 v204, v204, v205
	ds_swizzle_b32 v205, v204 offset:swizzle(SWAP,4)
	s_waitcnt lgkmcnt(0)
	v_add_f32_e32 v204, v204, v205
	ds_swizzle_b32 v205, v204 offset:swizzle(SWAP,8)
	s_waitcnt lgkmcnt(0)
	v_add_f32_e32 v204, v204, v205
	ds_swizzle_b32 v205, v204 offset:swizzle(SWAP,16)
	s_waitcnt lgkmcnt(0)
	v_add_f32_e32 v204, v204, v205
	v_mov_b32_e32 v205, v204
	s_nop 1
	v_permlane32_swap_b32_e32 v204, v205
	v_add_f32_e32 v204, v204, v205
	v_mov_b32_e32 v205, 0x358637bd
	v_fmamk_f32 v204, v204, 0x3a800000, v205
	v_rsq_f32_e32 v204, v204
	s_nop 0
	v_pk_mul_f32 v[128:129], v[128:129], v[204:205] op_sel_hi:[1,0]
	v_pk_mul_f32 v[130:131], v[130:131], v[204:205] op_sel_hi:[1,0]
	v_pk_mul_f32 v[128:129], v[188:189], v[128:129]
	v_pk_mul_f32 v[130:131], v[190:191], v[130:131]
	v_pk_fma_f32 v[128:129], v[34:35], v[128:129], v[224:225]
	v_pk_fma_f32 v[130:131], v[36:37], v[130:131], v[226:227]
	v_cvt_pk_bf16_f32 v128, v128, v129
	v_cvt_pk_bf16_f32 v129, v130, v131
	global_store_dwordx2 v146, v[128:129], s[66:67]
	v_pk_mul_f32 v[132:133], v[132:133], v[204:205] op_sel_hi:[1,0]
	v_pk_mul_f32 v[134:135], v[134:135], v[204:205] op_sel_hi:[1,0]
	v_pk_mul_f32 v[132:133], v[192:193], v[132:133]
	v_pk_mul_f32 v[134:135], v[194:195], v[134:135]
	v_pk_fma_f32 v[132:133], v[38:39], v[132:133], v[228:229]
	v_pk_fma_f32 v[134:135], v[40:41], v[134:135], v[230:231]
	v_cvt_pk_bf16_f32 v132, v132, v133
	v_cvt_pk_bf16_f32 v133, v134, v135
	global_store_dwordx2 v146, v[132:133], s[66:67] offset:512
	v_pk_mul_f32 v[136:137], v[136:137], v[204:205] op_sel_hi:[1,0]
	v_pk_mul_f32 v[138:139], v[138:139], v[204:205] op_sel_hi:[1,0]
	v_pk_mul_f32 v[136:137], v[196:197], v[136:137]
	v_pk_mul_f32 v[138:139], v[198:199], v[138:139]
	v_pk_fma_f32 v[136:137], v[42:43], v[136:137], v[232:233]
	v_pk_fma_f32 v[138:139], v[44:45], v[138:139], v[234:235]
	v_cvt_pk_bf16_f32 v136, v136, v137
	v_cvt_pk_bf16_f32 v137, v138, v139
	global_store_dwordx2 v146, v[136:137], s[66:67] offset:1024
	v_pk_mul_f32 v[140:141], v[140:141], v[204:205] op_sel_hi:[1,0]
	v_pk_mul_f32 v[142:143], v[142:143], v[204:205] op_sel_hi:[1,0]
	v_pk_mul_f32 v[140:141], v[200:201], v[140:141]
	v_pk_mul_f32 v[142:143], v[202:203], v[142:143]
	v_pk_fma_f32 v[140:141], v[46:47], v[140:141], v[236:237]
	v_pk_fma_f32 v[142:143], v[48:49], v[142:143], v[238:239]
	v_cvt_pk_bf16_f32 v140, v140, v141
	v_cvt_pk_bf16_f32 v141, v142, v143
	global_store_dwordx2 v146, v[140:141], s[66:67] offset:1536
	v_add_u32_e32 v146, 0x800, v146
	s_add_i32 s97, s97, 1
	s_cmp_lt_u32 s97, 1
	s_cbranch_scc1 .Lfz_pass
